# speedup vs baseline: 1.0254x; 1.0118x over previous
; __device__ __forceinline__ int get_tid() { int t = threadIdx.x; asm volatile("" : "+v"(t)); return t; }
; __device__ __forceinline__ void gemm_resid_phase(const Params& p, int layer, const u16* A, const u16* Bt, bool lat_only, bool from_input, char* smem) {
;     ...
;              [&](f32x4 (&acc)[4][4], int row0, int col0, int) __attribute__((always_inline)) {
;                const int tid = get_tid(), lane = tid & 63, wid = tid >> 6, wr = wid >> 1, wc = wid & 1, fr = lane & 15, fq = lane >> 4;
;                const int b = row0 / LT, l0 = row0 % LT;
;                const float* gate = mods + ((size_t)(layer * 33 + (l0 < LC ? 32 : b)) * 6 + 2) * 1024;
;                float* xb = (l0 < LC) ? xc + ((size_t)b * LC + l0) * D : xo + ((size_t)b * TL + (l0 - LC)) * D;
;                const float* xsb = (l0 < LC) ? xcs + ((size_t)b * LC + l0) * D : xls + ((size_t)b * TL + (l0 - LC)) * D;
; #pragma unroll
;                for (int m = 0; m < 4; ++m)
; #pragma unroll
;                  for (int n = 0; n < 4; ++n) {
;                    int r = wr * 64 + m * 16 + fr, c = col0 + wc * 64 + n * 16 + fq * 4;
;                    float4 g4 = *(const float4*)(gate + c);
;                    float4* xp = (float4*)(xb + (size_t)r * D + c);
;                    float4 xv = *(const float4*)(xsb + (size_t)r * D + c);
;                    xv.x += g4.x * acc[m][n][0]; xv.y += g4.y * acc[m][n][1]; xv.z += g4.z * acc[m][n][2]; xv.w += g4.w * acc[m][n][3];
;                    *xp = xv;
;                  }
;              });
.LBB0_435:
	s_mul_hi_i32 s7, s8, 0x38e38e39
	s_lshr_b32 s9, s7, 31
	s_ashr_i32 s7, s7, 9
	s_add_i32 s10, s7, s9
	s_mul_i32 s7, s10, 0x900
	s_sub_i32 s7, s8, s7
	s_cmpk_lt_i32 s7, 0x100
	s_cselect_b64 s[8:9], -1, 0
	s_add_i32 s11, s7, 0xffffff00
	s_ashr_i32 s14, s7, 31
	s_and_b64 s[12:13], s[8:9], exec
	s_cselect_b32 s13, s14, 0
	s_cselect_b32 s12, s7, s11
	s_cselect_b32 s7, s16, s26
	s_cselect_b32 s14, s17, s42
	s_cselect_b32 s15, 32, s10
	s_ashr_i32 s11, s10, 31
	s_and_b64 s[8:9], s[8:9], exec
	s_cselect_b32 s8, 20, 23
	s_lshl_b64 s[8:9], s[10:11], s8
	s_add_u32 s10, s14, s8
	s_addc_u32 s7, s7, s9
	s_lshl_b64 s[8:9], s[12:13], 12
	v_mov_b32_e32 v84, v107
	s_add_u32 s8, s10, s8
	s_addc_u32 s9, s7, s9
	s_add_i32 s7, s15, s81
	s_mul_hi_i32 s10, s7, 0x6000
	s_mulk_i32 s7, 0x6000
	v_and_b32_e32 v85, 15, v84
	v_and_b32_e32 v87, 64, v84
	v_ashrrev_i32_e32 v86, 1, v84
	v_lshrrev_b32_e32 v84, 2, v84
	s_add_u32 s7, s17, s7
	v_and_b32_e32 v84, 12, v84
	s_addc_u32 s11, s16, s10
	v_and_or_b32 v86, v86, s97, v85
	v_or3_b32 v98, v87, v84, s6
	s_add_u32 s10, s7, 0x2002000
	v_ashrrev_i32_e32 v99, 31, v98
	v_ashrrev_i32_e32 v87, 31, v86
	s_addc_u32 s11, s11, 0
	v_lshlrev_b64 v[88:89], 2, v[98:99]
	v_lshlrev_b64 v[90:91], 12, v[86:87]
	v_lshl_add_u64 v[84:85], s[10:11], 0, v[88:89]
	v_lshl_add_u64 v[90:91], s[8:9], 0, v[90:91]
	v_lshl_add_u64 v[100:101], v[90:91], 0, v[88:89]
	flat_load_dwordx4 v[170:173], v[84:85]
	flat_load_dwordx4 v[174:177], v[100:101]
	s_add_i32 s50, s50, 1
	s_cmp_eq_u32 s50, s43
	v_or_b32_e32 v226, 16, v98
	v_ashrrev_i32_e32 v227, 31, v226
	v_lshl_add_u64 v[226:227], v[226:227], 2, s[10:11]
	flat_load_dwordx4 v[178:181], v[226:227]
	flat_load_dwordx4 v[182:185], v[100:101] offset:64
	v_or_b32_e32 v228, 32, v98
	v_ashrrev_i32_e32 v229, 31, v228
	v_lshl_add_u64 v[228:229], v[228:229], 2, s[10:11]
	flat_load_dwordx4 v[186:189], v[228:229]
	flat_load_dwordx4 v[190:193], v[100:101] offset:128
	v_or_b32_e32 v230, 48, v98
	v_ashrrev_i32_e32 v231, 31, v230
	v_lshl_add_u64 v[230:231], v[230:231], 2, s[10:11]
	flat_load_dwordx4 v[194:197], v[230:231]
	flat_load_dwordx4 v[198:201], v[100:101] offset:192
	s_waitcnt vmcnt(0) lgkmcnt(0)
	v_pk_fma_f32 v[60:61], v[60:61], v[170:171], v[174:175]
	v_pk_fma_f32 v[62:63], v[62:63], v[172:173], v[176:177]
	flat_store_dwordx4 v[100:101], v[60:63]
	s_nop 1
	v_pk_fma_f32 v[56:57], v[56:57], v[178:179], v[182:183]
	v_pk_fma_f32 v[58:59], v[58:59], v[180:181], v[184:185]
	flat_store_dwordx4 v[100:101], v[56:59] offset:64
	s_nop 1
	v_pk_fma_f32 v[52:53], v[52:53], v[186:187], v[190:191]
	v_pk_fma_f32 v[54:55], v[54:55], v[188:189], v[192:193]
	flat_store_dwordx4 v[100:101], v[52:55] offset:128
	s_nop 1
	v_pk_fma_f32 v[48:49], v[48:49], v[194:195], v[198:199]
	v_pk_fma_f32 v[50:51], v[50:51], v[196:197], v[200:201]
	flat_store_dwordx4 v[100:101], v[48:51] offset:192
	s_nop 1
	v_or_b32_e32 v232, 16, v86
	v_ashrrev_i32_e32 v233, 31, v232
	v_lshlrev_b64 v[232:233], 12, v[232:233]
	v_lshl_add_u64 v[232:233], s[8:9], 0, v[232:233]
	v_lshl_add_u64 v[234:235], v[232:233], 0, v[88:89]
	flat_load_dwordx4 v[170:173], v[84:85]
	flat_load_dwordx4 v[174:177], v[234:235]
	flat_load_dwordx4 v[178:181], v[226:227]
	flat_load_dwordx4 v[182:185], v[234:235] offset:64
	flat_load_dwordx4 v[186:189], v[228:229]
	flat_load_dwordx4 v[190:193], v[234:235] offset:128
	flat_load_dwordx4 v[194:197], v[230:231]
	flat_load_dwordx4 v[198:201], v[234:235] offset:192
	s_waitcnt vmcnt(0) lgkmcnt(0)
	v_pk_fma_f32 v[44:45], v[44:45], v[170:171], v[174:175]
	v_pk_fma_f32 v[46:47], v[46:47], v[172:173], v[176:177]
	flat_store_dwordx4 v[234:235], v[44:47]
	v_pk_fma_f32 v[40:41], v[40:41], v[178:179], v[182:183]
	v_pk_fma_f32 v[42:43], v[42:43], v[180:181], v[184:185]
	flat_store_dwordx4 v[234:235], v[40:43] offset:64
	v_pk_fma_f32 v[36:37], v[36:37], v[186:187], v[190:191]
	v_pk_fma_f32 v[38:39], v[38:39], v[188:189], v[192:193]
	flat_store_dwordx4 v[234:235], v[36:39] offset:128
	v_pk_fma_f32 v[32:33], v[32:33], v[194:195], v[198:199]
	v_pk_fma_f32 v[34:35], v[34:35], v[196:197], v[200:201]
	flat_store_dwordx4 v[234:235], v[32:35] offset:192
	s_nop 1
	v_or_b32_e32 v236, 32, v86
	v_ashrrev_i32_e32 v237, 31, v236
	v_lshlrev_b64 v[236:237], 12, v[236:237]
	v_lshl_add_u64 v[236:237], s[8:9], 0, v[236:237]
	v_lshl_add_u64 v[238:239], v[236:237], 0, v[88:89]
	flat_load_dwordx4 v[170:173], v[84:85]
	flat_load_dwordx4 v[174:177], v[238:239]
	flat_load_dwordx4 v[178:181], v[226:227]
	flat_load_dwordx4 v[182:185], v[238:239] offset:64
	flat_load_dwordx4 v[186:189], v[228:229]
	flat_load_dwordx4 v[190:193], v[238:239] offset:128
	flat_load_dwordx4 v[194:197], v[230:231]
	flat_load_dwordx4 v[198:201], v[238:239] offset:192
	s_waitcnt vmcnt(0) lgkmcnt(0)
	v_pk_fma_f32 v[28:29], v[28:29], v[170:171], v[174:175]
	v_pk_fma_f32 v[30:31], v[30:31], v[172:173], v[176:177]
	flat_store_dwordx4 v[238:239], v[28:31]
	v_pk_fma_f32 v[24:25], v[24:25], v[178:179], v[182:183]
	v_pk_fma_f32 v[26:27], v[26:27], v[180:181], v[184:185]
	flat_store_dwordx4 v[238:239], v[24:27] offset:64
	v_pk_fma_f32 v[20:21], v[20:21], v[186:187], v[190:191]
	v_pk_fma_f32 v[22:23], v[22:23], v[188:189], v[192:193]
	flat_store_dwordx4 v[238:239], v[20:23] offset:128
	v_pk_fma_f32 v[16:17], v[16:17], v[194:195], v[198:199]
	v_pk_fma_f32 v[18:19], v[18:19], v[196:197], v[200:201]
	flat_store_dwordx4 v[238:239], v[16:19] offset:192
	s_nop 1
	v_or_b32_e32 v240, 48, v86
	v_ashrrev_i32_e32 v241, 31, v240
	v_lshlrev_b64 v[240:241], 12, v[240:241]
	v_lshl_add_u64 v[240:241], s[8:9], 0, v[240:241]
	v_lshl_add_u64 v[242:243], v[240:241], 0, v[88:89]
	flat_load_dwordx4 v[170:173], v[84:85]
	flat_load_dwordx4 v[174:177], v[242:243]
	flat_load_dwordx4 v[178:181], v[226:227]
	flat_load_dwordx4 v[182:185], v[242:243] offset:64
	flat_load_dwordx4 v[186:189], v[228:229]
	flat_load_dwordx4 v[190:193], v[242:243] offset:128
	flat_load_dwordx4 v[194:197], v[230:231]
	flat_load_dwordx4 v[198:201], v[242:243] offset:192
	s_waitcnt vmcnt(0) lgkmcnt(0)
	v_pk_fma_f32 v[12:13], v[12:13], v[170:171], v[174:175]
	v_pk_fma_f32 v[14:15], v[14:15], v[172:173], v[176:177]
	flat_store_dwordx4 v[242:243], v[12:15]
	v_pk_fma_f32 v[8:9], v[8:9], v[178:179], v[182:183]
	v_pk_fma_f32 v[10:11], v[10:11], v[180:181], v[184:185]
	flat_store_dwordx4 v[242:243], v[8:11] offset:64
	v_pk_fma_f32 v[4:5], v[4:5], v[186:187], v[190:191]
	v_pk_fma_f32 v[6:7], v[6:7], v[188:189], v[192:193]
	flat_store_dwordx4 v[242:243], v[4:7] offset:128
	v_pk_fma_f32 v[0:1], v[0:1], v[194:195], v[198:199]
	v_pk_fma_f32 v[2:3], v[2:3], v[196:197], v[200:201]
	flat_store_dwordx4 v[242:243], v[0:3] offset:192
	s_cbranch_scc1 .LBB0_454

; __device__ __forceinline__ int get_tid() { int t = threadIdx.x; asm volatile("" : "+v"(t)); return t; }
; __device__ __forceinline__ void gemm_resid_phase(const Params& p, int layer, const u16* A, const u16* Bt, bool lat_only, bool from_input, char* smem) {
;     ...
;              [&](f32x4 (&acc)[4][4], int row0, int col0, int) __attribute__((always_inline)) {
;                const int tid = get_tid(), lane = tid & 63, wid = tid >> 6, wr = wid >> 1, wc = wid & 1, fr = lane & 15, fq = lane >> 4;
;                const int b = row0 / LT, l0 = row0 % LT;
;                const float* gate = mods + ((size_t)(layer * 33 + (l0 < LC ? 32 : b)) * 6 + 2) * 1024;
;                float* xb = (l0 < LC) ? xc + ((size_t)b * LC + l0) * D : xo + ((size_t)b * TL + (l0 - LC)) * D;
;                const float* xsb = (l0 < LC) ? xcs + ((size_t)b * LC + l0) * D : xls + ((size_t)b * TL + (l0 - LC)) * D;
; #pragma unroll
;                for (int m = 0; m < 4; ++m)
; #pragma unroll
;                  for (int n = 0; n < 4; ++n) {
;                    int r = wr * 64 + m * 16 + fr, c = col0 + wc * 64 + n * 16 + fq * 4;
;                    float4 g4 = *(const float4*)(gate + c);
;                    float4* xp = (float4*)(xb + (size_t)r * D + c);
;                    float4 xv = *(const float4*)(xsb + (size_t)r * D + c);
;                    xv.x += g4.x * acc[m][n][0]; xv.y += g4.y * acc[m][n][1]; xv.z += g4.z * acc[m][n][2]; xv.w += g4.w * acc[m][n][3];
;                    *xp = xv;
;                  }
;              });
.LBB0_463:
	s_mul_hi_i32 s15, s80, 0x38e38e39
	s_lshr_b32 s17, s15, 31
	s_ashr_i32 s15, s15, 1
	s_add_i32 s42, s15, s17
	s_mul_hi_i32 s15, s16, 0x38e38e39
	s_lshr_b32 s17, s15, 31
	s_ashr_i32 s15, s15, 9
	s_add_i32 s15, s15, s17
	s_mulk_i32 s15, 0x900
	s_sub_i32 s15, s16, s15
	s_cmpk_lt_i32 s15, 0x100
	s_cselect_b64 s[16:17], -1, 0
	s_add_i32 s40, s15, 0xffffff00
	s_ashr_i32 s41, s15, 31
	s_and_b64 s[44:45], s[16:17], exec
	s_cselect_b32 s45, s41, 0
	s_cselect_b32 s44, s15, s40
	s_cselect_b32 s15, s5, s7
	s_cselect_b32 s40, s4, s6
	s_cselect_b32 s41, 32, s42
	s_cselect_b32 s46, s11, s9
	s_cselect_b32 s47, s10, s8
	s_ashr_i32 s43, s42, 31
	s_and_b64 s[16:17], s[16:17], exec
	s_cselect_b32 s16, 20, 23
	s_lshl_b64 s[42:43], s[42:43], s16
	s_add_u32 s16, s40, s42
	s_addc_u32 s15, s15, s43
	s_lshl_b64 s[44:45], s[44:45], 12
	s_add_u32 s16, s16, s44
	s_addc_u32 s17, s15, s45
	s_add_u32 s15, s47, s42
	s_addc_u32 s40, s46, s43
	v_mov_b32_e32 v84, v107
	s_add_u32 s42, s15, s44
	s_addc_u32 s43, s40, s45
	s_add_i32 s15, s41, s81
	s_mul_hi_i32 s40, s15, 0x6000
	s_mulk_i32 s15, 0x6000
	v_and_b32_e32 v85, 15, v84
	v_and_b32_e32 v86, 64, v84
	v_ashrrev_i32_e32 v87, 1, v84
	v_lshrrev_b32_e32 v84, 2, v84
	s_add_u32 s15, s4, s15
	v_and_b32_e32 v84, 12, v84
	s_addc_u32 s40, s5, s40
	v_and_or_b32 v88, v87, s97, v85
	v_or3_b32 v98, v86, v84, s14
	s_add_u32 s44, s15, 0x2002000
	v_ashrrev_i32_e32 v99, 31, v98
	v_ashrrev_i32_e32 v89, 31, v88
	s_addc_u32 s45, s40, 0
	v_lshlrev_b64 v[86:87], 2, v[98:99]
	v_lshlrev_b64 v[90:91], 12, v[88:89]
	v_lshl_add_u64 v[84:85], s[44:45], 0, v[86:87]
	v_lshl_add_u64 v[92:93], s[16:17], 0, v[90:91]
	v_lshl_add_u64 v[90:91], s[42:43], 0, v[90:91]
	v_lshl_add_u64 v[100:101], v[92:93], 0, v[86:87]
	v_lshl_add_u64 v[102:103], v[90:91], 0, v[86:87]
	flat_load_dwordx4 v[170:173], v[84:85]
	flat_load_dwordx4 v[174:177], v[102:103]
	s_add_i32 s50, s50, 1
	s_cmp_eq_u32 s50, s26
	s_mov_b64 s[86:87], 0xfffff
	v_or_b32_e32 v226, 16, v98
	v_ashrrev_i32_e32 v227, 31, v226
	v_lshl_add_u64 v[226:227], v[226:227], 2, s[44:45]
	flat_load_dwordx4 v[178:181], v[226:227]
	flat_load_dwordx4 v[182:185], v[102:103] offset:64
	v_or_b32_e32 v228, 32, v98
	v_ashrrev_i32_e32 v229, 31, v228
	v_lshl_add_u64 v[228:229], v[228:229], 2, s[44:45]
	flat_load_dwordx4 v[186:189], v[228:229]
	flat_load_dwordx4 v[190:193], v[102:103] offset:128
	v_or_b32_e32 v230, 48, v98
	v_ashrrev_i32_e32 v231, 31, v230
	v_lshl_add_u64 v[230:231], v[230:231], 2, s[44:45]
	flat_load_dwordx4 v[194:197], v[230:231]
	flat_load_dwordx4 v[198:201], v[102:103] offset:192
	s_waitcnt vmcnt(0) lgkmcnt(0)
	v_pk_fma_f32 v[60:61], v[60:61], v[170:171], v[174:175]
	v_pk_fma_f32 v[62:63], v[62:63], v[172:173], v[176:177]
	flat_store_dwordx4 v[100:101], v[60:63]
	s_nop 1
	v_pk_fma_f32 v[56:57], v[56:57], v[178:179], v[182:183]
	v_pk_fma_f32 v[58:59], v[58:59], v[180:181], v[184:185]
	flat_store_dwordx4 v[100:101], v[56:59] offset:64
	s_nop 1
	v_pk_fma_f32 v[52:53], v[52:53], v[186:187], v[190:191]
	v_pk_fma_f32 v[54:55], v[54:55], v[188:189], v[192:193]
	flat_store_dwordx4 v[100:101], v[52:55] offset:128
	s_nop 1
	v_pk_fma_f32 v[48:49], v[48:49], v[194:195], v[198:199]
	v_pk_fma_f32 v[50:51], v[50:51], v[196:197], v[200:201]
	flat_store_dwordx4 v[100:101], v[48:51] offset:192
	s_nop 1
	v_or_b32_e32 v232, 16, v88
	v_ashrrev_i32_e32 v233, 31, v232
	v_lshlrev_b64 v[232:233], 12, v[232:233]
	v_lshl_add_u64 v[234:235], s[16:17], 0, v[232:233]
	v_lshl_add_u64 v[232:233], s[42:43], 0, v[232:233]
	v_lshl_add_u64 v[236:237], v[234:235], 0, v[86:87]
	v_lshl_add_u64 v[238:239], v[232:233], 0, v[86:87]
	flat_load_dwordx4 v[170:173], v[84:85]
	flat_load_dwordx4 v[174:177], v[238:239]
	flat_load_dwordx4 v[178:181], v[226:227]
	flat_load_dwordx4 v[182:185], v[238:239] offset:64
	flat_load_dwordx4 v[186:189], v[228:229]
	flat_load_dwordx4 v[190:193], v[238:239] offset:128
	flat_load_dwordx4 v[194:197], v[230:231]
	flat_load_dwordx4 v[198:201], v[238:239] offset:192
	s_waitcnt vmcnt(0) lgkmcnt(0)
; __device__ __forceinline__ void gemm_resid_phase(const Params& p, int layer, const u16* A, const u16* Bt, bool lat_only, bool from_input, char* smem) {
;     ...
; #pragma unroll
;                for (int m = 0; m < 4; ++m)
; #pragma unroll
;                  for (int n = 0; n < 4; ++n) {
;                    int r = wr * 64 + m * 16 + fr, c = col0 + wc * 64 + n * 16 + fq * 4;
;                    float4 g4 = *(const float4*)(gate + c);
;                    float4* xp = (float4*)(xb + (size_t)r * D + c);
;                    float4 xv = *(const float4*)(xsb + (size_t)r * D + c);
;                    xv.x += g4.x * acc[m][n][0]; xv.y += g4.y * acc[m][n][1]; xv.z += g4.z * acc[m][n][2]; xv.w += g4.w * acc[m][n][3];
;                    *xp = xv;
;                  }
	v_pk_fma_f32 v[44:45], v[44:45], v[170:171], v[174:175]
	v_pk_fma_f32 v[46:47], v[46:47], v[172:173], v[176:177]
	flat_store_dwordx4 v[236:237], v[44:47]
	v_pk_fma_f32 v[40:41], v[40:41], v[178:179], v[182:183]
	v_pk_fma_f32 v[42:43], v[42:43], v[180:181], v[184:185]
	flat_store_dwordx4 v[236:237], v[40:43] offset:64
	v_pk_fma_f32 v[36:37], v[36:37], v[186:187], v[190:191]
	v_pk_fma_f32 v[38:39], v[38:39], v[188:189], v[192:193]
	flat_store_dwordx4 v[236:237], v[36:39] offset:128
	v_pk_fma_f32 v[32:33], v[32:33], v[194:195], v[198:199]
	v_pk_fma_f32 v[34:35], v[34:35], v[196:197], v[200:201]
	flat_store_dwordx4 v[236:237], v[32:35] offset:192
	s_nop 1
	v_or_b32_e32 v240, 32, v88
	v_ashrrev_i32_e32 v241, 31, v240
	v_lshlrev_b64 v[240:241], 12, v[240:241]
	v_lshl_add_u64 v[242:243], s[16:17], 0, v[240:241]
	v_lshl_add_u64 v[240:241], s[42:43], 0, v[240:241]
	v_lshl_add_u64 v[244:245], v[242:243], 0, v[86:87]
	v_lshl_add_u64 v[246:247], v[240:241], 0, v[86:87]
	flat_load_dwordx4 v[170:173], v[84:85]
	flat_load_dwordx4 v[174:177], v[246:247]
	flat_load_dwordx4 v[178:181], v[226:227]
	flat_load_dwordx4 v[182:185], v[246:247] offset:64
	flat_load_dwordx4 v[186:189], v[228:229]
	flat_load_dwordx4 v[190:193], v[246:247] offset:128
	flat_load_dwordx4 v[194:197], v[230:231]
	flat_load_dwordx4 v[198:201], v[246:247] offset:192
	s_waitcnt vmcnt(0) lgkmcnt(0)
	v_pk_fma_f32 v[28:29], v[28:29], v[170:171], v[174:175]
	v_pk_fma_f32 v[30:31], v[30:31], v[172:173], v[176:177]
	flat_store_dwordx4 v[244:245], v[28:31]
	v_pk_fma_f32 v[24:25], v[24:25], v[178:179], v[182:183]
	v_pk_fma_f32 v[26:27], v[26:27], v[180:181], v[184:185]
	flat_store_dwordx4 v[244:245], v[24:27] offset:64
	v_pk_fma_f32 v[20:21], v[20:21], v[186:187], v[190:191]
	v_pk_fma_f32 v[22:23], v[22:23], v[188:189], v[192:193]
	flat_store_dwordx4 v[244:245], v[20:23] offset:128
	v_pk_fma_f32 v[16:17], v[16:17], v[194:195], v[198:199]
	v_pk_fma_f32 v[18:19], v[18:19], v[196:197], v[200:201]
	flat_store_dwordx4 v[244:245], v[16:19] offset:192
	s_nop 1
	v_or_b32_e32 v248, 48, v88
	v_ashrrev_i32_e32 v249, 31, v248
	v_lshlrev_b64 v[248:249], 12, v[248:249]
	v_lshl_add_u64 v[250:251], s[16:17], 0, v[248:249]
	v_lshl_add_u64 v[248:249], s[42:43], 0, v[248:249]
	v_lshl_add_u64 v[252:253], v[250:251], 0, v[86:87]
	v_lshl_add_u64 v[232:233], v[248:249], 0, v[86:87]
	flat_load_dwordx4 v[170:173], v[84:85]
	flat_load_dwordx4 v[174:177], v[232:233]
	flat_load_dwordx4 v[178:181], v[226:227]
	flat_load_dwordx4 v[182:185], v[232:233] offset:64
	flat_load_dwordx4 v[186:189], v[228:229]
	flat_load_dwordx4 v[190:193], v[232:233] offset:128
	flat_load_dwordx4 v[194:197], v[230:231]
	flat_load_dwordx4 v[198:201], v[232:233] offset:192
	s_waitcnt vmcnt(0) lgkmcnt(0)
	v_pk_fma_f32 v[12:13], v[12:13], v[170:171], v[174:175]
	v_pk_fma_f32 v[14:15], v[14:15], v[172:173], v[176:177]
	flat_store_dwordx4 v[252:253], v[12:15]
	v_pk_fma_f32 v[8:9], v[8:9], v[178:179], v[182:183]
	v_pk_fma_f32 v[10:11], v[10:11], v[180:181], v[184:185]
	flat_store_dwordx4 v[252:253], v[8:11] offset:64
	v_pk_fma_f32 v[4:5], v[4:5], v[186:187], v[190:191]
	v_pk_fma_f32 v[6:7], v[6:7], v[188:189], v[192:193]
	flat_store_dwordx4 v[252:253], v[4:7] offset:128
	v_pk_fma_f32 v[0:1], v[0:1], v[194:195], v[198:199]
	v_pk_fma_f32 v[2:3], v[2:3], v[196:197], v[200:201]
	flat_store_dwordx4 v[252:253], v[0:3] offset:192
	s_cbranch_scc1 .LBB0_478

; __device__ __forceinline__ float bf2f(u16 h) { return __uint_as_float(((unsigned)h) << 16); }
; __device__ __forceinline__ void even_post_phase(const Params& p, int ei, char* smem) {
;     ...
;         for (int n = 0; n < 4; ++n) {
;           const int col = wid * 64 + n * 16 + fr;
;           ov[q8][n] = bf2f(of[row * 512 + col]) + bf2f(ob[row * 512 + col]);
;           const u16* pv = big + row * PSTR + 1024 + col;
;           const float c = bf2f(*pv);
;           const float pr = hp ? bf2f(*(pv - PSTR)) : 0.f;
;           const float nx = hn ? bf2f(*(pv + PSTR)) : 0.f;
;           vs[q8][n] = c + muv[n] * (0.5f * (pr + nx) - c);
;         }
;       }
;       __builtin_amdgcn_sched_barrier(0);
; #pragma unroll
;       for (int q8 = 0; q8 < 4; ++q8) {
;         const int m = mh, j = q8;
;         const size_t row = (size_t)row0 + m * 16 + fq * 4 + j;
;         float sm = ov[q8][0] + ov[q8][1] + ov[q8][2] + ov[q8][3];
;         sm = row_sum16(sm);
;         const float mean = sm * (1.f / 64.f);
;         float vsum = 0.f;
; #pragma unroll
;         for (int n = 0; n < 4; ++n) { float dlt = ov[q8][n] - mean; vsum += dlt * dlt; }
;         vsum = row_sum16(vsum);
;         const float rstd = rsqrtf(vsum * (1.f / 64.f) + 64e-5f);
.LBB0_507:
	s_or_b64 exec, exec, s[0:1]
	s_waitcnt vmcnt(0) lgkmcnt(0)
	v_lshlrev_b32_e32 v46, 16, v46
	v_lshlrev_b32_e32 v37, 16, v37
	v_lshlrev_b32_e32 v38, 16, v38
	v_lshlrev_b32_e32 v42, 16, v42
	v_lshlrev_b32_e32 v43, 16, v43
	v_lshlrev_b32_e32 v48, 16, v48
	v_lshlrev_b32_e32 v49, 16, v49
	v_lshlrev_b32_e32 v53, 16, v53
	v_lshlrev_b32_e32 v54, 16, v54
	v_lshlrev_b32_e32 v60, 16, v60
	v_lshlrev_b32_e32 v61, 16, v61
	v_lshlrev_b32_e32 v134, 16, v134
	v_lshlrev_b32_e32 v135, 16, v135
	v_lshlrev_b32_e32 v139, 16, v139
	v_lshlrev_b32_e32 v140, 16, v140
	v_lshlrev_b32_e32 v144, 16, v144
	v_lshlrev_b32_e32 v145, 16, v145
	v_lshlrev_b32_e32 v151, 16, v151
	v_lshlrev_b32_e32 v152, 16, v152
	v_lshlrev_b32_e32 v156, 16, v156
	v_lshlrev_b32_e32 v157, 16, v157
	v_lshlrev_b32_e32 v161, 16, v161
	v_lshlrev_b32_e32 v162, 16, v162
	v_lshlrev_b32_e32 v166, 16, v166
	v_lshlrev_b32_e32 v167, 16, v167
	v_lshlrev_b32_e32 v173, 16, v173
	v_lshlrev_b32_e32 v174, 16, v174
	v_lshlrev_b32_e32 v179, 16, v179
	v_lshlrev_b32_e32 v180, 16, v180
	v_lshlrev_b32_e32 v29, 16, v29
	v_lshlrev_b32_e32 v177, 16, v177
	v_lshlrev_b32_e32 v30, 16, v30
	v_lshlrev_b32_e32 v183, 16, v28
	v_add_f32_e32 v24, v180, v29
	v_fma_f32 v24, v24, 0.5, -v183
	v_fmac_f32_e32 v183, v95, v24
	v_lshlrev_b32_e32 v24, 16, v26
	v_lshlrev_b32_e32 v25, 16, v27
	v_add_f32_e32 v24, v24, v25
	v_lshlrev_b32_e32 v178, 16, v178
	v_add_f32_e32 v25, v174, v179
	v_fma_f32 v25, v25, 0.5, -v178
	v_fmac_f32_e32 v178, v93, v25
	v_lshlrev_b32_e32 v25, 16, v181
	v_lshlrev_b32_e32 v26, 16, v182
	v_add_f32_e32 v25, v25, v26
	v_lshlrev_b32_e32 v172, 16, v172
	v_add_f32_e32 v26, v167, v173
	v_fma_f32 v26, v26, 0.5, -v172
	v_fmac_f32_e32 v172, v91, v26
	v_lshlrev_b32_e32 v26, 16, v175
	v_lshlrev_b32_e32 v27, 16, v176
	v_add_f32_e32 v27, v26, v27
	v_lshlrev_b32_e32 v165, 16, v165
	v_add_f32_e32 v26, v162, v166
	v_fma_f32 v26, v26, 0.5, -v165
	v_fmac_f32_e32 v165, v121, v26
	v_add_f32_e32 v26, v168, v169
	v_mul_f32_e32 v162, 0.5, v26
	v_lshlrev_b32_e32 v26, 16, v170
	v_lshlrev_b32_e32 v28, 16, v171
	v_add_f32_e32 v26, v26, v28
	v_lshlrev_b32_e32 v160, 16, v160
	v_add_f32_e32 v28, v157, v161
	v_fma_f32 v28, v28, 0.5, -v160
	v_fmac_f32_e32 v160, v95, v28
	v_lshlrev_b32_e32 v28, 16, v163
	v_lshlrev_b32_e32 v29, 16, v164
	v_add_f32_e32 v28, v28, v29
	v_lshlrev_b32_e32 v155, 16, v155
	v_add_f32_e32 v29, v152, v156
	v_fma_f32 v29, v29, 0.5, -v155
	v_lshlrev_b32_e32 v180, 16, v31
	v_fmac_f32_e32 v155, v93, v29
	v_lshlrev_b32_e32 v29, 16, v158
	v_lshlrev_b32_e32 v31, 16, v159
	v_add_f32_e32 v29, v29, v31
	v_lshlrev_b32_e32 v150, 16, v150
	v_add_f32_e32 v31, v145, v151
	v_fma_f32 v31, v31, 0.5, -v150
	v_fmac_f32_e32 v150, v91, v31
	v_lshlrev_b32_e32 v31, 16, v153
	v_lshlrev_b32_e32 v145, 16, v154
	v_add_f32_e32 v145, v31, v145
	v_lshlrev_b32_e32 v143, 16, v143
	v_add_f32_e32 v31, v140, v144
	v_fma_f32 v31, v31, 0.5, -v143
	v_fmac_f32_e32 v143, v121, v31
	v_add_f32_e32 v31, v146, v149
	v_mul_f32_e32 v140, 0.5, v31
	v_lshlrev_b32_e32 v31, 16, v147
	v_lshlrev_b32_e32 v144, 16, v148
	v_add_f32_e32 v144, v31, v144
	v_lshlrev_b32_e32 v146, 16, v138
	v_add_f32_e32 v31, v135, v139
	v_fma_f32 v31, v31, 0.5, -v146
	v_fmac_f32_e32 v146, v95, v31
	v_lshlrev_b32_e32 v31, 16, v141
	v_lshlrev_b32_e32 v135, 16, v142
	v_add_f32_e32 v138, v31, v135
	v_lshlrev_b32_e32 v108, 16, v108
	v_add_f32_e32 v31, v61, v134
	v_fma_f32 v31, v31, 0.5, -v108
	v_fmac_f32_e32 v108, v93, v31
	v_lshlrev_b32_e32 v31, 16, v136
	v_lshlrev_b32_e32 v61, 16, v137
	v_add_f32_e32 v139, v31, v61
	v_lshlrev_b32_e32 v61, 16, v59
	v_add_f32_e32 v31, v54, v60
	v_fma_f32 v31, v31, 0.5, -v61
	v_fmac_f32_e32 v61, v91, v31
	v_lshlrev_b32_e32 v31, 16, v62
	v_lshlrev_b32_e32 v54, 16, v63
	v_add_f32_e32 v59, v31, v54
	v_lshlrev_b32_e32 v52, 16, v52
	v_add_f32_e32 v31, v49, v53
	v_fma_f32 v31, v31, 0.5, -v52
	v_fmac_f32_e32 v52, v121, v31
	v_add_f32_e32 v31, v55, v58
	v_mul_f32_e32 v53, 0.5, v31
	v_lshlrev_b32_e32 v31, 16, v56
	v_lshlrev_b32_e32 v49, 16, v57
	v_add_f32_e32 v58, v31, v49
	v_lshlrev_b32_e32 v54, 16, v47
	v_add_f32_e32 v31, v43, v48
	v_fma_f32 v31, v31, 0.5, -v54
	v_fmac_f32_e32 v54, v95, v31
	v_lshlrev_b32_e32 v31, 16, v50
	v_lshlrev_b32_e32 v43, 16, v51
	v_add_f32_e32 v48, v31, v43
	v_lshlrev_b32_e32 v50, 16, v41
	v_add_f32_e32 v31, v38, v42
	v_fma_f32 v31, v31, 0.5, -v50
	v_fmac_f32_e32 v50, v93, v31
	v_lshlrev_b32_e32 v31, 16, v44
	v_lshlrev_b32_e32 v38, 16, v45
	v_add_f32_e32 v49, v31, v38
	v_lshlrev_b32_e32 v51, 16, v36
	v_add_f32_e32 v31, v46, v37
	v_fma_f32 v31, v31, 0.5, -v51
	v_fmac_f32_e32 v51, v91, v31
	v_lshlrev_b32_e32 v31, 16, v39
	v_lshlrev_b32_e32 v36, 16, v40
	v_add_f32_e32 v37, v31, v36
	v_add_f32_e32 v31, v32, v35
	v_add_f32_e32 v30, v177, v30
	v_mul_f32_e32 v55, 0.5, v31
	v_lshlrev_b32_e32 v31, 16, v33
	v_lshlrev_b32_e32 v32, 16, v34
	v_fma_f32 v30, v30, 0.5, -v180
	v_add_f32_e32 v36, v31, v32
	v_fmac_f32_e32 v180, v121, v30
	v_add_f32_e32 v30, v36, v37
	v_add_f32_e32 v38, v58, v59
	v_add_f32_e32 v30, v30, v49
	v_add_f32_e32 v38, v38, v139
	v_add_f32_e32 v30, v30, v48
	v_add_f32_e32 v38, v38, v138
	s_mov_b32 s0, 0x3a27c5ac
	v_add_f32_dpp v30, v30, v30 row_ror:8 row_mask:0xf bank_mask:0xf bound_ctrl:1
	v_add_f32_dpp v38, v38, v38 row_ror:8 row_mask:0xf bank_mask:0xf bound_ctrl:1
	v_lshlrev_b64 v[16:17], 11, v[16:17]
	v_add_f32_dpp v30, v30, v30 row_ror:4 row_mask:0xf bank_mask:0xf bound_ctrl:1
	v_add_f32_dpp v38, v38, v38 row_ror:4 row_mask:0xf bank_mask:0xf bound_ctrl:1
	v_lshl_add_u64 v[16:17], s[86:87], 0, v[16:17]
	v_add_f32_dpp v30, v30, v30 row_ror:2 row_mask:0xf bank_mask:0xf bound_ctrl:1
	v_add_f32_dpp v38, v38, v38 row_ror:2 row_mask:0xf bank_mask:0xf bound_ctrl:1
; __device__ __forceinline__ u16 f2bf(float f) { return (u16)(pack2(f, 0.f) & 0xffffu); }
; __device__ __forceinline__ void even_post_phase(const Params& p, int ei, char* smem) {
;     ...
;       for (int q8 = 0; q8 < 4; ++q8) {
;         const int m = mh, j = q8;
;         const size_t row = (size_t)row0 + m * 16 + fq * 4 + j;
;         float sm = ov[q8][0] + ov[q8][1] + ov[q8][2] + ov[q8][3];
;         sm = row_sum16(sm);
;         const float mean = sm * (1.f / 64.f);
;         float vsum = 0.f;
; #pragma unroll
;         for (int n = 0; n < 4; ++n) { float dlt = ov[q8][n] - mean; vsum += dlt * dlt; }
;         vsum = row_sum16(vsum);
;         const float rstd = rsqrtf(vsum * (1.f / 64.f) + 64e-5f);
; #pragma unroll
;         for (int n = 0; n < 4; ++n) {
;           const int col = wid * 64 + n * 16 + fr;
;           const float on = (ov[q8][n] - mean) * rstd * lnw[n] + lnb[n];
;           act[row * D + col] = f2bf((on + bon[q8] * vs[q8][n]) * acc[m][n][j]);
;         }
	s_add_i32 s26, s26, s20
	v_add_f32_dpp v30, v30, v30 row_ror:1 row_mask:0xf bank_mask:0xf bound_ctrl:1
	v_add_f32_dpp v38, v38, v38 row_ror:1 row_mask:0xf bank_mask:0xf bound_ctrl:1
	v_mul_f32_e32 v30, 0x3c800000, v30
	v_mul_f32_e32 v38, 0x3c800000, v38
	v_pk_add_f32 v[32:33], v[36:37], v[30:31] op_sel_hi:[1,0] neg_lo:[0,1] neg_hi:[0,1]
	v_pk_add_f32 v[40:41], v[58:59], v[38:39] op_sel_hi:[1,0] neg_lo:[0,1] neg_hi:[0,1]
	v_pk_mul_f32 v[34:35], v[32:33], v[32:33]
	v_pk_add_f32 v[30:31], v[48:49], v[30:31] op_sel_hi:[1,0] neg_lo:[0,1] neg_hi:[0,1]
	v_pk_mul_f32 v[42:43], v[40:41], v[40:41]
	v_pk_add_f32 v[38:39], v[138:139], v[38:39] op_sel_hi:[1,0] neg_lo:[0,1] neg_hi:[0,1]
	v_pk_mul_f32 v[36:37], v[30:31], v[30:31]
	v_pk_mul_f32 v[44:45], v[38:39], v[38:39]
	v_mov_b32_e32 v46, v42
	v_mov_b32_e32 v47, v34
	v_mov_b32_e32 v34, v43
	v_pk_add_f32 v[34:35], v[46:47], v[34:35]
	v_mov_b32_e32 v42, v45
	v_mov_b32_e32 v43, v37
	v_pk_add_f32 v[34:35], v[42:43], v[34:35]
	v_mov_b32_e32 v45, v36
	v_pk_add_f32 v[34:35], v[44:45], v[34:35]
	s_nop 1
	v_mov_b32_dpp v37, v35 row_ror:8 row_mask:0xf bank_mask:0xf bound_ctrl:1
	v_mov_b32_dpp v36, v34 row_ror:8 row_mask:0xf bank_mask:0xf bound_ctrl:1
	v_pk_add_f32 v[34:35], v[34:35], v[36:37]
	s_nop 1
	v_mov_b32_dpp v37, v35 row_ror:4 row_mask:0xf bank_mask:0xf bound_ctrl:1
	v_mov_b32_dpp v36, v34 row_ror:4 row_mask:0xf bank_mask:0xf bound_ctrl:1
	v_pk_add_f32 v[34:35], v[34:35], v[36:37]
	s_nop 1
	v_mov_b32_dpp v37, v35 row_ror:2 row_mask:0xf bank_mask:0xf bound_ctrl:1
	v_mov_b32_dpp v36, v34 row_ror:2 row_mask:0xf bank_mask:0xf bound_ctrl:1
	v_pk_add_f32 v[34:35], v[34:35], v[36:37]
	s_nop 1
	v_mov_b32_dpp v37, v35 row_ror:1 row_mask:0xf bank_mask:0xf bound_ctrl:1
	v_mov_b32_dpp v36, v34 row_ror:1 row_mask:0xf bank_mask:0xf bound_ctrl:1
	v_pk_add_f32 v[34:35], v[34:35], v[36:37]
	v_mov_b64_e32 v[36:37], s[0:1]
	v_pk_fma_f32 v[34:35], v[34:35], s[22:23], v[36:37] op_sel_hi:[1,0,0]
	s_nop 0
	v_mul_f32_e32 v42, 0x4b800000, v35
	v_cmp_gt_f32_e32 vcc, s39, v35
	s_nop 1
	v_cndmask_b32_e32 v35, v35, v42, vcc
	v_rsq_f32_e32 v35, v35
	v_lshl_add_u64 v[42:43], v[16:17], 0, v[130:131]
	v_lshl_add_u64 v[16:17], v[16:17], 0, v[132:133]
	v_mul_f32_e32 v44, 0x45800000, v35
	v_cndmask_b32_e32 v35, v35, v44, vcc
	v_mul_f32_e32 v32, v32, v35
	v_fma_f32 v32, v97, v32, v75
	v_fmac_f32_e32 v32, v55, v51
	v_mul_f32_e32 v12, v12, v32
	v_cvt_pk_bf16_f32 v12, v12, s0
	flat_store_short v[42:43], v12
	v_mul_f32_e32 v12, v33, v35
	v_fma_f32 v12, v99, v12, v85
	v_fmac_f32_e32 v12, v55, v50
	v_mul_f32_e32 v8, v8, v12
	v_cvt_pk_bf16_f32 v8, v8, s0
	flat_store_short v[42:43], v8 offset:32
	v_mul_f32_e32 v8, v31, v35
	v_fma_f32 v8, v101, v8, v87
	v_fmac_f32_e32 v8, v55, v54
	v_mul_f32_e32 v4, v4, v8
	v_cvt_pk_bf16_f32 v4, v4, s0
	v_mul_f32_e32 v8, 0x4b800000, v34
	v_cmp_gt_f32_e32 vcc, s39, v34
	flat_store_short v[42:43], v4 offset:64
	v_mul_f32_e32 v4, v30, v35
	v_cndmask_b32_e32 v8, v34, v8, vcc
	v_fma_f32 v4, v103, v4, v89
	v_rsq_f32_e32 v8, v8
	v_fmac_f32_e32 v4, v55, v52
	v_mul_f32_e32 v0, v0, v4
	v_cvt_pk_bf16_f32 v0, v0, s0
	flat_store_short v[16:17], v0
	v_mul_f32_e32 v0, 0x45800000, v8
	v_cndmask_b32_e32 v0, v8, v0, vcc
	v_mul_f32_e32 v4, v40, v0
	v_fma_f32 v4, v97, v4, v75
	v_lshlrev_b64 v[16:17], 11, v[18:19]
	v_fmac_f32_e32 v4, v53, v61
	v_lshl_add_u64 v[16:17], s[86:87], 0, v[16:17]
	v_mul_f32_e32 v4, v13, v4
	v_cvt_pk_bf16_f32 v4, v4, s0
	v_lshl_add_u64 v[12:13], v[16:17], 0, v[130:131]
	flat_store_short v[12:13], v4
	v_mul_f32_e32 v4, v41, v0
	v_fma_f32 v4, v99, v4, v85
	v_fmac_f32_e32 v4, v53, v108
	v_mul_f32_e32 v4, v9, v4
	v_cvt_pk_bf16_f32 v4, v4, s0
	flat_store_short v[12:13], v4 offset:32
	v_mul_f32_e32 v4, v39, v0
	v_fma_f32 v4, v101, v4, v87
	v_mul_f32_e32 v0, v38, v0
	v_fmac_f32_e32 v4, v53, v146
	v_fma_f32 v0, v103, v0, v89
	v_mul_f32_e32 v4, v5, v4
	v_fmac_f32_e32 v0, v53, v143
	v_cvt_pk_bf16_f32 v4, v4, s0
	v_mul_f32_e32 v0, v1, v0
	flat_store_short v[12:13], v4 offset:64
	v_cvt_pk_bf16_f32 v4, v0, s0
	v_lshl_add_u64 v[0:1], v[16:17], 0, v[132:133]
	flat_store_short v[0:1], v4
	v_add_f32_e32 v0, v144, v145
	v_add_f32_e32 v18, v26, v27
	v_add_f32_e32 v0, v0, v29
	v_add_f32_e32 v18, v18, v25
	v_add_f32_e32 v0, v0, v28
	v_add_f32_e32 v18, v18, v24
	v_lshlrev_b64 v[16:17], 11, v[20:21]
	v_add_f32_dpp v0, v0, v0 row_ror:8 row_mask:0xf bank_mask:0xf bound_ctrl:1
	v_add_f32_dpp v18, v18, v18 row_ror:8 row_mask:0xf bank_mask:0xf bound_ctrl:1
	s_nop 0
	v_add_f32_dpp v0, v0, v0 row_ror:4 row_mask:0xf bank_mask:0xf bound_ctrl:1
	v_add_f32_dpp v18, v18, v18 row_ror:4 row_mask:0xf bank_mask:0xf bound_ctrl:1
	s_nop 0
	v_add_f32_dpp v0, v0, v0 row_ror:2 row_mask:0xf bank_mask:0xf bound_ctrl:1
	v_add_f32_dpp v18, v18, v18 row_ror:2 row_mask:0xf bank_mask:0xf bound_ctrl:1
	s_nop 0
	v_add_f32_dpp v0, v0, v0 row_ror:1 row_mask:0xf bank_mask:0xf bound_ctrl:1
	v_add_f32_dpp v18, v18, v18 row_ror:1 row_mask:0xf bank_mask:0xf bound_ctrl:1
	v_mul_f32_e32 v0, 0x3c800000, v0
	v_mul_f32_e32 v18, 0x3c800000, v18
	v_pk_add_f32 v[4:5], v[144:145], v[0:1] op_sel_hi:[1,0] neg_lo:[0,1] neg_hi:[0,1]
	v_pk_add_f32 v[20:21], v[26:27], v[18:19] op_sel_hi:[1,0] neg_lo:[0,1] neg_hi:[0,1]
	v_pk_mul_f32 v[8:9], v[4:5], v[4:5]
	v_pk_add_f32 v[0:1], v[28:29], v[0:1] op_sel_hi:[1,0] neg_lo:[0,1] neg_hi:[0,1]
	v_pk_mul_f32 v[26:27], v[20:21], v[20:21]
	v_pk_add_f32 v[18:19], v[24:25], v[18:19] op_sel_hi:[1,0] neg_lo:[0,1] neg_hi:[0,1]
	v_pk_mul_f32 v[12:13], v[0:1], v[0:1]
	v_pk_mul_f32 v[24:25], v[18:19], v[18:19]
	v_mov_b32_e32 v28, v26
	v_mov_b32_e32 v29, v8
	v_mov_b32_e32 v8, v27
	v_pk_add_f32 v[8:9], v[28:29], v[8:9]
	v_mov_b32_e32 v26, v25
; __device__ __forceinline__ u16 f2bf(float f) { return (u16)(pack2(f, 0.f) & 0xffffu); }
; __device__ __forceinline__ int get_tid() { int t = threadIdx.x; asm volatile("" : "+v"(t)); return t; }
; __device__ __forceinline__ void even_post_phase(const Params& p, int ei, char* smem) {
;     ...
; #pragma unroll
;         for (int n = 0; n < 4; ++n) {
;           const int col = wid * 64 + n * 16 + fr;
;           const float on = (ov[q8][n] - mean) * rstd * lnw[n] + lnb[n];
;           act[row * D + col] = f2bf((on + bon[q8] * vs[q8][n]) * acc[m][n][j]);
;         }
;     ...
;     {
;       const int tid1 = get_tid();
;       const int ti = tid1 >> 3, cg8 = tid1 & 7;
;       const size_t row = (size_t)row0 + ti;
; #pragma unroll
;       for (int v8 = 0; v8 < 8; ++v8) {
;         int ch = cg8 * 64 + v8 * 8;
;         float a[8], bq[8], g[8];
;         unpack8(*(const uint4*)(hf + row * 512 + ch), a);
;         unpack8(*(const uint4*)(hb + row * 512 + ch), bq);
;         unpack8(*(const uint4*)(big + row * PSTR + 2432 + ch), g);
;         float o[8];
; #pragma unroll
;         for (int e = 0; e < 8; ++e) o[e] = (a[e] + bq[e]) * gelu_fast(g[e]);
	v_mov_b32_e32 v27, v13
	v_pk_add_f32 v[8:9], v[26:27], v[8:9]
	v_mov_b32_e32 v25, v12
	v_pk_add_f32 v[8:9], v[24:25], v[8:9]
	s_nop 1
	v_mov_b32_dpp v13, v9 row_ror:8 row_mask:0xf bank_mask:0xf bound_ctrl:1
	v_mov_b32_dpp v12, v8 row_ror:8 row_mask:0xf bank_mask:0xf bound_ctrl:1
	v_pk_add_f32 v[8:9], v[8:9], v[12:13]
	s_nop 1
	v_mov_b32_dpp v13, v9 row_ror:4 row_mask:0xf bank_mask:0xf bound_ctrl:1
	v_mov_b32_dpp v12, v8 row_ror:4 row_mask:0xf bank_mask:0xf bound_ctrl:1
	v_pk_add_f32 v[8:9], v[8:9], v[12:13]
	s_nop 1
	v_mov_b32_dpp v13, v9 row_ror:2 row_mask:0xf bank_mask:0xf bound_ctrl:1
	v_mov_b32_dpp v12, v8 row_ror:2 row_mask:0xf bank_mask:0xf bound_ctrl:1
	v_pk_add_f32 v[8:9], v[8:9], v[12:13]
	s_nop 1
	v_mov_b32_dpp v13, v9 row_ror:1 row_mask:0xf bank_mask:0xf bound_ctrl:1
	v_mov_b32_dpp v12, v8 row_ror:1 row_mask:0xf bank_mask:0xf bound_ctrl:1
	v_pk_add_f32 v[8:9], v[8:9], v[12:13]
	s_nop 0
	v_pk_fma_f32 v[8:9], v[8:9], s[22:23], v[36:37] op_sel_hi:[1,0,0]
	s_nop 0
	v_mul_f32_e32 v12, 0x4b800000, v9
	v_cmp_gt_f32_e32 vcc, s39, v9
	s_nop 1
	v_cndmask_b32_e32 v9, v9, v12, vcc
	v_rsq_f32_e32 v9, v9
	v_lshl_add_u64 v[12:13], s[86:87], 0, v[16:17]
	v_lshl_add_u64 v[16:17], v[12:13], 0, v[130:131]
	v_lshl_add_u64 v[12:13], v[12:13], 0, v[132:133]
	v_mul_f32_e32 v24, 0x45800000, v9
	v_cndmask_b32_e32 v9, v9, v24, vcc
	v_mul_f32_e32 v1, v1, v9
	v_mul_f32_e32 v4, v4, v9
	v_fma_f32 v1, v101, v1, v87
	v_fma_f32 v4, v97, v4, v75
	v_fmac_f32_e32 v1, v140, v160
	v_fmac_f32_e32 v4, v140, v150
	v_mul_f32_e32 v1, v6, v1
	v_mul_f32_e32 v4, v14, v4
	v_cvt_pk_bf16_f32 v1, v1, s0
	v_cvt_pk_bf16_f32 v4, v4, s0
	flat_store_short v[16:17], v1 offset:64
	v_mul_f32_e32 v1, 0x4b800000, v8
	v_cmp_gt_f32_e32 vcc, s39, v8
	flat_store_short v[16:17], v4
	v_mul_f32_e32 v4, v5, v9
	v_mul_f32_e32 v0, v0, v9
	v_cndmask_b32_e32 v1, v8, v1, vcc
	v_fma_f32 v4, v99, v4, v85
	v_fma_f32 v0, v103, v0, v89
	v_rsq_f32_e32 v1, v1
	v_fmac_f32_e32 v4, v140, v155
	v_fmac_f32_e32 v0, v140, v165
	v_mul_f32_e32 v4, v10, v4
	v_mul_f32_e32 v0, v2, v0
	v_cvt_pk_bf16_f32 v4, v4, s0
	v_cvt_pk_bf16_f32 v0, v0, s0
	flat_store_short v[16:17], v4 offset:32
	flat_store_short v[12:13], v0
	v_mul_f32_e32 v0, 0x45800000, v1
	v_cndmask_b32_e32 v2, v1, v0, vcc
	v_mul_f32_e32 v4, v20, v2
	v_fma_f32 v4, v97, v4, v75
	v_lshlrev_b64 v[0:1], 11, v[22:23]
	v_fmac_f32_e32 v4, v162, v172
	v_lshl_add_u64 v[0:1], s[86:87], 0, v[0:1]
	v_mul_f32_e32 v4, v15, v4
	v_cvt_pk_bf16_f32 v6, v4, s0
	v_lshl_add_u64 v[4:5], v[0:1], 0, v[130:131]
	flat_store_short v[4:5], v6
	v_mul_f32_e32 v6, v21, v2
	v_fma_f32 v6, v99, v6, v85
	v_fmac_f32_e32 v6, v162, v178
	v_mul_f32_e32 v6, v11, v6
	v_cvt_pk_bf16_f32 v6, v6, s0
	flat_store_short v[4:5], v6 offset:32
	v_mul_f32_e32 v6, v19, v2
	v_fma_f32 v6, v101, v6, v87
	v_mul_f32_e32 v2, v18, v2
	v_fmac_f32_e32 v6, v162, v183
	v_fma_f32 v2, v103, v2, v89
	v_mul_f32_e32 v6, v7, v6
	v_fmac_f32_e32 v2, v162, v180
	v_cvt_pk_bf16_f32 v6, v6, s0
	v_mul_f32_e32 v2, v3, v2
	flat_store_short v[4:5], v6 offset:64
	v_cvt_pk_bf16_f32 v2, v2, s0
	v_lshl_add_u64 v[0:1], v[0:1], 0, v[132:133]
	v_mov_b32_e32 v6, v107
	flat_store_short v[0:1], v2
	s_nop 0
	v_ashrrev_i32_e32 v0, 3, v6
	v_ashrrev_i32_e32 v1, 31, v0
	v_lshl_add_u64 v[4:5], v[0:1], 0, s[50:51]
	v_lshlrev_b64 v[0:1], 10, v[4:5]
	v_lshlrev_b32_e32 v6, 7, v6
	v_lshl_add_u64 v[2:3], s[74:75], 0, v[0:1]
	v_and_b32_e32 v108, 0x380, v6
	v_lshl_add_u64 v[0:1], s[12:13], 0, v[0:1]
	v_lshl_add_u64 v[6:7], v[2:3], 0, v[108:109]
	v_lshl_add_u64 v[2:3], v[0:1], 0, v[108:109]
	flat_load_dwordx4 v[8:11], v[6:7]
	flat_load_dwordx4 v[20:23], v[6:7] offset:16
	flat_load_dwordx4 v[12:15], v[2:3]
	v_mov_b64_e32 v[0:1], s[8:9]
	v_mad_u64_u32 v[0:1], s[0:1], v4, s19, v[0:1]
	v_mad_i32_i24 v1, v5, s19, v1
	s_mov_b64 s[0:1], 0x1300
	v_lshl_add_u64 v[0:1], v[0:1], 0, s[0:1]
	v_lshl_add_u64 v[16:17], v[0:1], 0, v[108:109]
	flat_load_dwordx4 v[16:19], v[16:17]
	v_lshlrev_b64 v[4:5], 11, v[4:5]
	v_lshl_add_u64 v[4:5], s[86:87], 0, v[4:5]
	v_lshl_add_u64 v[4:5], v[4:5], 0, v[108:109]
	v_readlane_b32 s0, v254, 6
	s_add_i32 s50, s50, s0
	s_cmpk_gt_i32 s26, 0x47f
	s_waitcnt vmcnt(0) lgkmcnt(0)
	v_lshlrev_b32_e32 v24, 16, v8
	v_and_b32_e32 v25, 0xffff0000, v8
	v_lshlrev_b32_e32 v26, 16, v9
	v_and_b32_e32 v27, 0xffff0000, v9
	v_lshlrev_b32_e32 v28, 16, v10
	v_and_b32_e32 v29, 0xffff0000, v10
	v_lshlrev_b32_e32 v30, 16, v11
	v_and_b32_e32 v31, 0xffff0000, v11
	flat_load_dwordx4 v[8:11], v[2:3] offset:16
	v_lshlrev_b32_e32 v32, 16, v12
	v_and_b32_e32 v33, 0xffff0000, v12
	v_lshlrev_b32_e32 v34, 16, v13
	v_and_b32_e32 v35, 0xffff0000, v13
	v_or_b32_e32 v12, 16, v108
	v_mov_b32_e32 v13, v109
	v_lshl_add_u64 v[12:13], v[0:1], 0, v[12:13]
	v_lshlrev_b32_e32 v36, 16, v14
	v_and_b32_e32 v37, 0xffff0000, v14
	v_lshlrev_b32_e32 v38, 16, v15
	v_and_b32_e32 v39, 0xffff0000, v15
	flat_load_dwordx4 v[12:15], v[12:13]
	v_lshlrev_b32_e32 v40, 16, v16
	v_mul_f32_e32 v44, 0x3d372713, v40
	v_mul_f32_e32 v44, v44, v40
	v_mov_b32_e32 v45, v40
	v_and_b32_e32 v41, 0xffff0000, v16
	v_fmac_f32_e32 v45, v44, v45
	v_mul_f32_e32 v44, 0xbfcc422a, v45
	v_mul_f32_e32 v45, 0x3d372713, v41
	v_mul_f32_e32 v45, v45, v41
	v_mov_b32_e32 v46, v41
	v_fmac_f32_e32 v46, v45, v46
	v_mul_f32_e32 v45, 0xbfcc422a, v46
	v_mul_f32_e32 v45, 0x3fb8aa3b, v45
	v_exp_f32_e32 v45, v45
	v_lshlrev_b32_e32 v16, 16, v17
	v_pk_add_f32 v[24:25], v[24:25], v[32:33]
	v_mul_f32_e32 v33, 0x3d372713, v16
	v_add_f32_e32 v32, 1.0, v45
	v_mul_f32_e32 v33, v33, v16
	v_mov_b32_e32 v45, v16
	v_and_b32_e32 v17, 0xffff0000, v17
	v_fmac_f32_e32 v45, v33, v45
	v_mul_f32_e32 v33, 0xbfcc422a, v45
	v_mul_f32_e32 v45, 0x3d372713, v17
; __device__ __forceinline__ void even_post_phase(const Params& p, int ei, char* smem) {
;     ...
;       for (int v8 = 0; v8 < 8; ++v8) {
;         int ch = cg8 * 64 + v8 * 8;
;         float a[8], bq[8], g[8];
;         unpack8(*(const uint4*)(hf + row * 512 + ch), a);
;         unpack8(*(const uint4*)(hb + row * 512 + ch), bq);
;         unpack8(*(const uint4*)(big + row * PSTR + 2432 + ch), g);
;         float o[8];
; #pragma unroll
;         for (int e = 0; e < 8; ++e) o[e] = (a[e] + bq[e]) * gelu_fast(g[e]);
;         uint4 ou;
;         ou.x = pack2(o[0], o[1]); ou.y = pack2(o[2], o[3]); ou.z = pack2(o[4], o[5]); ou.w = pack2(o[6], o[7]);
;         *(uint4*)(act + row * D + 512 + ch) = ou;
	v_mul_f32_e32 v45, v45, v17
	v_mov_b32_e32 v46, v17
	v_fmac_f32_e32 v46, v45, v46
	v_mul_f32_e32 v45, 0xbfcc422a, v46
	v_mul_f32_e32 v33, 0x3fb8aa3b, v33
	v_mul_f32_e32 v45, 0x3fb8aa3b, v45
	v_exp_f32_e32 v33, v33
	v_exp_f32_e32 v46, v45
	v_rcp_f32_e32 v45, v32
	v_lshlrev_b32_e32 v42, 16, v18
	v_add_f32_e32 v32, 1.0, v33
	v_add_f32_e32 v33, 1.0, v46
	v_rcp_f32_e32 v32, v32
	v_rcp_f32_e32 v33, v33
	v_pk_add_f32 v[26:27], v[26:27], v[34:35]
	v_and_b32_e32 v43, 0xffff0000, v18
	v_lshlrev_b32_e32 v18, 16, v19
	v_pk_mul_f32 v[16:17], v[32:33], v[16:17]
	v_mov_b32_e32 v32, v43
	v_pk_mul_f32 v[26:27], v[26:27], v[16:17]
	v_mul_f32_e32 v16, 0x3d372713, v42
	v_mul_f32_e32 v16, v16, v42
	v_mov_b32_e32 v17, v42
	v_fmac_f32_e32 v17, v16, v17
	v_mul_f32_e32 v16, 0xbfcc422a, v17
	v_mul_f32_e32 v17, 0x3d372713, v43
	v_mul_f32_e32 v17, v17, v43
	v_fmac_f32_e32 v32, v17, v32
	v_mul_f32_e32 v17, 0xbfcc422a, v32
	v_mul_f32_e32 v32, 0x3d372713, v18
	v_mul_f32_e32 v32, v32, v18
	v_mov_b32_e32 v33, v18
	v_and_b32_e32 v19, 0xffff0000, v19
	v_fmac_f32_e32 v33, v32, v33
	v_mul_f32_e32 v32, 0xbfcc422a, v33
	v_mul_f32_e32 v33, 0x3d372713, v19
	v_mul_f32_e32 v33, v33, v19
	v_mov_b32_e32 v34, v19
	v_fmac_f32_e32 v34, v33, v34
	v_mul_f32_e32 v16, 0x3fb8aa3b, v16
	v_mul_f32_e32 v17, 0x3fb8aa3b, v17
	v_mul_f32_e32 v33, 0xbfcc422a, v34
	v_mul_f32_e32 v44, 0x3fb8aa3b, v44
	v_exp_f32_e32 v16, v16
	v_exp_f32_e32 v17, v17
	v_mul_f32_e32 v32, 0x3fb8aa3b, v32
	v_mul_f32_e32 v33, 0x3fb8aa3b, v33
	v_exp_f32_e32 v44, v44
	v_exp_f32_e32 v32, v32
	v_exp_f32_e32 v33, v33
	v_add_f32_e32 v16, 1.0, v16
	v_add_f32_e32 v17, 1.0, v17
	v_add_f32_e32 v44, 1.0, v44
	v_rcp_f32_e32 v16, v16
	v_rcp_f32_e32 v17, v17
	v_add_f32_e32 v32, 1.0, v32
	v_add_f32_e32 v33, 1.0, v33
	v_rcp_f32_e32 v44, v44
	v_rcp_f32_e32 v32, v32
	v_rcp_f32_e32 v33, v33
	v_pk_add_f32 v[28:29], v[28:29], v[36:37]
	v_pk_mul_f32 v[16:17], v[16:17], v[42:43]
	v_pk_mul_f32 v[40:41], v[44:45], v[40:41]
	v_pk_mul_f32 v[28:29], v[28:29], v[16:17]
	v_pk_add_f32 v[16:17], v[30:31], v[38:39]
	v_pk_mul_f32 v[18:19], v[32:33], v[18:19]
	v_pk_mul_f32 v[24:25], v[24:25], v[40:41]
	v_pk_mul_f32 v[30:31], v[16:17], v[18:19]
	v_cvt_pk_bf16_f32 v16, v24, v25
	v_cvt_pk_bf16_f32 v17, v26, v27
	v_cvt_pk_bf16_f32 v18, v28, v29
	v_cvt_pk_bf16_f32 v19, v30, v31
	s_waitcnt vmcnt(0) lgkmcnt(0)
	v_lshlrev_b32_e32 v32, 16, v12
	flat_store_dwordx4 v[4:5], v[16:19] offset:1024
	v_lshlrev_b32_e32 v26, 16, v9
	v_and_b32_e32 v27, 0xffff0000, v9
	v_lshlrev_b32_e32 v18, 16, v8
	v_and_b32_e32 v19, 0xffff0000, v8
	v_mul_f32_e32 v8, 0x3d372713, v32
	v_mul_f32_e32 v8, v8, v32
	v_mov_b32_e32 v9, v32
	v_and_b32_e32 v33, 0xffff0000, v12
	v_fmac_f32_e32 v9, v8, v9
	v_mul_f32_e32 v8, 0xbfcc422a, v9
	v_mul_f32_e32 v9, 0x3d372713, v33
	v_lshlrev_b32_e32 v28, 16, v10
	v_and_b32_e32 v29, 0xffff0000, v10
	v_mul_f32_e32 v9, v9, v33
	v_mov_b32_e32 v10, v33
	v_fmac_f32_e32 v10, v9, v10
	v_mul_f32_e32 v9, 0xbfcc422a, v10
	v_mul_f32_e32 v9, 0x3fb8aa3b, v9
	v_exp_f32_e32 v12, v9
	v_mul_f32_e32 v8, 0x3fb8aa3b, v8
	v_lshlrev_b32_e32 v34, 16, v13
	v_exp_f32_e32 v8, v8
	v_add_f32_e32 v41, 1.0, v12
	v_mul_f32_e32 v12, 0x3d372713, v34
	v_and_b32_e32 v35, 0xffff0000, v13
	v_mul_f32_e32 v12, v12, v34
	v_mov_b32_e32 v13, v34
	v_fmac_f32_e32 v13, v12, v13
	v_lshlrev_b32_e32 v16, 16, v20
	v_and_b32_e32 v17, 0xffff0000, v20
	v_add_f32_e32 v8, 1.0, v8
	v_mul_f32_e32 v12, 0xbfcc422a, v13
	v_lshlrev_b32_e32 v30, 16, v11
	v_and_b32_e32 v31, 0xffff0000, v11
	v_lshlrev_b32_e32 v36, 16, v14
	v_and_b32_e32 v37, 0xffff0000, v14
	v_lshlrev_b32_e32 v38, 16, v15
	v_and_b32_e32 v39, 0xffff0000, v15
	v_rcp_f32_e32 v40, v8
	flat_load_dwordx4 v[8:11], v[6:7] offset:32
	v_pk_add_f32 v[42:43], v[16:17], v[18:19]
	v_mul_f32_e32 v16, 0x3fb8aa3b, v12
	flat_load_dwordx4 v[12:15], v[2:3] offset:32
	v_exp_f32_e32 v44, v16
	v_mul_f32_e32 v16, 0x3d372713, v35
	v_mul_f32_e32 v16, v16, v35
	v_mov_b32_e32 v17, v35
	v_fmac_f32_e32 v17, v16, v17
	v_mul_f32_e32 v16, 0xbfcc422a, v17
	v_mul_f32_e32 v16, 0x3fb8aa3b, v16
	v_exp_f32_e32 v45, v16
	v_or_b32_e32 v16, 32, v108
	v_mov_b32_e32 v17, v109
	v_lshl_add_u64 v[16:17], v[0:1], 0, v[16:17]
	flat_load_dwordx4 v[16:19], v[16:17]
	v_add_f32_e32 v44, 1.0, v44
	v_add_f32_e32 v45, 1.0, v45
	v_rcp_f32_e32 v44, v44
	v_rcp_f32_e32 v45, v45
	v_lshlrev_b32_e32 v20, 16, v21
	v_and_b32_e32 v21, 0xffff0000, v21
	v_pk_add_f32 v[20:21], v[20:21], v[26:27]
	v_pk_mul_f32 v[26:27], v[44:45], v[34:35]
	v_lshlrev_b32_e32 v24, 16, v22
	v_pk_mul_f32 v[26:27], v[20:21], v[26:27]
	v_mul_f32_e32 v20, 0x3d372713, v36
	v_and_b32_e32 v25, 0xffff0000, v22
	v_mul_f32_e32 v20, v20, v36
	v_mov_b32_e32 v21, v36
	v_fmac_f32_e32 v21, v20, v21
	v_pk_add_f32 v[24:25], v[24:25], v[28:29]
	v_mul_f32_e32 v28, 0x3d372713, v38
	v_mul_f32_e32 v20, 0xbfcc422a, v21
	v_mul_f32_e32 v21, 0x3d372713, v37
	v_mul_f32_e32 v28, v28, v38
	v_mov_b32_e32 v29, v38
	v_mul_f32_e32 v21, v21, v37
	v_mov_b32_e32 v34, v37
	v_fmac_f32_e32 v29, v28, v29
	v_fmac_f32_e32 v34, v21, v34
	v_mul_f32_e32 v28, 0xbfcc422a, v29
	v_mul_f32_e32 v29, 0x3d372713, v39
	v_mul_f32_e32 v21, 0xbfcc422a, v34
	v_mul_f32_e32 v29, v29, v39
	v_mov_b32_e32 v34, v39
	v_fmac_f32_e32 v34, v29, v34
	v_mul_f32_e32 v20, 0x3fb8aa3b, v20
	v_mul_f32_e32 v21, 0x3fb8aa3b, v21
	v_mul_f32_e32 v29, 0xbfcc422a, v34
	v_exp_f32_e32 v20, v20
	v_exp_f32_e32 v21, v21
	v_mul_f32_e32 v28, 0x3fb8aa3b, v28
	v_mul_f32_e32 v29, 0x3fb8aa3b, v29
	v_exp_f32_e32 v28, v28
	v_exp_f32_e32 v29, v29
	v_add_f32_e32 v20, 1.0, v20
	v_add_f32_e32 v21, 1.0, v21
	v_rcp_f32_e32 v20, v20
	v_rcp_f32_e32 v21, v21
	v_add_f32_e32 v28, 1.0, v28
	v_add_f32_e32 v29, 1.0, v29
	v_rcp_f32_e32 v41, v41
	v_rcp_f32_e32 v28, v28
	v_rcp_f32_e32 v29, v29
	v_lshlrev_b32_e32 v22, 16, v23
	v_and_b32_e32 v23, 0xffff0000, v23
	v_pk_mul_f32 v[20:21], v[20:21], v[36:37]
	v_pk_mul_f32 v[32:33], v[40:41], v[32:33]
	v_pk_mul_f32 v[24:25], v[24:25], v[20:21]
	v_pk_add_f32 v[20:21], v[22:23], v[30:31]
	v_pk_mul_f32 v[22:23], v[28:29], v[38:39]
	v_pk_mul_f32 v[32:33], v[42:43], v[32:33]
	v_pk_mul_f32 v[28:29], v[20:21], v[22:23]
	v_cvt_pk_bf16_f32 v20, v32, v33
	v_cvt_pk_bf16_f32 v21, v26, v27
	v_cvt_pk_bf16_f32 v22, v24, v25
	v_cvt_pk_bf16_f32 v23, v28, v29
	flat_store_dwordx4 v[4:5], v[20:23] offset:1040
	flat_load_dwordx4 v[20:23], v[6:7] offset:48
	s_waitcnt vmcnt(0) lgkmcnt(0)
; __device__ __forceinline__ void even_post_phase(const Params& p, int ei, char* smem) {
;     ...
;       for (int v8 = 0; v8 < 8; ++v8) {
;         int ch = cg8 * 64 + v8 * 8;
;         float a[8], bq[8], g[8];
;         unpack8(*(const uint4*)(hf + row * 512 + ch), a);
;         unpack8(*(const uint4*)(hb + row * 512 + ch), bq);
;         unpack8(*(const uint4*)(big + row * PSTR + 2432 + ch), g);
;         float o[8];
; #pragma unroll
;         for (int e = 0; e < 8; ++e) o[e] = (a[e] + bq[e]) * gelu_fast(g[e]);
;         uint4 ou;
;         ou.x = pack2(o[0], o[1]); ou.y = pack2(o[2], o[3]); ou.z = pack2(o[4], o[5]); ou.w = pack2(o[6], o[7]);
;         *(uint4*)(act + row * D + 512 + ch) = ou;
	v_lshlrev_b32_e32 v24, 16, v8
	v_and_b32_e32 v25, 0xffff0000, v8
	v_lshlrev_b32_e32 v26, 16, v9
	v_and_b32_e32 v27, 0xffff0000, v9
	v_lshlrev_b32_e32 v28, 16, v10
	v_and_b32_e32 v29, 0xffff0000, v10
	v_lshlrev_b32_e32 v30, 16, v11
	v_and_b32_e32 v31, 0xffff0000, v11
	flat_load_dwordx4 v[8:11], v[2:3] offset:48
	v_lshlrev_b32_e32 v32, 16, v12
	v_and_b32_e32 v33, 0xffff0000, v12
	v_lshlrev_b32_e32 v34, 16, v13
	v_and_b32_e32 v35, 0xffff0000, v13
	v_or_b32_e32 v12, 48, v108
	v_mov_b32_e32 v13, v109
	v_lshl_add_u64 v[12:13], v[0:1], 0, v[12:13]
	v_lshlrev_b32_e32 v36, 16, v14
	v_and_b32_e32 v37, 0xffff0000, v14
	v_lshlrev_b32_e32 v38, 16, v15
	v_and_b32_e32 v39, 0xffff0000, v15
	flat_load_dwordx4 v[12:15], v[12:13]
	v_lshlrev_b32_e32 v40, 16, v16
	v_mul_f32_e32 v44, 0x3d372713, v40
	v_mul_f32_e32 v44, v44, v40
	v_mov_b32_e32 v45, v40
	v_and_b32_e32 v41, 0xffff0000, v16
	v_fmac_f32_e32 v45, v44, v45
	v_mul_f32_e32 v44, 0xbfcc422a, v45
	v_mul_f32_e32 v45, 0x3d372713, v41
	v_mul_f32_e32 v45, v45, v41
	v_mov_b32_e32 v46, v41
	v_fmac_f32_e32 v46, v45, v46
	v_mul_f32_e32 v45, 0xbfcc422a, v46
	v_mul_f32_e32 v45, 0x3fb8aa3b, v45
	v_exp_f32_e32 v45, v45
	v_lshlrev_b32_e32 v16, 16, v17
	v_pk_add_f32 v[24:25], v[24:25], v[32:33]
	v_mul_f32_e32 v33, 0x3d372713, v16
	v_add_f32_e32 v32, 1.0, v45
	v_mul_f32_e32 v33, v33, v16
	v_mov_b32_e32 v45, v16
	v_and_b32_e32 v17, 0xffff0000, v17
	v_fmac_f32_e32 v45, v33, v45
	v_mul_f32_e32 v33, 0xbfcc422a, v45
	v_mul_f32_e32 v45, 0x3d372713, v17
	v_mul_f32_e32 v45, v45, v17
	v_mov_b32_e32 v46, v17
	v_fmac_f32_e32 v46, v45, v46
	v_mul_f32_e32 v45, 0xbfcc422a, v46
	v_mul_f32_e32 v33, 0x3fb8aa3b, v33
	v_mul_f32_e32 v45, 0x3fb8aa3b, v45
	v_exp_f32_e32 v33, v33
	v_exp_f32_e32 v46, v45
	v_rcp_f32_e32 v45, v32
	v_lshlrev_b32_e32 v42, 16, v18
	v_add_f32_e32 v32, 1.0, v33
	v_add_f32_e32 v33, 1.0, v46
	v_rcp_f32_e32 v32, v32
	v_rcp_f32_e32 v33, v33
	v_pk_add_f32 v[26:27], v[26:27], v[34:35]
	v_and_b32_e32 v43, 0xffff0000, v18
	v_lshlrev_b32_e32 v18, 16, v19
	v_pk_mul_f32 v[16:17], v[32:33], v[16:17]
	v_mov_b32_e32 v32, v43
	v_pk_mul_f32 v[26:27], v[26:27], v[16:17]
	v_mul_f32_e32 v16, 0x3d372713, v42
	v_mul_f32_e32 v16, v16, v42
	v_mov_b32_e32 v17, v42
	v_fmac_f32_e32 v17, v16, v17
	v_mul_f32_e32 v16, 0xbfcc422a, v17
	v_mul_f32_e32 v17, 0x3d372713, v43
	v_mul_f32_e32 v17, v17, v43
	v_fmac_f32_e32 v32, v17, v32
	v_mul_f32_e32 v17, 0xbfcc422a, v32
	v_mul_f32_e32 v32, 0x3d372713, v18
	v_mul_f32_e32 v32, v32, v18
	v_mov_b32_e32 v33, v18
	v_and_b32_e32 v19, 0xffff0000, v19
	v_fmac_f32_e32 v33, v32, v33
	v_mul_f32_e32 v32, 0xbfcc422a, v33
	v_mul_f32_e32 v33, 0x3d372713, v19
	v_mul_f32_e32 v33, v33, v19
	v_mov_b32_e32 v34, v19
	v_fmac_f32_e32 v34, v33, v34
	v_mul_f32_e32 v16, 0x3fb8aa3b, v16
	v_mul_f32_e32 v17, 0x3fb8aa3b, v17
	v_mul_f32_e32 v33, 0xbfcc422a, v34
	v_mul_f32_e32 v44, 0x3fb8aa3b, v44
	v_exp_f32_e32 v16, v16
	v_exp_f32_e32 v17, v17
	v_mul_f32_e32 v32, 0x3fb8aa3b, v32
	v_mul_f32_e32 v33, 0x3fb8aa3b, v33
	v_exp_f32_e32 v44, v44
	v_exp_f32_e32 v32, v32
	v_exp_f32_e32 v33, v33
	v_add_f32_e32 v16, 1.0, v16
	v_add_f32_e32 v17, 1.0, v17
	v_add_f32_e32 v44, 1.0, v44
	v_rcp_f32_e32 v16, v16
	v_rcp_f32_e32 v17, v17
	v_add_f32_e32 v32, 1.0, v32
	v_add_f32_e32 v33, 1.0, v33
	v_rcp_f32_e32 v44, v44
	v_rcp_f32_e32 v32, v32
	v_rcp_f32_e32 v33, v33
	v_pk_add_f32 v[28:29], v[28:29], v[36:37]
	v_pk_mul_f32 v[16:17], v[16:17], v[42:43]
	v_pk_mul_f32 v[40:41], v[44:45], v[40:41]
	v_pk_mul_f32 v[28:29], v[28:29], v[16:17]
	v_pk_add_f32 v[16:17], v[30:31], v[38:39]
	v_pk_mul_f32 v[18:19], v[32:33], v[18:19]
	v_pk_mul_f32 v[24:25], v[24:25], v[40:41]
	v_pk_mul_f32 v[30:31], v[16:17], v[18:19]
	v_cvt_pk_bf16_f32 v16, v24, v25
	v_cvt_pk_bf16_f32 v17, v26, v27
	v_cvt_pk_bf16_f32 v18, v28, v29
	v_cvt_pk_bf16_f32 v19, v30, v31
	s_waitcnt vmcnt(0) lgkmcnt(0)
	v_lshlrev_b32_e32 v32, 16, v12
	flat_store_dwordx4 v[4:5], v[16:19] offset:1056
	v_lshlrev_b32_e32 v26, 16, v9
	v_and_b32_e32 v27, 0xffff0000, v9
	v_lshlrev_b32_e32 v18, 16, v8
	v_and_b32_e32 v19, 0xffff0000, v8
	v_mul_f32_e32 v8, 0x3d372713, v32
	v_mul_f32_e32 v8, v8, v32
	v_mov_b32_e32 v9, v32
	v_and_b32_e32 v33, 0xffff0000, v12
	v_fmac_f32_e32 v9, v8, v9
	v_mul_f32_e32 v8, 0xbfcc422a, v9
	v_mul_f32_e32 v9, 0x3d372713, v33
	v_lshlrev_b32_e32 v28, 16, v10
	v_and_b32_e32 v29, 0xffff0000, v10
	v_mul_f32_e32 v9, v9, v33
	v_mov_b32_e32 v10, v33
	v_fmac_f32_e32 v10, v9, v10
	v_mul_f32_e32 v9, 0xbfcc422a, v10
	v_mul_f32_e32 v9, 0x3fb8aa3b, v9
	v_exp_f32_e32 v12, v9
	v_mul_f32_e32 v8, 0x3fb8aa3b, v8
	v_lshlrev_b32_e32 v34, 16, v13
	v_exp_f32_e32 v8, v8
	v_add_f32_e32 v41, 1.0, v12
	v_mul_f32_e32 v12, 0x3d372713, v34
	v_and_b32_e32 v35, 0xffff0000, v13
	v_mul_f32_e32 v12, v12, v34
	v_mov_b32_e32 v13, v34
	v_fmac_f32_e32 v13, v12, v13
	v_lshlrev_b32_e32 v16, 16, v20
	v_and_b32_e32 v17, 0xffff0000, v20
	v_add_f32_e32 v8, 1.0, v8
	v_mul_f32_e32 v12, 0xbfcc422a, v13
	v_lshlrev_b32_e32 v30, 16, v11
	v_and_b32_e32 v31, 0xffff0000, v11
	v_lshlrev_b32_e32 v36, 16, v14
	v_and_b32_e32 v37, 0xffff0000, v14
	v_lshlrev_b32_e32 v38, 16, v15
	v_and_b32_e32 v39, 0xffff0000, v15
	v_rcp_f32_e32 v40, v8
	flat_load_dwordx4 v[8:11], v[6:7] offset:64
	v_pk_add_f32 v[42:43], v[16:17], v[18:19]
	v_mul_f32_e32 v16, 0x3fb8aa3b, v12
	flat_load_dwordx4 v[12:15], v[2:3] offset:64
	v_exp_f32_e32 v44, v16
	v_mul_f32_e32 v16, 0x3d372713, v35
	v_mul_f32_e32 v16, v16, v35
	v_mov_b32_e32 v17, v35
	v_fmac_f32_e32 v17, v16, v17
	v_mul_f32_e32 v16, 0xbfcc422a, v17
	v_mul_f32_e32 v16, 0x3fb8aa3b, v16
	v_exp_f32_e32 v45, v16
	v_or_b32_e32 v16, 64, v108
	v_mov_b32_e32 v17, v109
	v_lshl_add_u64 v[16:17], v[0:1], 0, v[16:17]
; __device__ __forceinline__ void even_post_phase(const Params& p, int ei, char* smem) {
;     ...
;       for (int v8 = 0; v8 < 8; ++v8) {
;         int ch = cg8 * 64 + v8 * 8;
;         float a[8], bq[8], g[8];
;         unpack8(*(const uint4*)(hf + row * 512 + ch), a);
;         unpack8(*(const uint4*)(hb + row * 512 + ch), bq);
;         unpack8(*(const uint4*)(big + row * PSTR + 2432 + ch), g);
;         float o[8];
; #pragma unroll
;         for (int e = 0; e < 8; ++e) o[e] = (a[e] + bq[e]) * gelu_fast(g[e]);
;         uint4 ou;
;         ou.x = pack2(o[0], o[1]); ou.y = pack2(o[2], o[3]); ou.z = pack2(o[4], o[5]); ou.w = pack2(o[6], o[7]);
;         *(uint4*)(act + row * D + 512 + ch) = ou;
	flat_load_dwordx4 v[16:19], v[16:17]
	v_add_f32_e32 v44, 1.0, v44
	v_add_f32_e32 v45, 1.0, v45
	v_rcp_f32_e32 v44, v44
	v_rcp_f32_e32 v45, v45
	v_lshlrev_b32_e32 v20, 16, v21
	v_and_b32_e32 v21, 0xffff0000, v21
	v_pk_add_f32 v[20:21], v[20:21], v[26:27]
	v_pk_mul_f32 v[26:27], v[44:45], v[34:35]
	v_lshlrev_b32_e32 v24, 16, v22
	v_pk_mul_f32 v[26:27], v[20:21], v[26:27]
	v_mul_f32_e32 v20, 0x3d372713, v36
	v_and_b32_e32 v25, 0xffff0000, v22
	v_mul_f32_e32 v20, v20, v36
	v_mov_b32_e32 v21, v36
	v_fmac_f32_e32 v21, v20, v21
	v_pk_add_f32 v[24:25], v[24:25], v[28:29]
	v_mul_f32_e32 v28, 0x3d372713, v38
	v_mul_f32_e32 v20, 0xbfcc422a, v21
	v_mul_f32_e32 v21, 0x3d372713, v37
	v_mul_f32_e32 v28, v28, v38
	v_mov_b32_e32 v29, v38
	v_mul_f32_e32 v21, v21, v37
	v_mov_b32_e32 v34, v37
	v_fmac_f32_e32 v29, v28, v29
	v_fmac_f32_e32 v34, v21, v34
	v_mul_f32_e32 v28, 0xbfcc422a, v29
	v_mul_f32_e32 v29, 0x3d372713, v39
	v_mul_f32_e32 v21, 0xbfcc422a, v34
	v_mul_f32_e32 v29, v29, v39
	v_mov_b32_e32 v34, v39
	v_fmac_f32_e32 v34, v29, v34
	v_mul_f32_e32 v20, 0x3fb8aa3b, v20
	v_mul_f32_e32 v21, 0x3fb8aa3b, v21
	v_mul_f32_e32 v29, 0xbfcc422a, v34
	v_exp_f32_e32 v20, v20
	v_exp_f32_e32 v21, v21
	v_mul_f32_e32 v28, 0x3fb8aa3b, v28
	v_mul_f32_e32 v29, 0x3fb8aa3b, v29
	v_exp_f32_e32 v28, v28
	v_exp_f32_e32 v29, v29
	v_add_f32_e32 v20, 1.0, v20
	v_add_f32_e32 v21, 1.0, v21
	v_rcp_f32_e32 v20, v20
	v_rcp_f32_e32 v21, v21
	v_add_f32_e32 v28, 1.0, v28
	v_add_f32_e32 v29, 1.0, v29
	v_rcp_f32_e32 v41, v41
	v_rcp_f32_e32 v28, v28
	v_rcp_f32_e32 v29, v29
	v_lshlrev_b32_e32 v22, 16, v23
	v_and_b32_e32 v23, 0xffff0000, v23
	v_pk_mul_f32 v[20:21], v[20:21], v[36:37]
	v_pk_mul_f32 v[32:33], v[40:41], v[32:33]
	v_pk_mul_f32 v[24:25], v[24:25], v[20:21]
	v_pk_add_f32 v[20:21], v[22:23], v[30:31]
	v_pk_mul_f32 v[22:23], v[28:29], v[38:39]
	v_pk_mul_f32 v[32:33], v[42:43], v[32:33]
	v_pk_mul_f32 v[28:29], v[20:21], v[22:23]
	v_cvt_pk_bf16_f32 v20, v32, v33
	v_cvt_pk_bf16_f32 v21, v26, v27
	v_cvt_pk_bf16_f32 v22, v24, v25
	v_cvt_pk_bf16_f32 v23, v28, v29
	flat_store_dwordx4 v[4:5], v[20:23] offset:1072
	flat_load_dwordx4 v[20:23], v[6:7] offset:80
	s_waitcnt vmcnt(0) lgkmcnt(0)
	v_lshlrev_b32_e32 v24, 16, v8
	v_and_b32_e32 v25, 0xffff0000, v8
	v_lshlrev_b32_e32 v26, 16, v9
	v_and_b32_e32 v27, 0xffff0000, v9
	v_lshlrev_b32_e32 v28, 16, v10
	v_and_b32_e32 v29, 0xffff0000, v10
	v_lshlrev_b32_e32 v30, 16, v11
	v_and_b32_e32 v31, 0xffff0000, v11
	flat_load_dwordx4 v[8:11], v[2:3] offset:80
	v_lshlrev_b32_e32 v32, 16, v12
	v_and_b32_e32 v33, 0xffff0000, v12
	v_lshlrev_b32_e32 v34, 16, v13
	v_and_b32_e32 v35, 0xffff0000, v13
	v_or_b32_e32 v12, 0x50, v108
	v_mov_b32_e32 v13, v109
	v_lshl_add_u64 v[12:13], v[0:1], 0, v[12:13]
	v_lshlrev_b32_e32 v36, 16, v14
	v_and_b32_e32 v37, 0xffff0000, v14
	v_lshlrev_b32_e32 v38, 16, v15
	v_and_b32_e32 v39, 0xffff0000, v15
	flat_load_dwordx4 v[12:15], v[12:13]
	v_lshlrev_b32_e32 v40, 16, v16
	v_mul_f32_e32 v44, 0x3d372713, v40
	v_mul_f32_e32 v44, v44, v40
	v_mov_b32_e32 v45, v40
	v_and_b32_e32 v41, 0xffff0000, v16
	v_fmac_f32_e32 v45, v44, v45
	v_mul_f32_e32 v44, 0xbfcc422a, v45
	v_mul_f32_e32 v45, 0x3d372713, v41
	v_mul_f32_e32 v45, v45, v41
	v_mov_b32_e32 v46, v41
	v_fmac_f32_e32 v46, v45, v46
	v_mul_f32_e32 v45, 0xbfcc422a, v46
	v_mul_f32_e32 v45, 0x3fb8aa3b, v45
	v_exp_f32_e32 v45, v45
	v_lshlrev_b32_e32 v16, 16, v17
	v_pk_add_f32 v[24:25], v[24:25], v[32:33]
	v_mul_f32_e32 v33, 0x3d372713, v16
	v_add_f32_e32 v32, 1.0, v45
	v_mul_f32_e32 v33, v33, v16
	v_mov_b32_e32 v45, v16
	v_and_b32_e32 v17, 0xffff0000, v17
	v_fmac_f32_e32 v45, v33, v45
	v_mul_f32_e32 v33, 0xbfcc422a, v45
	v_mul_f32_e32 v45, 0x3d372713, v17
	v_mul_f32_e32 v45, v45, v17
	v_mov_b32_e32 v46, v17
	v_fmac_f32_e32 v46, v45, v46
	v_mul_f32_e32 v45, 0xbfcc422a, v46
	v_mul_f32_e32 v33, 0x3fb8aa3b, v33
	v_mul_f32_e32 v45, 0x3fb8aa3b, v45
	v_exp_f32_e32 v33, v33
	v_exp_f32_e32 v46, v45
	v_rcp_f32_e32 v45, v32
	v_lshlrev_b32_e32 v42, 16, v18
	v_add_f32_e32 v32, 1.0, v33
	v_add_f32_e32 v33, 1.0, v46
	v_rcp_f32_e32 v32, v32
	v_rcp_f32_e32 v33, v33
	v_pk_add_f32 v[26:27], v[26:27], v[34:35]
	v_and_b32_e32 v43, 0xffff0000, v18
	v_lshlrev_b32_e32 v18, 16, v19
	v_pk_mul_f32 v[16:17], v[32:33], v[16:17]
	v_mov_b32_e32 v32, v43
	v_pk_mul_f32 v[26:27], v[26:27], v[16:17]
	v_mul_f32_e32 v16, 0x3d372713, v42
	v_mul_f32_e32 v16, v16, v42
	v_mov_b32_e32 v17, v42
	v_fmac_f32_e32 v17, v16, v17
	v_mul_f32_e32 v16, 0xbfcc422a, v17
	v_mul_f32_e32 v17, 0x3d372713, v43
	v_mul_f32_e32 v17, v17, v43
	v_fmac_f32_e32 v32, v17, v32
	v_mul_f32_e32 v17, 0xbfcc422a, v32
	v_mul_f32_e32 v32, 0x3d372713, v18
	v_mul_f32_e32 v32, v32, v18
	v_mov_b32_e32 v33, v18
	v_and_b32_e32 v19, 0xffff0000, v19
	v_fmac_f32_e32 v33, v32, v33
	v_mul_f32_e32 v32, 0xbfcc422a, v33
	v_mul_f32_e32 v33, 0x3d372713, v19
	v_mul_f32_e32 v33, v33, v19
	v_mov_b32_e32 v34, v19
	v_fmac_f32_e32 v34, v33, v34
	v_mul_f32_e32 v16, 0x3fb8aa3b, v16
	v_mul_f32_e32 v17, 0x3fb8aa3b, v17
	v_mul_f32_e32 v33, 0xbfcc422a, v34
	v_mul_f32_e32 v44, 0x3fb8aa3b, v44
	v_exp_f32_e32 v16, v16
	v_exp_f32_e32 v17, v17
	v_mul_f32_e32 v32, 0x3fb8aa3b, v32
	v_mul_f32_e32 v33, 0x3fb8aa3b, v33
	v_exp_f32_e32 v44, v44
	v_exp_f32_e32 v32, v32
	v_exp_f32_e32 v33, v33
	v_add_f32_e32 v16, 1.0, v16
	v_add_f32_e32 v17, 1.0, v17
	v_add_f32_e32 v44, 1.0, v44
	v_rcp_f32_e32 v16, v16
	v_rcp_f32_e32 v17, v17
	v_add_f32_e32 v32, 1.0, v32
	v_add_f32_e32 v33, 1.0, v33
	v_rcp_f32_e32 v44, v44
	v_rcp_f32_e32 v32, v32
	v_rcp_f32_e32 v33, v33
	v_pk_add_f32 v[28:29], v[28:29], v[36:37]
	v_pk_mul_f32 v[16:17], v[16:17], v[42:43]
	v_pk_mul_f32 v[40:41], v[44:45], v[40:41]
	v_pk_mul_f32 v[28:29], v[28:29], v[16:17]
	v_pk_add_f32 v[16:17], v[30:31], v[38:39]
	v_pk_mul_f32 v[18:19], v[32:33], v[18:19]
	v_pk_mul_f32 v[24:25], v[24:25], v[40:41]
	v_pk_mul_f32 v[30:31], v[16:17], v[18:19]
	v_cvt_pk_bf16_f32 v16, v24, v25
	v_cvt_pk_bf16_f32 v17, v26, v27
	v_cvt_pk_bf16_f32 v18, v28, v29
	v_cvt_pk_bf16_f32 v19, v30, v31
	s_waitcnt vmcnt(0) lgkmcnt(0)
; __device__ __forceinline__ void even_post_phase(const Params& p, int ei, char* smem) {
;     ...
;       for (int v8 = 0; v8 < 8; ++v8) {
;         int ch = cg8 * 64 + v8 * 8;
;         float a[8], bq[8], g[8];
;         unpack8(*(const uint4*)(hf + row * 512 + ch), a);
;         unpack8(*(const uint4*)(hb + row * 512 + ch), bq);
;         unpack8(*(const uint4*)(big + row * PSTR + 2432 + ch), g);
;         float o[8];
; #pragma unroll
;         for (int e = 0; e < 8; ++e) o[e] = (a[e] + bq[e]) * gelu_fast(g[e]);
;         uint4 ou;
;         ou.x = pack2(o[0], o[1]); ou.y = pack2(o[2], o[3]); ou.z = pack2(o[4], o[5]); ou.w = pack2(o[6], o[7]);
;         *(uint4*)(act + row * D + 512 + ch) = ou;
	v_lshlrev_b32_e32 v32, 16, v12
	flat_store_dwordx4 v[4:5], v[16:19] offset:1088
	v_lshlrev_b32_e32 v26, 16, v9
	v_and_b32_e32 v27, 0xffff0000, v9
	v_lshlrev_b32_e32 v18, 16, v8
	v_and_b32_e32 v19, 0xffff0000, v8
	v_mul_f32_e32 v8, 0x3d372713, v32
	v_mul_f32_e32 v8, v8, v32
	v_mov_b32_e32 v9, v32
	v_fmac_f32_e32 v9, v8, v9
	v_mul_f32_e32 v8, 0xbfcc422a, v9
	v_and_b32_e32 v33, 0xffff0000, v12
	v_mul_f32_e32 v8, 0x3fb8aa3b, v8
	v_exp_f32_e32 v8, v8
	v_mul_f32_e32 v9, 0x3d372713, v33
	v_lshlrev_b32_e32 v28, 16, v10
	v_and_b32_e32 v29, 0xffff0000, v10
	v_mul_f32_e32 v9, v9, v33
	v_mov_b32_e32 v10, v33
	v_fmac_f32_e32 v10, v9, v10
	v_mul_f32_e32 v9, 0xbfcc422a, v10
	v_add_f32_e32 v8, 1.0, v8
	v_mul_f32_e32 v9, 0x3fb8aa3b, v9
	v_lshlrev_b32_e32 v30, 16, v11
	v_and_b32_e32 v31, 0xffff0000, v11
	v_exp_f32_e32 v12, v9
	v_rcp_f32_e32 v40, v8
	flat_load_dwordx4 v[8:11], v[6:7] offset:96
	v_lshlrev_b32_e32 v34, 16, v13
	v_add_f32_e32 v41, 1.0, v12
	v_mul_f32_e32 v12, 0x3d372713, v34
	v_and_b32_e32 v35, 0xffff0000, v13
	v_mul_f32_e32 v12, v12, v34
	v_mov_b32_e32 v13, v34
	v_fmac_f32_e32 v13, v12, v13
	v_lshlrev_b32_e32 v16, 16, v20
	v_and_b32_e32 v17, 0xffff0000, v20
	v_mul_f32_e32 v12, 0xbfcc422a, v13
	v_pk_add_f32 v[42:43], v[16:17], v[18:19]
	v_mul_f32_e32 v16, 0x3fb8aa3b, v12
	v_exp_f32_e32 v44, v16
	v_mul_f32_e32 v16, 0x3d372713, v35
	v_mul_f32_e32 v16, v16, v35
	v_mov_b32_e32 v17, v35
	v_fmac_f32_e32 v17, v16, v17
	v_mul_f32_e32 v16, 0xbfcc422a, v17
	v_mul_f32_e32 v45, 0x3fb8aa3b, v16
	v_or_b32_e32 v16, 0x60, v108
	v_mov_b32_e32 v17, v109
	v_lshl_add_u64 v[16:17], v[0:1], 0, v[16:17]
	flat_load_dwordx4 v[16:19], v[16:17]
	v_lshlrev_b32_e32 v36, 16, v14
	v_and_b32_e32 v37, 0xffff0000, v14
	v_lshlrev_b32_e32 v38, 16, v15
	v_and_b32_e32 v39, 0xffff0000, v15
	flat_load_dwordx4 v[12:15], v[2:3] offset:96
	v_exp_f32_e32 v45, v45
	v_add_f32_e32 v44, 1.0, v44
	v_rcp_f32_e32 v44, v44
	v_lshlrev_b32_e32 v20, 16, v21
	v_add_f32_e32 v45, 1.0, v45
	v_rcp_f32_e32 v45, v45
	v_and_b32_e32 v21, 0xffff0000, v21
	v_pk_add_f32 v[20:21], v[20:21], v[26:27]
	v_lshlrev_b32_e32 v24, 16, v22
	v_pk_mul_f32 v[26:27], v[44:45], v[34:35]
	v_and_b32_e32 v25, 0xffff0000, v22
	v_pk_mul_f32 v[26:27], v[20:21], v[26:27]
	v_mul_f32_e32 v20, 0x3d372713, v36
	v_mul_f32_e32 v20, v20, v36
	v_mov_b32_e32 v21, v36
	v_fmac_f32_e32 v21, v20, v21
	v_pk_add_f32 v[24:25], v[24:25], v[28:29]
	v_mul_f32_e32 v28, 0x3d372713, v38
	v_mul_f32_e32 v20, 0xbfcc422a, v21
	v_mul_f32_e32 v21, 0x3d372713, v37
	v_mul_f32_e32 v28, v28, v38
	v_mov_b32_e32 v29, v38
	v_mul_f32_e32 v21, v21, v37
	v_mov_b32_e32 v34, v37
	v_fmac_f32_e32 v29, v28, v29
	v_fmac_f32_e32 v34, v21, v34
	v_mul_f32_e32 v28, 0xbfcc422a, v29
	v_mul_f32_e32 v29, 0x3d372713, v39
	v_mul_f32_e32 v21, 0xbfcc422a, v34
	v_mul_f32_e32 v29, v29, v39
	v_mov_b32_e32 v34, v39
	v_fmac_f32_e32 v34, v29, v34
	v_mul_f32_e32 v20, 0x3fb8aa3b, v20
	v_mul_f32_e32 v21, 0x3fb8aa3b, v21
	v_mul_f32_e32 v29, 0xbfcc422a, v34
	v_exp_f32_e32 v20, v20
	v_exp_f32_e32 v21, v21
	v_mul_f32_e32 v28, 0x3fb8aa3b, v28
	v_mul_f32_e32 v29, 0x3fb8aa3b, v29
	v_exp_f32_e32 v28, v28
	v_exp_f32_e32 v29, v29
	v_add_f32_e32 v20, 1.0, v20
	v_add_f32_e32 v21, 1.0, v21
	v_rcp_f32_e32 v20, v20
	v_rcp_f32_e32 v21, v21
	v_add_f32_e32 v28, 1.0, v28
	v_add_f32_e32 v29, 1.0, v29
	v_rcp_f32_e32 v41, v41
	v_rcp_f32_e32 v28, v28
	v_rcp_f32_e32 v29, v29
	v_lshlrev_b32_e32 v22, 16, v23
	v_and_b32_e32 v23, 0xffff0000, v23
	v_pk_mul_f32 v[20:21], v[20:21], v[36:37]
	v_pk_mul_f32 v[32:33], v[40:41], v[32:33]
	v_pk_mul_f32 v[24:25], v[24:25], v[20:21]
	v_pk_add_f32 v[20:21], v[22:23], v[30:31]
	v_pk_mul_f32 v[22:23], v[28:29], v[38:39]
	v_pk_mul_f32 v[32:33], v[42:43], v[32:33]
	v_pk_mul_f32 v[28:29], v[20:21], v[22:23]
	v_or_b32_e32 v108, 0x70, v108
	v_cvt_pk_bf16_f32 v20, v32, v33
	v_cvt_pk_bf16_f32 v21, v26, v27
	v_cvt_pk_bf16_f32 v22, v24, v25
	v_cvt_pk_bf16_f32 v23, v28, v29
	v_lshl_add_u64 v[0:1], v[0:1], 0, v[108:109]
	flat_store_dwordx4 v[4:5], v[20:23] offset:1104
	flat_load_dwordx4 v[20:23], v[6:7] offset:112
	s_waitcnt vmcnt(0) lgkmcnt(0)
	v_lshlrev_b32_e32 v24, 16, v8
	v_and_b32_e32 v25, 0xffff0000, v8
	v_lshlrev_b32_e32 v26, 16, v9
	v_and_b32_e32 v27, 0xffff0000, v9
	flat_load_dwordx4 v[6:9], v[2:3] offset:112
	v_lshlrev_b32_e32 v28, 16, v10
	flat_load_dwordx4 v[0:3], v[0:1]
	v_lshlrev_b32_e32 v34, 16, v16
	v_mul_f32_e32 v38, 0x3d372713, v34
	v_mul_f32_e32 v38, v38, v34
	v_mov_b32_e32 v39, v34
	v_and_b32_e32 v35, 0xffff0000, v16
	v_fmac_f32_e32 v39, v38, v39
	v_mul_f32_e32 v38, 0xbfcc422a, v39
	v_mul_f32_e32 v39, 0x3d372713, v35
	v_mul_f32_e32 v39, v39, v35
	v_mov_b32_e32 v40, v35
	v_fmac_f32_e32 v40, v39, v40
	v_mul_f32_e32 v39, 0xbfcc422a, v40
	v_mul_f32_e32 v39, 0x3fb8aa3b, v39
	v_exp_f32_e32 v39, v39
	v_lshlrev_b32_e32 v30, 16, v12
	v_and_b32_e32 v31, 0xffff0000, v12
	v_lshlrev_b32_e32 v16, 16, v17
	v_pk_add_f32 v[24:25], v[24:25], v[30:31]
	v_mul_f32_e32 v31, 0x3d372713, v16
	v_add_f32_e32 v30, 1.0, v39
	v_mul_f32_e32 v31, v31, v16
	v_mov_b32_e32 v39, v16
	v_and_b32_e32 v17, 0xffff0000, v17
	v_fmac_f32_e32 v39, v31, v39
	v_mul_f32_e32 v31, 0xbfcc422a, v39
	v_mul_f32_e32 v39, 0x3d372713, v17
	v_mul_f32_e32 v39, v39, v17
	v_mov_b32_e32 v40, v17
	v_fmac_f32_e32 v40, v39, v40
	v_mul_f32_e32 v39, 0xbfcc422a, v40
	v_mul_f32_e32 v31, 0x3fb8aa3b, v31
	v_mul_f32_e32 v39, 0x3fb8aa3b, v39
	v_exp_f32_e32 v31, v31
	v_exp_f32_e32 v40, v39
	v_rcp_f32_e32 v39, v30
	v_lshlrev_b32_e32 v12, 16, v13
	v_add_f32_e32 v30, 1.0, v31
	v_add_f32_e32 v31, 1.0, v40
	v_rcp_f32_e32 v30, v30
	v_rcp_f32_e32 v31, v31
	v_and_b32_e32 v13, 0xffff0000, v13
	v_lshlrev_b32_e32 v36, 16, v18
	v_pk_add_f32 v[12:13], v[26:27], v[12:13]
; __device__ __forceinline__ void even_post_phase(const Params& p, int ei, char* smem) {
;     ...
;       for (int v8 = 0; v8 < 8; ++v8) {
;         int ch = cg8 * 64 + v8 * 8;
;         float a[8], bq[8], g[8];
;         unpack8(*(const uint4*)(hf + row * 512 + ch), a);
;         unpack8(*(const uint4*)(hb + row * 512 + ch), bq);
;         unpack8(*(const uint4*)(big + row * PSTR + 2432 + ch), g);
;         float o[8];
; #pragma unroll
;         for (int e = 0; e < 8; ++e) o[e] = (a[e] + bq[e]) * gelu_fast(g[e]);
;         uint4 ou;
;         ou.x = pack2(o[0], o[1]); ou.y = pack2(o[2], o[3]); ou.z = pack2(o[4], o[5]); ou.w = pack2(o[6], o[7]);
;         *(uint4*)(act + row * D + 512 + ch) = ou;
;       }
;     }
;     __syncthreads();
	v_pk_mul_f32 v[16:17], v[30:31], v[16:17]
	v_and_b32_e32 v37, 0xffff0000, v18
	v_pk_mul_f32 v[12:13], v[12:13], v[16:17]
	v_mul_f32_e32 v16, 0x3d372713, v36
	v_mul_f32_e32 v16, v16, v36
	v_mov_b32_e32 v17, v36
	v_fmac_f32_e32 v17, v16, v17
	v_mul_f32_e32 v16, 0xbfcc422a, v17
	v_mul_f32_e32 v17, 0x3d372713, v37
	v_mul_f32_e32 v17, v17, v37
	v_mov_b32_e32 v26, v37
	v_and_b32_e32 v29, 0xffff0000, v10
	v_lshlrev_b32_e32 v32, 16, v14
	v_and_b32_e32 v33, 0xffff0000, v14
	v_lshlrev_b32_e32 v18, 16, v19
	v_fmac_f32_e32 v26, v17, v26
	v_mul_f32_e32 v17, 0xbfcc422a, v26
	v_pk_add_f32 v[26:27], v[28:29], v[32:33]
	v_mul_f32_e32 v28, 0x3d372713, v18
	v_mul_f32_e32 v28, v28, v18
	v_mov_b32_e32 v29, v18
	v_and_b32_e32 v19, 0xffff0000, v19
	v_fmac_f32_e32 v29, v28, v29
	v_mul_f32_e32 v28, 0xbfcc422a, v29
	v_mul_f32_e32 v29, 0x3d372713, v19
	v_mul_f32_e32 v29, v29, v19
	v_mov_b32_e32 v30, v19
	v_fmac_f32_e32 v30, v29, v30
	v_mul_f32_e32 v29, 0xbfcc422a, v30
	v_mul_f32_e32 v28, 0x3fb8aa3b, v28
	v_mul_f32_e32 v29, 0x3fb8aa3b, v29
	v_exp_f32_e32 v28, v28
	v_exp_f32_e32 v29, v29
	v_mul_f32_e32 v16, 0x3fb8aa3b, v16
	v_mul_f32_e32 v17, 0x3fb8aa3b, v17
	v_exp_f32_e32 v16, v16
	v_exp_f32_e32 v17, v17
	v_add_f32_e32 v28, 1.0, v28
	v_add_f32_e32 v29, 1.0, v29
	v_rcp_f32_e32 v28, v28
	v_rcp_f32_e32 v29, v29
	v_add_f32_e32 v16, 1.0, v16
	v_add_f32_e32 v17, 1.0, v17
	v_rcp_f32_e32 v16, v16
	v_rcp_f32_e32 v17, v17
	v_lshlrev_b32_e32 v10, 16, v11
	v_and_b32_e32 v11, 0xffff0000, v11
	v_lshlrev_b32_e32 v14, 16, v15
	v_and_b32_e32 v15, 0xffff0000, v15
	v_mul_f32_e32 v38, 0x3fb8aa3b, v38
	v_pk_add_f32 v[10:11], v[10:11], v[14:15]
	v_pk_mul_f32 v[14:15], v[28:29], v[18:19]
	v_exp_f32_e32 v38, v38
	v_pk_mul_f32 v[14:15], v[10:11], v[14:15]
	v_pk_mul_f32 v[16:17], v[16:17], v[36:37]
	v_cvt_pk_bf16_f32 v11, v12, v13
	v_cvt_pk_bf16_f32 v13, v14, v15
	v_lshlrev_b32_e32 v14, 16, v22
	v_and_b32_e32 v15, 0xffff0000, v22
	s_waitcnt vmcnt(0) lgkmcnt(0)
	v_lshlrev_b32_e32 v22, 16, v0
	v_pk_mul_f32 v[16:17], v[26:27], v[16:17]
	v_mul_f32_e32 v26, 0x3d372713, v22
	v_mul_f32_e32 v26, v26, v22
	v_mov_b32_e32 v27, v22
	v_add_f32_e32 v38, 1.0, v38
	v_cvt_pk_bf16_f32 v12, v16, v17
	v_lshlrev_b32_e32 v16, 16, v23
	v_and_b32_e32 v17, 0xffff0000, v23
	v_and_b32_e32 v23, 0xffff0000, v0
	v_fmac_f32_e32 v27, v26, v27
	v_rcp_f32_e32 v38, v38
	v_mul_f32_e32 v26, 0xbfcc422a, v27
	v_mul_f32_e32 v27, 0x3d372713, v23
	v_mul_f32_e32 v27, v27, v23
	v_mov_b32_e32 v28, v23
	v_fmac_f32_e32 v28, v27, v28
	v_mul_f32_e32 v27, 0xbfcc422a, v28
	v_pk_mul_f32 v[34:35], v[38:39], v[34:35]
	v_mul_f32_e32 v27, 0x3fb8aa3b, v27
	v_pk_mul_f32 v[24:25], v[24:25], v[34:35]
	v_exp_f32_e32 v27, v27
	v_cvt_pk_bf16_f32 v10, v24, v25
	flat_store_dwordx4 v[4:5], v[10:13] offset:1120
	v_lshlrev_b32_e32 v18, 16, v6
	v_and_b32_e32 v19, 0xffff0000, v6
	v_lshlrev_b32_e32 v10, 16, v20
	v_and_b32_e32 v11, 0xffff0000, v20
	v_lshlrev_b32_e32 v0, 16, v1
	v_pk_add_f32 v[10:11], v[10:11], v[18:19]
	v_mul_f32_e32 v19, 0x3d372713, v0
	v_add_f32_e32 v18, 1.0, v27
	v_mul_f32_e32 v19, v19, v0
	v_mov_b32_e32 v27, v0
	v_and_b32_e32 v1, 0xffff0000, v1
	v_fmac_f32_e32 v27, v19, v27
	v_mul_f32_e32 v19, 0xbfcc422a, v27
	v_mul_f32_e32 v27, 0x3d372713, v1
	v_mul_f32_e32 v27, v27, v1
	v_mov_b32_e32 v28, v1
	v_fmac_f32_e32 v28, v27, v28
	v_mul_f32_e32 v27, 0xbfcc422a, v28
	v_mul_f32_e32 v19, 0x3fb8aa3b, v19
	v_mul_f32_e32 v27, 0x3fb8aa3b, v27
	v_exp_f32_e32 v19, v19
	v_exp_f32_e32 v28, v27
	v_rcp_f32_e32 v27, v18
	v_lshlrev_b32_e32 v12, 16, v21
	v_add_f32_e32 v18, 1.0, v19
	v_add_f32_e32 v19, 1.0, v28
	v_rcp_f32_e32 v18, v18
	v_rcp_f32_e32 v19, v19
	v_and_b32_e32 v13, 0xffff0000, v21
	v_lshlrev_b32_e32 v6, 16, v7
	v_and_b32_e32 v7, 0xffff0000, v7
	v_lshlrev_b32_e32 v24, 16, v2
	v_pk_add_f32 v[6:7], v[12:13], v[6:7]
	v_pk_mul_f32 v[0:1], v[18:19], v[0:1]
	v_and_b32_e32 v25, 0xffff0000, v2
	v_pk_mul_f32 v[6:7], v[6:7], v[0:1]
	v_mul_f32_e32 v0, 0x3d372713, v24
	v_mul_f32_e32 v0, v0, v24
	v_mov_b32_e32 v1, v24
	v_fmac_f32_e32 v1, v0, v1
	v_mul_f32_e32 v0, 0xbfcc422a, v1
	v_mul_f32_e32 v1, 0x3d372713, v25
	v_mul_f32_e32 v1, v1, v25
	v_mov_b32_e32 v12, v25
	v_lshlrev_b32_e32 v20, 16, v8
	v_and_b32_e32 v21, 0xffff0000, v8
	v_lshlrev_b32_e32 v2, 16, v3
	v_fmac_f32_e32 v12, v1, v12
	v_mul_f32_e32 v1, 0xbfcc422a, v12
	v_pk_add_f32 v[12:13], v[14:15], v[20:21]
	v_mul_f32_e32 v14, 0x3d372713, v2
	v_mul_f32_e32 v14, v14, v2
	v_mov_b32_e32 v15, v2
	v_and_b32_e32 v3, 0xffff0000, v3
	v_fmac_f32_e32 v15, v14, v15
	v_mul_f32_e32 v14, 0xbfcc422a, v15
	v_mul_f32_e32 v15, 0x3d372713, v3
	v_mul_f32_e32 v15, v15, v3
	v_mov_b32_e32 v18, v3
	v_fmac_f32_e32 v18, v15, v18
	v_mul_f32_e32 v0, 0x3fb8aa3b, v0
	v_mul_f32_e32 v1, 0x3fb8aa3b, v1
	v_mul_f32_e32 v15, 0xbfcc422a, v18
	v_mul_f32_e32 v26, 0x3fb8aa3b, v26
	v_exp_f32_e32 v0, v0
	v_exp_f32_e32 v1, v1
	v_mul_f32_e32 v14, 0x3fb8aa3b, v14
	v_mul_f32_e32 v15, 0x3fb8aa3b, v15
	v_exp_f32_e32 v26, v26
	v_exp_f32_e32 v14, v14
	v_exp_f32_e32 v15, v15
	v_add_f32_e32 v0, 1.0, v0
	v_add_f32_e32 v1, 1.0, v1
	v_add_f32_e32 v26, 1.0, v26
	v_rcp_f32_e32 v0, v0
	v_rcp_f32_e32 v1, v1
	v_add_f32_e32 v14, 1.0, v14
	v_add_f32_e32 v15, 1.0, v15
	v_rcp_f32_e32 v26, v26
	v_rcp_f32_e32 v14, v14
	v_rcp_f32_e32 v15, v15
	v_lshlrev_b32_e32 v8, 16, v9
	v_and_b32_e32 v9, 0xffff0000, v9
	v_pk_mul_f32 v[0:1], v[0:1], v[24:25]
	v_pk_mul_f32 v[22:23], v[26:27], v[22:23]
	v_pk_mul_f32 v[12:13], v[12:13], v[0:1]
	v_pk_add_f32 v[0:1], v[16:17], v[8:9]
	v_pk_mul_f32 v[2:3], v[14:15], v[2:3]
	v_pk_mul_f32 v[10:11], v[10:11], v[22:23]
	v_pk_mul_f32 v[8:9], v[0:1], v[2:3]
	v_cvt_pk_bf16_f32 v0, v10, v11
	v_cvt_pk_bf16_f32 v1, v6, v7
	v_cvt_pk_bf16_f32 v2, v12, v13
	v_cvt_pk_bf16_f32 v3, v8, v9
	flat_store_dwordx4 v[4:5], v[0:3] offset:1136
	s_waitcnt lgkmcnt(0)
	s_barrier
	s_cbranch_scc1 .LBB0_772

; __device__ __forceinline__ float sigm(float x) { return __builtin_amdgcn_rcpf(1.f + __expf(-x)); }
; #define MFMA(a, b, c) __builtin_amdgcn_mfma_f32_16x16x32_bf16(a, b, c, 0, 0, 0)
; __device__ __forceinline__ void even_post_phase(const Params& p, int ei, char* smem) {
;     ...
;       const u16* pc = big + row * PSTR + 1792 + cg8 * 16;
; #pragma unroll
;       for (int hh = 0; hh < 2; ++hh) {
;         float c[8], pv[8], nv[8];
;         unpack8(*(const uint4*)(pc + hh * 8), c);
;         if (hp) unpack8(*(const uint4*)(pc - PSTR + hh * 8), pv); else { for (int e = 0; e < 8; ++e) pv[e] = 0.f; }
;         if (hn) unpack8(*(const uint4*)(pc + PSTR + hh * 8), nv); else { for (int e = 0; e < 8; ++e) nv[e] = 0.f; }
;         float o[8];
; #pragma unroll
;         for (int e = 0; e < 8; ++e) {
;           float m = mu[1792 + cg8 * 16 + hh * 8 + e];
;           o[e] = sigm(c[e] + m * (0.5f * (pv[e] + nv[e]) - c[e]));
;         }
;         uint4 ou;
;         ou.x = pack2(o[0], o[1]); ou.y = pack2(o[2], o[3]); ou.z = pack2(o[4], o[5]); ou.w = pack2(o[6], o[7]);
;         *(uint4*)(smem + sw256(ti, cg8 * 2 + hh)) = ou;
;       }
;     }
;     __syncthreads();
;     f32x4 acc[4][4];
; #pragma unroll
;     for (int m = 0; m < 4; ++m)
; #pragma unroll
;       for (int n = 0; n < 4; ++n) acc[m][n] = f32x4{0.f, 0.f, 0.f, 0.f};
; #pragma unroll
;     for (int ks = 0; ks < 4; ++ks) {
;       bf16x8 af[4], bg[4];
; #pragma unroll
;       for (int m = 0; m < 4; ++m) af[m] = *(const bf16x8*)(smem + sw256(m * 16 + fr, ks * 4 + fq));
; #pragma unroll
;       for (int n = 0; n < 4; ++n) bg[n] = *(const bf16x8*)(gup + (size_t)(wid * 64 + n * 16 + fr) * 128 + ks * 32 + fq * 8);
; #pragma unroll
;       for (int m = 0; m < 4; ++m)
; #pragma unroll
;         for (int n = 0; n < 4; ++n) acc[m][n] = MFMA(af[m], bg[n], acc[m][n]);
;     }
.LBB0_516:
	s_or_b64 exec, exec, s[0:1]
	flat_load_dwordx4 v[28:31], v[10:11] offset:3104
	flat_load_dwordx4 v[32:35], v[10:11] offset:3120
	s_waitcnt vmcnt(0) lgkmcnt(0)
	v_lshlrev_b32_e32 v6, 16, v0
	v_and_b32_e32 v0, 0xffff0000, v0
	v_lshlrev_b32_e32 v7, 16, v1
	v_and_b32_e32 v1, 0xffff0000, v1
	v_lshlrev_b32_e32 v10, 16, v2
	v_and_b32_e32 v2, 0xffff0000, v2
	v_lshlrev_b32_e32 v11, 16, v3
	v_and_b32_e32 v3, 0xffff0000, v3
	v_add_f32_e32 v14, v15, v14
	v_add_f32_e32 v15, v16, v23
	v_add_f32_e32 v16, v17, v24
	v_add_f32_e32 v17, v18, v25
	v_add_f32_e32 v18, v19, v26
	v_add_f32_e32 v13, v13, v22
	v_add_f32_e32 v9, v9, v21
	v_add_f32_e32 v8, v8, v20
	v_fma_f32 v14, v14, 0.5, -v6
	v_fma_f32 v15, v15, 0.5, -v0
	v_fma_f32 v16, v16, 0.5, -v7
	v_fma_f32 v17, v17, 0.5, -v1
	v_fma_f32 v18, v18, 0.5, -v10
	v_fma_f32 v13, v13, 0.5, -v2
	v_fma_f32 v9, v9, 0.5, -v11
	v_fma_f32 v8, v8, 0.5, -v3
	v_and_b32_e32 v4, 15, v4
	v_bitop3_b32 v4, v5, v4, 1 bitop3:0x36
	v_lshl_add_u32 v4, v4, 4, v12
	v_or_b32_e32 v108, s46, v74
	v_fmac_f32_e32 v6, v28, v14
	v_fmac_f32_e32 v0, v29, v15
	v_fmac_f32_e32 v7, v30, v16
	v_fmac_f32_e32 v1, v17, v31
	v_fmac_f32_e32 v10, v18, v32
	v_fmac_f32_e32 v2, v13, v33
	v_fmac_f32_e32 v11, v9, v34
	v_fmac_f32_e32 v3, v8, v35
	v_mul_f32_e32 v5, 0xbfb8aa3b, v6
	v_mul_f32_e32 v0, 0xbfb8aa3b, v0
	v_mul_f32_e32 v6, 0xbfb8aa3b, v7
	v_mul_f32_e32 v1, 0xbfb8aa3b, v1
	v_mul_f32_e32 v7, 0xbfb8aa3b, v10
	v_mul_f32_e32 v2, 0xbfb8aa3b, v2
	v_mul_f32_e32 v8, 0xbfb8aa3b, v11
	v_mul_f32_e32 v3, 0xbfb8aa3b, v3
	v_exp_f32_e32 v5, v5
	v_exp_f32_e32 v0, v0
	v_exp_f32_e32 v6, v6
	v_exp_f32_e32 v1, v1
	v_exp_f32_e32 v7, v7
	v_exp_f32_e32 v2, v2
	v_exp_f32_e32 v8, v8
	v_exp_f32_e32 v3, v3
	v_add_f32_e32 v5, 1.0, v5
	v_add_f32_e32 v0, 1.0, v0
	v_add_f32_e32 v6, 1.0, v6
	v_add_f32_e32 v1, 1.0, v1
	v_add_f32_e32 v7, 1.0, v7
	v_add_f32_e32 v2, 1.0, v2
	v_add_f32_e32 v8, 1.0, v8
	v_add_f32_e32 v3, 1.0, v3
	v_rcp_f32_e32 v5, v5
	v_rcp_f32_e32 v0, v0
	v_rcp_f32_e32 v6, v6
	v_rcp_f32_e32 v1, v1
	v_rcp_f32_e32 v7, v7
	v_rcp_f32_e32 v2, v2
	v_rcp_f32_e32 v8, v8
	v_rcp_f32_e32 v3, v3
	v_cvt_pk_bf16_f32 v0, v5, v0
	v_cvt_pk_bf16_f32 v1, v6, v1
	v_cvt_pk_bf16_f32 v2, v7, v2
	v_cvt_pk_bf16_f32 v3, v8, v3
	ds_write_b128 v4, v[0:3]
	s_waitcnt lgkmcnt(0)
	s_barrier
	flat_load_dwordx4 v[0:3], v[76:77]
	flat_load_dwordx4 v[134:137], v[76:77] offset:64
	flat_load_dwordx4 v[12:15], v[78:79]
	flat_load_dwordx4 v[138:141], v[78:79] offset:64
	flat_load_dwordx4 v[20:23], v[80:81]
	flat_load_dwordx4 v[142:145], v[80:81] offset:64
	flat_load_dwordx4 v[28:31], v[82:83]
	flat_load_dwordx4 v[146:149], v[82:83] offset:64
	ds_read_b128 v[4:7], v123
	ds_read_b128 v[32:35], v123 offset:4096
	ds_read_b128 v[48:51], v123 offset:8192
	ds_read_b128 v[130:133], v123 offset:12288
	s_waitcnt vmcnt(0) lgkmcnt(0)
	v_mfma_f32_16x16x32_bf16 v[8:11], v[4:7], v[0:3], 0
	ds_read_b128 v[182:185], v129 offset:12288
	flat_load_dwordx4 v[174:177], v[80:81] offset:192
	flat_load_dwordx4 v[178:181], v[82:83] offset:192
	v_mfma_f32_16x16x32_bf16 v[16:19], v[4:7], v[12:15], 0
	v_mfma_f32_16x16x32_bf16 v[24:27], v[4:7], v[20:23], 0
	v_mfma_f32_16x16x32_bf16 v[4:7], v[4:7], v[28:31], 0
	v_mfma_f32_16x16x32_bf16 v[36:39], v[32:35], v[0:3], 0
	v_mfma_f32_16x16x32_bf16 v[40:43], v[32:35], v[12:15], 0
	v_mfma_f32_16x16x32_bf16 v[44:47], v[32:35], v[20:23], 0
	v_mfma_f32_16x16x32_bf16 v[32:35], v[32:35], v[28:31], 0
	v_mfma_f32_16x16x32_bf16 v[52:55], v[48:51], v[0:3], 0
	v_mfma_f32_16x16x32_bf16 v[56:59], v[48:51], v[12:15], 0
	v_mfma_f32_16x16x32_bf16 v[60:63], v[48:51], v[20:23], 0
	v_mfma_f32_16x16x32_bf16 v[48:51], v[48:51], v[28:31], 0
	v_mfma_f32_16x16x32_bf16 v[0:3], v[130:133], v[0:3], 0
	v_mfma_f32_16x16x32_bf16 v[12:15], v[130:133], v[12:15], 0
	v_mfma_f32_16x16x32_bf16 v[20:23], v[130:133], v[20:23], 0
	v_mfma_f32_16x16x32_bf16 v[28:31], v[130:133], v[28:31], 0
	ds_read_b128 v[130:133], v125
	s_waitcnt lgkmcnt(0)
	v_mfma_f32_16x16x32_bf16 v[8:11], v[130:133], v[134:137], v[8:11]
	v_mfma_f32_16x16x32_bf16 v[16:19], v[130:133], v[138:141], v[16:19]
	v_mfma_f32_16x16x32_bf16 v[24:27], v[130:133], v[142:145], v[24:27]
	v_mfma_f32_16x16x32_bf16 v[4:7], v[130:133], v[146:149], v[4:7]
	ds_read_b128 v[130:133], v125 offset:4096
	s_waitcnt lgkmcnt(0)
	v_mfma_f32_16x16x32_bf16 v[36:39], v[130:133], v[134:137], v[36:39]
	v_mfma_f32_16x16x32_bf16 v[40:43], v[130:133], v[138:141], v[40:43]
	v_mfma_f32_16x16x32_bf16 v[44:47], v[130:133], v[142:145], v[44:47]
	v_mfma_f32_16x16x32_bf16 v[32:35], v[130:133], v[146:149], v[32:35]
	ds_read_b128 v[130:133], v125 offset:8192
	s_waitcnt lgkmcnt(0)
	v_mfma_f32_16x16x32_bf16 v[52:55], v[130:133], v[134:137], v[52:55]
	v_mfma_f32_16x16x32_bf16 v[56:59], v[130:133], v[138:141], v[56:59]
	v_mfma_f32_16x16x32_bf16 v[60:63], v[130:133], v[142:145], v[60:63]
	v_mfma_f32_16x16x32_bf16 v[48:51], v[130:133], v[146:149], v[48:51]
	ds_read_b128 v[130:133], v125 offset:12288
	s_waitcnt lgkmcnt(0)
	v_mfma_f32_16x16x32_bf16 v[0:3], v[130:133], v[134:137], v[0:3]
	flat_load_dwordx4 v[134:137], v[76:77] offset:128
	v_mfma_f32_16x16x32_bf16 v[12:15], v[130:133], v[138:141], v[12:15]
	flat_load_dwordx4 v[138:141], v[78:79] offset:128
	v_mfma_f32_16x16x32_bf16 v[20:23], v[130:133], v[142:145], v[20:23]
	flat_load_dwordx4 v[142:145], v[80:81] offset:128
	v_mfma_f32_16x16x32_bf16 v[28:31], v[130:133], v[146:149], v[28:31]
	flat_load_dwordx4 v[146:149], v[82:83] offset:128
	ds_read_b128 v[130:133], v127
	s_waitcnt vmcnt(0) lgkmcnt(0)
; __device__ __forceinline__ float bf2f(u16 h) { return __uint_as_float(((unsigned)h) << 16); }
; #define MFMA(a, b, c) __builtin_amdgcn_mfma_f32_16x16x32_bf16(a, b, c, 0, 0, 0)
; __device__ __forceinline__ void even_post_phase(const Params& p, int ei, char* smem) {
;     ...
;     for (int ks = 0; ks < 4; ++ks) {
;       bf16x8 af[4], bg[4];
; #pragma unroll
;       for (int m = 0; m < 4; ++m) af[m] = *(const bf16x8*)(smem + sw256(m * 16 + fr, ks * 4 + fq));
; #pragma unroll
;       for (int n = 0; n < 4; ++n) bg[n] = *(const bf16x8*)(gup + (size_t)(wid * 64 + n * 16 + fr) * 128 + ks * 32 + fq * 8);
; #pragma unroll
;       for (int m = 0; m < 4; ++m)
; #pragma unroll
;         for (int n = 0; n < 4; ++n) acc[m][n] = MFMA(af[m], bg[n], acc[m][n]);
;     }
; #pragma unroll
;     for (int mh = 0; mh < 4; ++mh) {
;       float ov[4][4], vs[4][4], bon[4];
; #pragma unroll
;       for (int q8 = 0; q8 < 4; ++q8) {
;         const int m = mh, j = q8;
;         const int tk = m * 16 + fq * 4 + j;
;         const size_t row = (size_t)row0 + tk;
;         const int l = l0 + tk;
;         const bool hp = l > seg_lo, hn = (l + 1) < seg_hi;
;         bon[q8] = 0.5f * (bonf[row * 8 + wid] + bonb[row * 8 + wid]);
; #pragma unroll
;         for (int n = 0; n < 4; ++n) {
;           const int col = wid * 64 + n * 16 + fr;
;           ov[q8][n] = bf2f(of[row * 512 + col]) + bf2f(ob[row * 512 + col]);
;           const u16* pv = big + row * PSTR + 1024 + col;
;           const float c = bf2f(*pv);
;           const float pr = hp ? bf2f(*(pv - PSTR)) : 0.f;
;           const float nx = hn ? bf2f(*(pv + PSTR)) : 0.f;
;           vs[q8][n] = c + muv[n] * (0.5f * (pr + nx) - c);
;         }
;       }
	v_mfma_f32_16x16x32_bf16 v[8:11], v[130:133], v[134:137], v[8:11]
	v_mfma_f32_16x16x32_bf16 v[16:19], v[130:133], v[138:141], v[16:19]
	v_mfma_f32_16x16x32_bf16 v[24:27], v[130:133], v[142:145], v[24:27]
	v_mfma_f32_16x16x32_bf16 v[4:7], v[130:133], v[146:149], v[4:7]
	ds_read_b128 v[130:133], v127 offset:4096
	s_waitcnt lgkmcnt(0)
	v_mfma_f32_16x16x32_bf16 v[150:153], v[130:133], v[142:145], v[44:47]
	s_nop 2
	ds_read_b128 v[44:47], v127 offset:8192
	s_waitcnt lgkmcnt(0)
	v_mfma_f32_16x16x32_bf16 v[154:157], v[44:47], v[134:137], v[52:55]
	v_mfma_f32_16x16x32_bf16 v[158:161], v[44:47], v[138:141], v[56:59]
	v_mfma_f32_16x16x32_bf16 v[162:165], v[44:47], v[142:145], v[60:63]
	v_mfma_f32_16x16x32_bf16 v[166:169], v[44:47], v[146:149], v[48:51]
	ds_read_b128 v[44:47], v127 offset:12288
	v_mfma_f32_16x16x32_bf16 v[36:39], v[130:133], v[134:137], v[36:39]
	v_mfma_f32_16x16x32_bf16 v[40:43], v[130:133], v[138:141], v[40:43]
	s_waitcnt lgkmcnt(0)
	v_mfma_f32_16x16x32_bf16 v[0:3], v[44:47], v[134:137], v[0:3]
	v_mfma_f32_16x16x32_bf16 v[136:139], v[44:47], v[138:141], v[12:15]
	s_nop 2
	flat_load_dwordx4 v[12:15], v[76:77] offset:192
	v_mfma_f32_16x16x32_bf16 v[140:143], v[44:47], v[142:145], v[20:23]
	s_nop 2
	ds_read_b128 v[20:23], v129
	s_waitcnt vmcnt(0) lgkmcnt(0)
	v_mfma_f32_16x16x32_bf16 v[48:51], v[20:23], v[12:15], v[8:11]
	s_nop 2
	flat_load_dwordx4 v[8:11], v[78:79] offset:192
	v_mfma_f32_16x16x32_bf16 v[52:55], v[20:23], v[178:181], v[4:7]
	s_nop 2
	ds_read_b128 v[4:7], v129 offset:4096
	s_waitcnt vmcnt(0) lgkmcnt(0)
	v_mfma_f32_16x16x32_bf16 v[60:63], v[20:23], v[8:11], v[16:19]
	v_mfma_f32_16x16x32_bf16 v[56:59], v[20:23], v[174:177], v[24:27]
	ds_read_b128 v[20:23], v129 offset:8192
	v_mfma_f32_16x16x32_bf16 v[32:35], v[130:133], v[146:149], v[32:35]
	v_mov_b32_e32 v131, s51
	v_or_b32_e32 v130, s50, v74
	v_lshlrev_b64 v[134:135], 9, v[130:131]
	v_mfma_f32_16x16x32_bf16 v[170:173], v[44:47], v[146:149], v[28:31]
	v_mov_b64_e32 v[132:133], s[8:9]
	v_lshl_add_u64 v[144:145], v[134:135], 0, v[64:65]
	v_mad_i64_i32 v[132:133], s[0:1], v130, s19, v[132:133]
	v_mfma_f32_16x16x32_bf16 v[44:47], v[4:7], v[12:15], v[36:39]
	v_lshlrev_b64 v[144:145], 1, v[144:145]
	v_cmp_lt_i32_e64 s[0:1], s47, v108
	v_mfma_f32_16x16x32_bf16 v[40:43], v[4:7], v[8:11], v[40:43]
	v_mfma_f32_16x16x32_bf16 v[36:39], v[4:7], v[174:177], v[150:153]
	v_mfma_f32_16x16x32_bf16 v[32:35], v[4:7], v[178:181], v[32:35]
	v_lshl_add_u64 v[4:5], v[130:131], 3, v[72:73]
	v_lshlrev_b64 v[4:5], 2, v[4:5]
	v_lshl_add_u64 v[6:7], s[42:43], 0, v[4:5]
	v_lshl_add_u64 v[4:5], s[14:15], 0, v[4:5]
	s_waitcnt lgkmcnt(0)
	v_mfma_f32_16x16x32_bf16 v[28:31], v[20:23], v[8:11], v[158:161]
	v_lshl_add_u64 v[150:151], s[16:17], 0, v[144:145]
	v_lshl_add_u64 v[144:145], s[10:11], 0, v[144:145]
	flat_load_dword v146, v[6:7]
	flat_load_dword v149, v[4:5]
	flat_load_ushort v147, v[150:151]
	flat_load_ushort v148, v[144:145]
	v_mfma_f32_16x16x32_bf16 v[8:11], v[182:185], v[8:11], v[136:139]
	v_mov_b32_e32 v152, 0
	v_mov_b32_e32 v151, 0
	s_nop 0
	v_lshl_add_u64 v[136:137], v[64:65], 1, v[132:133]
	flat_load_ushort v150, v[136:137] offset:2048
	v_mfma_f32_16x16x32_bf16 v[24:27], v[20:23], v[12:15], v[154:157]
	v_lshl_add_u64 v[138:139], v[136:137], 0, s[54:55]
	v_mfma_f32_16x16x32_bf16 v[16:19], v[20:23], v[174:177], v[162:165]
	v_mfma_f32_16x16x32_bf16 v[20:23], v[20:23], v[178:181], v[166:169]
	v_mfma_f32_16x16x32_bf16 v[12:15], v[182:185], v[12:15], v[0:3]
	v_mfma_f32_16x16x32_bf16 v[4:7], v[182:185], v[174:177], v[140:143]
	v_mfma_f32_16x16x32_bf16 v[0:3], v[182:185], v[178:181], v[170:173]
	s_and_saveexec_b64 s[4:5], s[0:1]
	s_cbranch_execz .LBB0_518
	v_add_co_u32_e32 v140, vcc, 0xffffe900, v138
	s_nop 1
	v_addc_co_u32_e32 v141, vcc, -1, v139, vcc
	flat_load_ushort v151, v[140:141]
.LBB0_518:
	s_or_b64 exec, exec, s[4:5]
	s_add_i32 s80, s80, -1
	v_cmp_gt_i32_e64 s[4:5], s80, v108
	v_mov_b32_e32 v153, 0
	s_and_saveexec_b64 s[44:45], s[4:5]
	s_cbranch_execz .LBB0_520
	v_add_co_u32_e32 v138, vcc, 0x1000, v138
	s_nop 1
	v_addc_co_u32_e32 v139, vcc, 0, v139, vcc
	flat_load_ushort v153, v[138:139] offset:1792
.LBB0_520:
	s_or_b64 exec, exec, s[44:45]
	v_lshl_add_u64 v[138:139], v[134:135], 0, v[68:69]
	v_lshlrev_b64 v[138:139], 1, v[138:139]
	v_lshl_add_u64 v[140:141], s[16:17], 0, v[138:139]
	v_lshl_add_u64 v[138:139], s[10:11], 0, v[138:139]
	flat_load_ushort v154, v[140:141]
	flat_load_ushort v155, v[138:139]
	flat_load_ushort v156, v[136:137] offset:2080
	v_lshl_add_u64 v[138:139], v[136:137], 0, s[56:57]
	s_and_saveexec_b64 s[44:45], s[0:1]
	s_cbranch_execz .LBB0_522
	v_add_co_u32_e32 v140, vcc, 0xffffe900, v138
	s_nop 1
	v_addc_co_u32_e32 v141, vcc, -1, v139, vcc
	flat_load_ushort v152, v[140:141]
.LBB0_522:
	s_or_b64 exec, exec, s[44:45]
	v_mov_b32_e32 v158, 0
	v_mov_b32_e32 v157, 0
	s_and_saveexec_b64 s[44:45], s[4:5]
	s_cbranch_execz .LBB0_524
	v_add_co_u32_e32 v138, vcc, 0x1000, v138
	s_nop 1
	v_addc_co_u32_e32 v139, vcc, 0, v139, vcc
	flat_load_ushort v157, v[138:139] offset:1792
.LBB0_524:
	s_or_b64 exec, exec, s[44:45]
	v_lshl_add_u64 v[138:139], v[134:135], 0, v[70:71]
	v_lshlrev_b64 v[138:139], 1, v[138:139]
	v_lshl_add_u64 v[140:141], s[16:17], 0, v[138:139]
	v_lshl_add_u64 v[138:139], s[10:11], 0, v[138:139]
	flat_load_ushort v159, v[140:141]
	flat_load_ushort v160, v[138:139]
	flat_load_ushort v161, v[136:137] offset:2112
	v_lshl_add_u64 v[138:139], v[136:137], 0, s[58:59]
	s_and_saveexec_b64 s[44:45], s[0:1]
	s_cbranch_execz .LBB0_526
	v_add_co_u32_e32 v136, vcc, 0xffffe900, v138
	s_nop 1
	v_addc_co_u32_e32 v137, vcc, -1, v139, vcc
	flat_load_ushort v158, v[136:137]
; __device__ __forceinline__ float bf2f(u16 h) { return __uint_as_float(((unsigned)h) << 16); }
; __device__ __forceinline__ void even_post_phase(const Params& p, int ei, char* smem) {
;     ...
;       for (int q8 = 0; q8 < 4; ++q8) {
;         const int m = mh, j = q8;
;         const int tk = m * 16 + fq * 4 + j;
;         const size_t row = (size_t)row0 + tk;
;         const int l = l0 + tk;
;         const bool hp = l > seg_lo, hn = (l + 1) < seg_hi;
;         bon[q8] = 0.5f * (bonf[row * 8 + wid] + bonb[row * 8 + wid]);
; #pragma unroll
;         for (int n = 0; n < 4; ++n) {
;           const int col = wid * 64 + n * 16 + fr;
;           ov[q8][n] = bf2f(of[row * 512 + col]) + bf2f(ob[row * 512 + col]);
;           const u16* pv = big + row * PSTR + 1024 + col;
;           const float c = bf2f(*pv);
;           const float pr = hp ? bf2f(*(pv - PSTR)) : 0.f;
;           const float nx = hn ? bf2f(*(pv + PSTR)) : 0.f;
;           vs[q8][n] = c + muv[n] * (0.5f * (pr + nx) - c);
;         }
;       }
.LBB0_526:
	s_or_b64 exec, exec, s[44:45]
	v_mov_b32_e32 v163, 0
	v_mov_b32_e32 v162, 0
	s_and_saveexec_b64 s[44:45], s[4:5]
	s_cbranch_execz .LBB0_528
	v_add_co_u32_e32 v136, vcc, 0x1000, v138
	s_nop 1
	v_addc_co_u32_e32 v137, vcc, 0, v139, vcc
	flat_load_ushort v162, v[136:137] offset:1792
.LBB0_528:
	s_or_b64 exec, exec, s[44:45]
	v_lshl_add_u64 v[134:135], v[134:135], 0, v[66:67]
	v_lshlrev_b64 v[134:135], 1, v[134:135]
	v_lshl_add_u64 v[136:137], s[16:17], 0, v[134:135]
	v_lshl_add_u64 v[134:135], s[10:11], 0, v[134:135]
	flat_load_ushort v164, v[136:137]
	flat_load_ushort v165, v[134:135]
	v_lshl_add_u64 v[134:135], v[66:67], 1, v[132:133]
	flat_load_ushort v166, v[134:135] offset:2048
	v_lshl_add_u64 v[132:133], v[134:135], 0, s[54:55]
	s_and_saveexec_b64 s[44:45], s[0:1]
	s_cbranch_execz .LBB0_530
	v_add_co_u32_e32 v134, vcc, 0xffffe900, v132
	s_nop 1
	v_addc_co_u32_e32 v135, vcc, -1, v133, vcc
	flat_load_ushort v163, v[134:135]
.LBB0_530:
	s_or_b64 exec, exec, s[44:45]
	v_mov_b32_e32 v168, 0
	v_mov_b32_e32 v167, 0
	s_and_saveexec_b64 s[0:1], s[4:5]
	s_cbranch_execz .LBB0_532
	v_add_co_u32_e32 v132, vcc, 0x1000, v132
	s_nop 1
	v_addc_co_u32_e32 v133, vcc, 0, v133, vcc
	flat_load_ushort v167, v[132:133] offset:1792
.LBB0_532:
	s_or_b64 exec, exec, s[0:1]
	v_mov_b32_e32 v135, s51
	v_or_b32_e32 v134, s50, v84
	v_lshl_add_u64 v[132:133], v[134:135], 3, v[72:73]
	v_lshlrev_b64 v[132:133], 2, v[132:133]
	v_lshlrev_b64 v[136:137], 9, v[134:135]
	v_lshl_add_u64 v[140:141], s[42:43], 0, v[132:133]
	v_lshl_add_u64 v[142:143], s[14:15], 0, v[132:133]
	v_mov_b64_e32 v[132:133], s[8:9]
	v_lshl_add_u64 v[138:139], v[136:137], 0, v[64:65]
	v_mad_i64_i32 v[132:133], s[0:1], v134, s19, v[132:133]
	v_lshlrev_b64 v[138:139], 1, v[138:139]
	v_lshl_add_u64 v[144:145], s[16:17], 0, v[138:139]
	v_lshl_add_u64 v[174:175], s[10:11], 0, v[138:139]
	v_lshl_add_u64 v[138:139], v[64:65], 1, v[132:133]
	flat_load_dword v169, v[140:141]
	flat_load_dword v172, v[142:143]
	flat_load_ushort v170, v[144:145]
	flat_load_ushort v171, v[174:175]
	flat_load_ushort v173, v[138:139] offset:2048
	v_or_b32_e32 v108, s46, v84
	v_cmp_lt_i32_e64 s[0:1], s47, v108
	v_lshl_add_u64 v[140:141], v[138:139], 0, s[54:55]
	s_and_saveexec_b64 s[4:5], s[0:1]
	s_cbranch_execz .LBB0_534
	v_add_co_u32_e32 v142, vcc, 0xffffe900, v140
	s_nop 1
	v_addc_co_u32_e32 v143, vcc, -1, v141, vcc
	flat_load_ushort v168, v[142:143]
.LBB0_534:
	s_or_b64 exec, exec, s[4:5]
	v_cmp_gt_i32_e64 s[4:5], s80, v108
	v_mov_b32_e32 v175, 0
	v_mov_b32_e32 v174, 0
	s_and_saveexec_b64 s[44:45], s[4:5]
	s_cbranch_execz .LBB0_536
	v_add_co_u32_e32 v140, vcc, 0x1000, v140
	s_nop 1
	v_addc_co_u32_e32 v141, vcc, 0, v141, vcc
	flat_load_ushort v174, v[140:141] offset:1792
.LBB0_536:
	s_or_b64 exec, exec, s[44:45]
	v_lshl_add_u64 v[140:141], v[136:137], 0, v[68:69]
	v_lshlrev_b64 v[140:141], 1, v[140:141]
	v_lshl_add_u64 v[142:143], s[16:17], 0, v[140:141]
	v_lshl_add_u64 v[140:141], s[10:11], 0, v[140:141]
	flat_load_ushort v176, v[142:143]
	flat_load_ushort v177, v[140:141]
	flat_load_ushort v178, v[138:139] offset:2080
	v_lshl_add_u64 v[140:141], v[138:139], 0, s[56:57]
	s_and_saveexec_b64 s[44:45], s[0:1]
	s_cbranch_execz .LBB0_538
	v_add_co_u32_e32 v142, vcc, 0xffffe900, v140
	s_nop 1
	v_addc_co_u32_e32 v143, vcc, -1, v141, vcc
	flat_load_ushort v175, v[142:143]
.LBB0_538:
	s_or_b64 exec, exec, s[44:45]
	v_mov_b32_e32 v180, 0
	v_mov_b32_e32 v179, 0
	s_and_saveexec_b64 s[44:45], s[4:5]
	s_cbranch_execz .LBB0_540
	v_add_co_u32_e32 v140, vcc, 0x1000, v140
	s_nop 1
	v_addc_co_u32_e32 v141, vcc, 0, v141, vcc
	flat_load_ushort v179, v[140:141] offset:1792
.LBB0_540:
	s_or_b64 exec, exec, s[44:45]
	v_lshl_add_u64 v[140:141], v[136:137], 0, v[70:71]
	v_lshlrev_b64 v[140:141], 1, v[140:141]
	v_lshl_add_u64 v[142:143], s[16:17], 0, v[140:141]
	v_lshl_add_u64 v[140:141], s[10:11], 0, v[140:141]
	flat_load_ushort v181, v[142:143]
	flat_load_ushort v182, v[140:141]
	flat_load_ushort v183, v[138:139] offset:2112
	v_lshl_add_u64 v[140:141], v[138:139], 0, s[58:59]
	s_and_saveexec_b64 s[44:45], s[0:1]
	s_cbranch_execz .LBB0_542
	v_add_co_u32_e32 v138, vcc, 0xffffe900, v140
	s_nop 1
	v_addc_co_u32_e32 v139, vcc, -1, v141, vcc
	flat_load_ushort v180, v[138:139]
.LBB0_542:
	s_or_b64 exec, exec, s[44:45]
	v_mov_b32_e32 v185, 0
	v_mov_b32_e32 v184, 0
	s_and_saveexec_b64 s[44:45], s[4:5]
	s_cbranch_execz .LBB0_544
	v_add_co_u32_e32 v138, vcc, 0x1000, v140
	s_nop 1
	v_addc_co_u32_e32 v139, vcc, 0, v141, vcc
	flat_load_ushort v184, v[138:139] offset:1792
.LBB0_544:
	s_or_b64 exec, exec, s[44:45]
	v_lshl_add_u64 v[136:137], v[136:137], 0, v[66:67]
	v_lshlrev_b64 v[136:137], 1, v[136:137]
	v_lshl_add_u64 v[138:139], s[16:17], 0, v[136:137]
	v_lshl_add_u64 v[136:137], s[10:11], 0, v[136:137]
	flat_load_ushort v186, v[138:139]
	flat_load_ushort v187, v[136:137]
	v_lshl_add_u64 v[136:137], v[66:67], 1, v[132:133]
	flat_load_ushort v188, v[136:137] offset:2048
	v_lshl_add_u64 v[132:133], v[136:137], 0, s[54:55]
	s_and_saveexec_b64 s[44:45], s[0:1]
	s_cbranch_execz .LBB0_546
	v_add_co_u32_e32 v136, vcc, 0xffffe900, v132
	s_nop 1
	v_addc_co_u32_e32 v137, vcc, -1, v133, vcc
	flat_load_ushort v185, v[136:137]
; __device__ __forceinline__ float bf2f(u16 h) { return __uint_as_float(((unsigned)h) << 16); }
; __device__ __forceinline__ void even_post_phase(const Params& p, int ei, char* smem) {
;     ...
;       for (int q8 = 0; q8 < 4; ++q8) {
;         const int m = mh, j = q8;
;         const int tk = m * 16 + fq * 4 + j;
;         const size_t row = (size_t)row0 + tk;
;         const int l = l0 + tk;
;         const bool hp = l > seg_lo, hn = (l + 1) < seg_hi;
;         bon[q8] = 0.5f * (bonf[row * 8 + wid] + bonb[row * 8 + wid]);
; #pragma unroll
;         for (int n = 0; n < 4; ++n) {
;           const int col = wid * 64 + n * 16 + fr;
;           ov[q8][n] = bf2f(of[row * 512 + col]) + bf2f(ob[row * 512 + col]);
;           const u16* pv = big + row * PSTR + 1024 + col;
;           const float c = bf2f(*pv);
;           const float pr = hp ? bf2f(*(pv - PSTR)) : 0.f;
;           const float nx = hn ? bf2f(*(pv + PSTR)) : 0.f;
;           vs[q8][n] = c + muv[n] * (0.5f * (pr + nx) - c);
;         }
;       }
.LBB0_546:
	s_or_b64 exec, exec, s[44:45]
	v_mov_b32_e32 v190, 0
	v_mov_b32_e32 v189, 0
	s_and_saveexec_b64 s[0:1], s[4:5]
	s_cbranch_execz .LBB0_548
	v_add_co_u32_e32 v132, vcc, 0x1000, v132
	s_nop 1
	v_addc_co_u32_e32 v133, vcc, 0, v133, vcc
	flat_load_ushort v189, v[132:133] offset:1792
.LBB0_548:
	s_or_b64 exec, exec, s[0:1]
	v_mov_b32_e32 v137, s51
	v_or_b32_e32 v136, s50, v86
	v_lshl_add_u64 v[132:133], v[136:137], 3, v[72:73]
	v_lshlrev_b64 v[138:139], 9, v[136:137]
	v_lshlrev_b64 v[132:133], 2, v[132:133]
	v_lshl_add_u64 v[140:141], v[138:139], 0, v[64:65]
	v_lshl_add_u64 v[142:143], s[42:43], 0, v[132:133]
	v_lshl_add_u64 v[144:145], s[14:15], 0, v[132:133]
	v_mov_b64_e32 v[132:133], s[8:9]
	v_lshlrev_b64 v[140:141], 1, v[140:141]
	v_mad_i64_i32 v[132:133], s[0:1], v136, s19, v[132:133]
	v_lshl_add_u64 v[192:193], s[16:17], 0, v[140:141]
	v_lshl_add_u64 v[196:197], s[10:11], 0, v[140:141]
	v_lshl_add_u64 v[140:141], v[64:65], 1, v[132:133]
	flat_load_dword v191, v[142:143]
	flat_load_dword v194, v[144:145]
	s_nop 0
	flat_load_ushort v192, v[192:193]
	s_nop 0
	flat_load_ushort v193, v[196:197]
	flat_load_ushort v195, v[140:141] offset:2048
	v_or_b32_e32 v108, s46, v86
	v_cmp_lt_i32_e64 s[0:1], s47, v108
	v_lshl_add_u64 v[142:143], v[140:141], 0, s[54:55]
	s_and_saveexec_b64 s[4:5], s[0:1]
	s_cbranch_execz .LBB0_550
	v_add_co_u32_e32 v144, vcc, 0xffffe900, v142
	s_nop 1
	v_addc_co_u32_e32 v145, vcc, -1, v143, vcc
	flat_load_ushort v190, v[144:145]
.LBB0_550:
	s_or_b64 exec, exec, s[4:5]
	v_cmp_gt_i32_e64 s[4:5], s80, v108
	v_mov_b32_e32 v197, 0
	v_mov_b32_e32 v196, 0
	s_and_saveexec_b64 s[44:45], s[4:5]
	s_cbranch_execz .LBB0_552
	v_add_co_u32_e32 v142, vcc, 0x1000, v142
	s_nop 1
	v_addc_co_u32_e32 v143, vcc, 0, v143, vcc
	flat_load_ushort v196, v[142:143] offset:1792
.LBB0_552:
	s_or_b64 exec, exec, s[44:45]
	v_lshl_add_u64 v[142:143], v[138:139], 0, v[68:69]
	v_lshlrev_b64 v[142:143], 1, v[142:143]
	v_lshl_add_u64 v[144:145], s[16:17], 0, v[142:143]
	v_lshl_add_u64 v[142:143], s[10:11], 0, v[142:143]
	flat_load_ushort v198, v[144:145]
	flat_load_ushort v199, v[142:143]
	flat_load_ushort v200, v[140:141] offset:2080
	v_lshl_add_u64 v[142:143], v[140:141], 0, s[56:57]
	s_and_saveexec_b64 s[44:45], s[0:1]
	s_cbranch_execz .LBB0_554
	v_add_co_u32_e32 v144, vcc, 0xffffe900, v142
	s_nop 1
	v_addc_co_u32_e32 v145, vcc, -1, v143, vcc
	flat_load_ushort v197, v[144:145]
.LBB0_554:
	s_or_b64 exec, exec, s[44:45]
	v_mov_b32_e32 v225, 0
	v_mov_b32_e32 v201, 0
	s_and_saveexec_b64 s[44:45], s[4:5]
	s_cbranch_execz .LBB0_556
	v_add_co_u32_e32 v142, vcc, 0x1000, v142
	s_nop 1
	v_addc_co_u32_e32 v143, vcc, 0, v143, vcc
	flat_load_ushort v201, v[142:143] offset:1792
.LBB0_556:
	s_or_b64 exec, exec, s[44:45]
	v_lshl_add_u64 v[142:143], v[138:139], 0, v[70:71]
	v_lshlrev_b64 v[142:143], 1, v[142:143]
	v_lshl_add_u64 v[144:145], s[16:17], 0, v[142:143]
	v_lshl_add_u64 v[142:143], s[10:11], 0, v[142:143]
	flat_load_ushort v226, v[144:145]
	flat_load_ushort v227, v[142:143]
	flat_load_ushort v228, v[140:141] offset:2112
	v_lshl_add_u64 v[142:143], v[140:141], 0, s[58:59]
	s_and_saveexec_b64 s[44:45], s[0:1]
	s_cbranch_execz .LBB0_558
	v_add_co_u32_e32 v140, vcc, 0xffffe900, v142
	s_nop 1
	v_addc_co_u32_e32 v141, vcc, -1, v143, vcc
	flat_load_ushort v225, v[140:141]
.LBB0_558:
	s_or_b64 exec, exec, s[44:45]
	v_mov_b32_e32 v230, 0
	v_mov_b32_e32 v229, 0
	s_and_saveexec_b64 s[44:45], s[4:5]
	s_cbranch_execz .LBB0_560
	v_add_co_u32_e32 v140, vcc, 0x1000, v142
	s_nop 1
	v_addc_co_u32_e32 v141, vcc, 0, v143, vcc
	flat_load_ushort v229, v[140:141] offset:1792
.LBB0_560:
	s_or_b64 exec, exec, s[44:45]
	v_lshl_add_u64 v[138:139], v[138:139], 0, v[66:67]
	v_lshlrev_b64 v[138:139], 1, v[138:139]
	v_lshl_add_u64 v[140:141], s[16:17], 0, v[138:139]
	v_lshl_add_u64 v[138:139], s[10:11], 0, v[138:139]
	flat_load_ushort v231, v[140:141]
	flat_load_ushort v232, v[138:139]
	v_lshl_add_u64 v[138:139], v[66:67], 1, v[132:133]
	flat_load_ushort v233, v[138:139] offset:2048
	v_lshl_add_u64 v[132:133], v[138:139], 0, s[54:55]
	s_and_saveexec_b64 s[44:45], s[0:1]
	s_cbranch_execz .LBB0_562
	v_add_co_u32_e32 v138, vcc, 0xffffe900, v132
	s_nop 1
	v_addc_co_u32_e32 v139, vcc, -1, v133, vcc
	flat_load_ushort v230, v[138:139]
.LBB0_562:
	s_or_b64 exec, exec, s[44:45]
	v_mov_b32_e32 v235, 0
	v_mov_b32_e32 v234, 0
	s_and_saveexec_b64 s[0:1], s[4:5]
	s_cbranch_execz .LBB0_564
	v_add_co_u32_e32 v132, vcc, 0x1000, v132
	s_nop 1
	v_addc_co_u32_e32 v133, vcc, 0, v133, vcc
	flat_load_ushort v234, v[132:133] offset:1792

; __device__ __forceinline__ float bf2f(u16 h) { return __uint_as_float(((unsigned)h) << 16); }
; __device__ __forceinline__ void even_post_phase(const Params& p, int ei, char* smem) {
;     ...
;       for (int q8 = 0; q8 < 4; ++q8) {
;         const int m = mh, j = q8;
;         const int tk = m * 16 + fq * 4 + j;
;         const size_t row = (size_t)row0 + tk;
;         const int l = l0 + tk;
;         const bool hp = l > seg_lo, hn = (l + 1) < seg_hi;
;         bon[q8] = 0.5f * (bonf[row * 8 + wid] + bonb[row * 8 + wid]);
; #pragma unroll
;         for (int n = 0; n < 4; ++n) {
;           const int col = wid * 64 + n * 16 + fr;
;           ov[q8][n] = bf2f(of[row * 512 + col]) + bf2f(ob[row * 512 + col]);
;           const u16* pv = big + row * PSTR + 1024 + col;
;           const float c = bf2f(*pv);
;           const float pr = hp ? bf2f(*(pv - PSTR)) : 0.f;
;           const float nx = hn ? bf2f(*(pv + PSTR)) : 0.f;
;           vs[q8][n] = c + muv[n] * (0.5f * (pr + nx) - c);
;         }
;       }
;       __builtin_amdgcn_sched_barrier(0);
; #pragma unroll
;       for (int q8 = 0; q8 < 4; ++q8) {
;         const int m = mh, j = q8;
;         const size_t row = (size_t)row0 + m * 16 + fq * 4 + j;
;         float sm = ov[q8][0] + ov[q8][1] + ov[q8][2] + ov[q8][3];
;         sm = row_sum16(sm);
;         const float mean = sm * (1.f / 64.f);
;         float vsum = 0.f;
; #pragma unroll
;         for (int n = 0; n < 4; ++n) { float dlt = ov[q8][n] - mean; vsum += dlt * dlt; }
;         vsum = row_sum16(vsum);
;         const float rstd = rsqrtf(vsum * (1.f / 64.f) + 64e-5f);
.LBB0_566:
	s_or_b64 exec, exec, s[4:5]
	v_cmp_gt_i32_e64 s[4:5], s80, v108
	v_mov_b32_e32 v242, 0
	v_mov_b32_e32 v241, 0
	s_and_saveexec_b64 s[44:45], s[4:5]
	s_cbranch_execz .LBB0_568
	v_add_co_u32_e32 v144, vcc, 0x1000, v144
	s_nop 1
	v_addc_co_u32_e32 v145, vcc, 0, v145, vcc
	flat_load_ushort v241, v[144:145] offset:1792
.LBB0_568:
	s_or_b64 exec, exec, s[44:45]
	v_lshl_add_u64 v[144:145], v[140:141], 0, v[68:69]
	v_lshlrev_b64 v[144:145], 1, v[144:145]
	v_lshl_add_u64 v[244:245], s[16:17], 0, v[144:145]
	v_lshl_add_u64 v[144:145], s[10:11], 0, v[144:145]
	flat_load_ushort v243, v[244:245]
	flat_load_ushort v246, v[142:143] offset:2080
	s_nop 0
	flat_load_ushort v244, v[144:145]
	v_lshl_add_u64 v[144:145], v[142:143], 0, s[56:57]
	s_and_saveexec_b64 s[44:45], s[0:1]
	s_cbranch_execz .LBB0_570
	v_add_co_u32_e32 v248, vcc, 0xffffe900, v144
	s_nop 1
	v_addc_co_u32_e32 v249, vcc, -1, v145, vcc
	flat_load_ushort v242, v[248:249]
.LBB0_570:
	s_or_b64 exec, exec, s[44:45]
	v_mov_b32_e32 v248, 0
	v_mov_b32_e32 v247, 0
	s_and_saveexec_b64 s[44:45], s[4:5]
	s_cbranch_execz .LBB0_572
	v_add_co_u32_e32 v144, vcc, 0x1000, v144
	s_nop 1
	v_addc_co_u32_e32 v145, vcc, 0, v145, vcc
	flat_load_ushort v247, v[144:145] offset:1792
.LBB0_572:
	s_or_b64 exec, exec, s[44:45]
	v_lshl_add_u64 v[144:145], v[140:141], 0, v[70:71]
	v_lshlrev_b64 v[144:145], 1, v[144:145]
	v_lshl_add_u64 v[250:251], s[16:17], 0, v[144:145]
	v_lshl_add_u64 v[144:145], s[10:11], 0, v[144:145]
	flat_load_ushort v249, v[250:251]
	s_nop 0
	flat_load_ushort v250, v[144:145]
	v_lshl_add_u64 v[144:145], v[142:143], 0, s[58:59]
	flat_load_ushort v142, v[142:143] offset:2112
	s_and_saveexec_b64 s[44:45], s[0:1]
	s_cbranch_execz .LBB0_574
	v_add_co_u32_e32 v252, vcc, 0xffffe900, v144
	s_nop 1
	v_addc_co_u32_e32 v253, vcc, -1, v145, vcc
	flat_load_ushort v248, v[252:253]
.LBB0_574:
	s_or_b64 exec, exec, s[44:45]
	v_mov_b32_e32 v245, 0
	v_mov_b32_e32 v143, 0
	s_and_saveexec_b64 s[44:45], s[4:5]
	s_cbranch_execz .LBB0_576
	v_add_co_u32_e32 v144, vcc, 0x1000, v144
	s_nop 1
	v_addc_co_u32_e32 v145, vcc, 0, v145, vcc
	flat_load_ushort v143, v[144:145] offset:1792
.LBB0_576:
	s_or_b64 exec, exec, s[44:45]
	v_lshl_add_u64 v[140:141], v[140:141], 0, v[66:67]
	v_lshlrev_b64 v[144:145], 1, v[140:141]
	v_lshl_add_u64 v[140:141], s[16:17], 0, v[144:145]
	v_lshl_add_u64 v[144:145], s[10:11], 0, v[144:145]
	flat_load_ushort v140, v[140:141]
	s_nop 0
	flat_load_ushort v141, v[144:145]
	v_lshl_add_u64 v[144:145], v[66:67], 1, v[132:133]
	v_lshl_add_u64 v[132:133], v[144:145], 0, s[54:55]
	flat_load_ushort v144, v[144:145] offset:2048
	s_and_saveexec_b64 s[44:45], s[0:1]
	s_cbranch_execz .LBB0_578
	v_add_co_u32_e32 v252, vcc, 0xffffe900, v132
	s_nop 1
	v_addc_co_u32_e32 v253, vcc, -1, v133, vcc
	flat_load_ushort v245, v[252:253]
.LBB0_578:
	s_or_b64 exec, exec, s[44:45]
	v_mov_b32_e32 v108, 0
	v_mov_b32_e32 v251, 0
	s_and_saveexec_b64 s[0:1], s[4:5]
	s_cbranch_execz .LBB0_580
	v_add_co_u32_e32 v132, vcc, 0x1000, v132
	s_nop 1
	v_addc_co_u32_e32 v133, vcc, 0, v133, vcc
	flat_load_ushort v251, v[132:133] offset:1792
.LBB0_580:
	s_or_b64 exec, exec, s[0:1]
	s_waitcnt vmcnt(0) lgkmcnt(0)
	v_lshlrev_b32_e32 v151, 16, v151
	v_lshlrev_b32_e32 v153, 16, v153
	v_lshlrev_b32_e32 v152, 16, v152
	v_lshlrev_b32_e32 v157, 16, v157
	v_lshlrev_b32_e32 v158, 16, v158
	v_lshlrev_b32_e32 v162, 16, v162
	v_lshlrev_b32_e32 v163, 16, v163
	v_lshlrev_b32_e32 v167, 16, v167
	v_lshlrev_b32_e32 v168, 16, v168
	v_lshlrev_b32_e32 v174, 16, v174
	v_lshlrev_b32_e32 v175, 16, v175
	v_lshlrev_b32_e32 v179, 16, v179
	v_lshlrev_b32_e32 v180, 16, v180
	v_lshlrev_b32_e32 v184, 16, v184
	v_lshlrev_b32_e32 v185, 16, v185
	v_lshlrev_b32_e32 v189, 16, v189
	v_lshlrev_b32_e32 v190, 16, v190
	v_lshlrev_b32_e32 v196, 16, v196
	v_lshlrev_b32_e32 v197, 16, v197
	v_lshlrev_b32_e32 v201, 16, v201
	v_lshlrev_b32_e32 v225, 16, v225
	v_lshlrev_b32_e32 v229, 16, v229
	v_lshlrev_b32_e32 v230, 16, v230
	v_lshlrev_b32_e32 v234, 16, v234
	v_lshlrev_b32_e32 v235, 16, v235
	v_lshlrev_b32_e32 v241, 16, v241
	v_lshlrev_b32_e32 v242, 16, v242
	v_lshlrev_b32_e32 v247, 16, v247
	v_lshlrev_b32_e32 v248, 16, v248
	v_lshlrev_b32_e32 v143, 16, v143
	v_lshlrev_b32_e32 v245, 16, v245
	v_lshlrev_b32_e32 v251, 16, v251
	v_lshlrev_b32_e32 v252, 16, v142
	v_add_f32_e32 v132, v248, v143
	v_fma_f32 v132, v132, 0.5, -v252
	v_fmac_f32_e32 v252, v95, v132
	v_lshlrev_b32_e32 v132, 16, v140
	v_lshlrev_b32_e32 v133, 16, v141
	v_add_f32_e32 v140, v132, v133
	v_lshlrev_b32_e32 v246, 16, v246
	v_add_f32_e32 v132, v242, v247
	v_fma_f32 v132, v132, 0.5, -v246
	v_fmac_f32_e32 v246, v93, v132
	v_lshlrev_b32_e32 v132, 16, v249
	v_lshlrev_b32_e32 v133, 16, v250
	v_add_f32_e32 v141, v132, v133
	v_lshlrev_b32_e32 v240, 16, v240
	v_add_f32_e32 v132, v235, v241
	v_fma_f32 v132, v132, 0.5, -v240
	v_fmac_f32_e32 v240, v91, v132
	v_lshlrev_b32_e32 v132, 16, v243
	v_lshlrev_b32_e32 v133, 16, v244
	v_add_f32_e32 v143, v132, v133
	v_lshlrev_b32_e32 v233, 16, v233
	v_add_f32_e32 v132, v230, v234
	v_fma_f32 v132, v132, 0.5, -v233
	v_fmac_f32_e32 v233, v121, v132
	v_add_f32_e32 v132, v236, v237
	v_mul_f32_e32 v230, 0.5, v132
	v_lshlrev_b32_e32 v132, 16, v238
	v_lshlrev_b32_e32 v133, 16, v239
	v_add_f32_e32 v142, v132, v133
	v_lshlrev_b32_e32 v228, 16, v228
	v_add_f32_e32 v132, v225, v229
	v_fma_f32 v132, v132, 0.5, -v228
	v_fmac_f32_e32 v228, v95, v132
	v_lshlrev_b32_e32 v132, 16, v231
	v_lshlrev_b32_e32 v133, 16, v232
	v_lshlrev_b32_e32 v248, 16, v144
	v_add_f32_e32 v144, v132, v133
	v_lshlrev_b32_e32 v200, 16, v200
	v_add_f32_e32 v132, v197, v201
	v_fma_f32 v132, v132, 0.5, -v200
	v_fmac_f32_e32 v200, v93, v132
; __device__ __forceinline__ float bf2f(u16 h) { return __uint_as_float(((unsigned)h) << 16); }
; __device__ __forceinline__ void even_post_phase(const Params& p, int ei, char* smem) {
;     ...
;           ov[q8][n] = bf2f(of[row * 512 + col]) + bf2f(ob[row * 512 + col]);
;           const u16* pv = big + row * PSTR + 1024 + col;
;           const float c = bf2f(*pv);
;           const float pr = hp ? bf2f(*(pv - PSTR)) : 0.f;
;           const float nx = hn ? bf2f(*(pv + PSTR)) : 0.f;
;           vs[q8][n] = c + muv[n] * (0.5f * (pr + nx) - c);
;         }
;       }
;       __builtin_amdgcn_sched_barrier(0);
; #pragma unroll
;       for (int q8 = 0; q8 < 4; ++q8) {
;         const int m = mh, j = q8;
;         const size_t row = (size_t)row0 + m * 16 + fq * 4 + j;
;         float sm = ov[q8][0] + ov[q8][1] + ov[q8][2] + ov[q8][3];
;         sm = row_sum16(sm);
;         const float mean = sm * (1.f / 64.f);
;         float vsum = 0.f;
; #pragma unroll
;         for (int n = 0; n < 4; ++n) { float dlt = ov[q8][n] - mean; vsum += dlt * dlt; }
;         vsum = row_sum16(vsum);
;         const float rstd = rsqrtf(vsum * (1.f / 64.f) + 64e-5f);
	v_lshlrev_b32_e32 v132, 16, v226
	v_lshlrev_b32_e32 v133, 16, v227
	v_add_f32_e32 v145, v132, v133
	v_lshlrev_b32_e32 v197, 16, v195
	v_add_f32_e32 v132, v190, v196
	v_fma_f32 v132, v132, 0.5, -v197
	v_fmac_f32_e32 v197, v91, v132
	v_lshlrev_b32_e32 v132, 16, v198
	v_lshlrev_b32_e32 v133, 16, v199
	v_add_f32_e32 v195, v132, v133
	v_lshlrev_b32_e32 v188, 16, v188
	v_add_f32_e32 v132, v185, v189
	v_fma_f32 v132, v132, 0.5, -v188
	v_fmac_f32_e32 v188, v121, v132
	v_add_f32_e32 v132, v191, v194
	v_mul_f32_e32 v185, 0.5, v132
	v_lshlrev_b32_e32 v132, 16, v192
	v_lshlrev_b32_e32 v133, 16, v193
	v_add_f32_e32 v194, v132, v133
	v_lshlrev_b32_e32 v183, 16, v183
	v_add_f32_e32 v132, v180, v184
	v_fma_f32 v132, v132, 0.5, -v183
	v_fmac_f32_e32 v183, v95, v132
	v_lshlrev_b32_e32 v132, 16, v186
	v_lshlrev_b32_e32 v133, 16, v187
	v_add_f32_e32 v132, v132, v133
	v_lshlrev_b32_e32 v178, 16, v178
	v_add_f32_e32 v133, v175, v179
	v_fma_f32 v133, v133, 0.5, -v178
	v_fmac_f32_e32 v178, v93, v133
	v_lshlrev_b32_e32 v133, 16, v181
	v_lshlrev_b32_e32 v175, 16, v182
	v_add_f32_e32 v133, v133, v175
	v_lshlrev_b32_e32 v175, 16, v173
	v_add_f32_e32 v168, v168, v174
	v_lshlrev_b32_e32 v166, 16, v166
	v_add_f32_e32 v163, v163, v167
	v_fma_f32 v168, v168, 0.5, -v175
	v_fma_f32 v163, v163, 0.5, -v166
	v_fmac_f32_e32 v175, v91, v168
	v_lshlrev_b32_e32 v168, 16, v176
	v_lshlrev_b32_e32 v173, 16, v177
	v_fmac_f32_e32 v166, v121, v163
	v_add_f32_e32 v163, v169, v172
	v_add_f32_e32 v173, v168, v173
	v_mul_f32_e32 v167, 0.5, v163
	v_lshlrev_b32_e32 v163, 16, v170
	v_lshlrev_b32_e32 v168, 16, v171
	v_add_f32_e32 v172, v163, v168
	v_lshlrev_b32_e32 v168, 16, v161
	v_add_f32_e32 v158, v158, v162
	v_lshlrev_b32_e32 v161, 16, v165
	v_lshlrev_b32_e32 v165, 16, v150
	v_add_f32_e32 v150, v151, v153
	v_fma_f32 v158, v158, 0.5, -v168
	v_fma_f32 v150, v150, 0.5, -v165
	v_add_f32_e32 v146, v146, v149
	v_fmac_f32_e32 v168, v95, v158
	v_lshlrev_b32_e32 v158, 16, v164
	v_lshlrev_b32_e32 v164, 16, v156
	v_add_f32_e32 v152, v152, v157
	v_fmac_f32_e32 v165, v91, v150
	v_lshlrev_b32_e32 v150, 16, v154
	v_lshlrev_b32_e32 v151, 16, v155
	v_mul_f32_e32 v169, 0.5, v146
	v_lshlrev_b32_e32 v146, 16, v147
	v_lshlrev_b32_e32 v147, 16, v148
	v_fma_f32 v152, v152, 0.5, -v164
	v_add_f32_e32 v151, v150, v151
	v_add_f32_e32 v150, v146, v147
	v_add_f32_e32 v146, v245, v251
	v_fmac_f32_e32 v164, v93, v152
	v_lshlrev_b32_e32 v152, 16, v159
	v_lshlrev_b32_e32 v156, 16, v160
	v_fma_f32 v146, v146, 0.5, -v248
	v_add_f32_e32 v158, v158, v161
	v_add_f32_e32 v159, v152, v156
	v_fmac_f32_e32 v248, v121, v146
	v_add_f32_e32 v146, v150, v151
	v_add_f32_e32 v156, v172, v173
	v_add_f32_e32 v146, v146, v159
	v_add_f32_e32 v156, v156, v133
	v_add_f32_e32 v146, v146, v158
	v_add_f32_e32 v156, v156, v132
	s_mov_b32 s0, 0x3a27c5ac
	v_add_f32_dpp v146, v146, v146 row_ror:8 row_mask:0xf bank_mask:0xf bound_ctrl:1
	v_add_f32_dpp v156, v156, v156 row_ror:8 row_mask:0xf bank_mask:0xf bound_ctrl:1
	v_lshlrev_b64 v[130:131], 11, v[130:131]
	v_add_f32_dpp v146, v146, v146 row_ror:4 row_mask:0xf bank_mask:0xf bound_ctrl:1
	v_add_f32_dpp v156, v156, v156 row_ror:4 row_mask:0xf bank_mask:0xf bound_ctrl:1
	v_lshl_add_u64 v[154:155], s[86:87], 0, v[130:131]
	v_add_f32_dpp v146, v146, v146 row_ror:2 row_mask:0xf bank_mask:0xf bound_ctrl:1
	v_add_f32_dpp v156, v156, v156 row_ror:2 row_mask:0xf bank_mask:0xf bound_ctrl:1
	v_lshlrev_b64 v[130:131], 1, v[64:65]
	v_add_f32_dpp v146, v146, v146 row_ror:1 row_mask:0xf bank_mask:0xf bound_ctrl:1
	v_add_f32_dpp v156, v156, v156 row_ror:1 row_mask:0xf bank_mask:0xf bound_ctrl:1
	v_mul_f32_e32 v146, 0x3c800000, v146
	v_mul_f32_e32 v156, 0x3c800000, v156
	v_pk_add_f32 v[148:149], v[150:151], v[146:147] op_sel_hi:[1,0] neg_lo:[0,1] neg_hi:[0,1]
	v_pk_add_f32 v[146:147], v[158:159], v[146:147] op_sel_hi:[1,0] neg_lo:[0,1] neg_hi:[0,1]
	v_pk_add_f32 v[158:159], v[172:173], v[156:157] op_sel_hi:[1,0] neg_lo:[0,1] neg_hi:[0,1]
	v_pk_mul_f32 v[150:151], v[148:149], v[148:149]
	v_pk_mul_f32 v[160:161], v[158:159], v[158:159]
	v_pk_add_f32 v[156:157], v[132:133], v[156:157] op_sel_hi:[1,0] neg_lo:[0,1] neg_hi:[0,1]
	v_pk_mul_f32 v[152:153], v[146:147], v[146:147]
	v_pk_mul_f32 v[132:133], v[156:157], v[156:157]
	v_mov_b32_e32 v162, v160
	v_mov_b32_e32 v163, v150
	v_mov_b32_e32 v150, v161
	v_pk_add_f32 v[150:151], v[162:163], v[150:151]
	v_mov_b32_e32 v160, v133
	v_mov_b32_e32 v161, v153
	v_pk_add_f32 v[150:151], v[160:161], v[150:151]
	v_mov_b32_e32 v133, v152
	v_pk_add_f32 v[132:133], v[132:133], v[150:151]
	v_lshl_add_u64 v[160:161], v[154:155], 0, v[130:131]
	v_lshlrev_b64 v[134:135], 11, v[134:135]
	v_mov_b32_dpp v151, v133 row_ror:8 row_mask:0xf bank_mask:0xf bound_ctrl:1
	v_mov_b32_dpp v150, v132 row_ror:8 row_mask:0xf bank_mask:0xf bound_ctrl:1
	v_pk_add_f32 v[132:133], v[132:133], v[150:151]
	v_lshl_add_u64 v[134:135], s[86:87], 0, v[134:135]
	s_nop 0
	v_mov_b32_dpp v151, v133 row_ror:4 row_mask:0xf bank_mask:0xf bound_ctrl:1
	v_mov_b32_dpp v150, v132 row_ror:4 row_mask:0xf bank_mask:0xf bound_ctrl:1
	v_pk_add_f32 v[132:133], v[132:133], v[150:151]
	s_nop 1
	v_mov_b32_dpp v151, v133 row_ror:2 row_mask:0xf bank_mask:0xf bound_ctrl:1
	v_mov_b32_dpp v150, v132 row_ror:2 row_mask:0xf bank_mask:0xf bound_ctrl:1
	v_pk_add_f32 v[132:133], v[132:133], v[150:151]
	s_nop 1
	v_mov_b32_dpp v151, v133 row_ror:1 row_mask:0xf bank_mask:0xf bound_ctrl:1
	v_mov_b32_dpp v150, v132 row_ror:1 row_mask:0xf bank_mask:0xf bound_ctrl:1
	v_pk_add_f32 v[132:133], v[132:133], v[150:151]
	v_mov_b64_e32 v[150:151], s[0:1]
	v_pk_fma_f32 v[152:153], v[132:133], s[22:23], v[150:151] op_sel_hi:[1,0,0]
	s_nop 0
; __device__ __forceinline__ u16 f2bf(float f) { return (u16)(pack2(f, 0.f) & 0xffffu); }
; __device__ __forceinline__ void even_post_phase(const Params& p, int ei, char* smem) {
;     ...
;       for (int q8 = 0; q8 < 4; ++q8) {
;         const int m = mh, j = q8;
;         const size_t row = (size_t)row0 + m * 16 + fq * 4 + j;
;         float sm = ov[q8][0] + ov[q8][1] + ov[q8][2] + ov[q8][3];
;         sm = row_sum16(sm);
;         const float mean = sm * (1.f / 64.f);
;         float vsum = 0.f;
; #pragma unroll
;         for (int n = 0; n < 4; ++n) { float dlt = ov[q8][n] - mean; vsum += dlt * dlt; }
;         vsum = row_sum16(vsum);
;         const float rstd = rsqrtf(vsum * (1.f / 64.f) + 64e-5f);
; #pragma unroll
;         for (int n = 0; n < 4; ++n) {
;           const int col = wid * 64 + n * 16 + fr;
;           const float on = (ov[q8][n] - mean) * rstd * lnw[n] + lnb[n];
;           act[row * D + col] = f2bf((on + bon[q8] * vs[q8][n]) * acc[m][n][j]);
;         }
;       }
	v_mul_f32_e32 v132, 0x4b800000, v153
	v_cmp_gt_f32_e32 vcc, s39, v153
	s_nop 1
	v_cndmask_b32_e32 v132, v153, v132, vcc
	v_rsq_f32_e32 v153, v132
	v_lshlrev_b64 v[132:133], 1, v[66:67]
	v_lshl_add_u64 v[154:155], v[154:155], 0, v[132:133]
	v_mul_f32_e32 v162, 0x45800000, v153
	v_cndmask_b32_e32 v153, v153, v162, vcc
	v_mul_f32_e32 v148, v148, v153
	v_fma_f32 v148, v97, v148, v75
	v_fmac_f32_e32 v148, v169, v165
	v_mul_f32_e32 v48, v48, v148
	v_cvt_pk_bf16_f32 v48, v48, s0
	flat_store_short v[160:161], v48
	v_mul_f32_e32 v48, v149, v153
	v_fma_f32 v48, v99, v48, v85
	v_fmac_f32_e32 v48, v169, v164
	v_mul_f32_e32 v48, v60, v48
	v_cvt_pk_bf16_f32 v48, v48, s0
	flat_store_short v[160:161], v48 offset:32
	v_mul_f32_e32 v48, v147, v153
	v_fma_f32 v48, v101, v48, v87
	v_fmac_f32_e32 v48, v169, v168
	v_mul_f32_e32 v48, v56, v48
	v_cvt_pk_bf16_f32 v48, v48, s0
	v_mul_f32_e32 v56, 0x4b800000, v152
	v_cmp_gt_f32_e32 vcc, s39, v152
	flat_store_short v[160:161], v48 offset:64
	v_mul_f32_e32 v48, v146, v153
	v_cndmask_b32_e32 v56, v152, v56, vcc
	v_fma_f32 v48, v103, v48, v89
	v_rsq_f32_e32 v56, v56
	v_fmac_f32_e32 v48, v169, v166
	v_mul_f32_e32 v48, v52, v48
	v_cvt_pk_bf16_f32 v48, v48, s0
	flat_store_short v[154:155], v48
	v_mul_f32_e32 v48, 0x45800000, v56
	v_cndmask_b32_e32 v52, v56, v48, vcc
	v_mul_f32_e32 v48, v158, v52
	v_fma_f32 v48, v97, v48, v75
	v_fmac_f32_e32 v48, v167, v175
	v_mul_f32_e32 v48, v49, v48
	v_cvt_pk_bf16_f32 v56, v48, s0
	v_lshl_add_u64 v[48:49], v[134:135], 0, v[130:131]
	flat_store_short v[48:49], v56
	v_mul_f32_e32 v56, v159, v52
	v_fma_f32 v56, v99, v56, v85
	v_fmac_f32_e32 v56, v167, v178
	v_mul_f32_e32 v56, v61, v56
	v_cvt_pk_bf16_f32 v56, v56, s0
	flat_store_short v[48:49], v56 offset:32
	v_mul_f32_e32 v56, v157, v52
	v_fma_f32 v56, v101, v56, v87
	v_fmac_f32_e32 v56, v167, v183
	v_mul_f32_e32 v56, v57, v56
	v_cvt_pk_bf16_f32 v56, v56, s0
	flat_store_short v[48:49], v56 offset:64
	v_mul_f32_e32 v48, v156, v52
	v_fma_f32 v48, v103, v48, v89
	v_fmac_f32_e32 v48, v167, v188
	v_mul_f32_e32 v48, v53, v48
	v_cvt_pk_bf16_f32 v52, v48, s0
	v_lshl_add_u64 v[48:49], v[134:135], 0, v[132:133]
	flat_store_short v[48:49], v52
	v_add_f32_e32 v48, v194, v195
	v_lshlrev_b64 v[134:135], 11, v[136:137]
	v_add_f32_e32 v136, v142, v143
	v_add_f32_e32 v48, v48, v145
	v_add_f32_e32 v136, v136, v141
	v_add_f32_e32 v48, v48, v144
	v_add_f32_e32 v136, v136, v140
	s_nop 0
	v_add_f32_dpp v48, v48, v48 row_ror:8 row_mask:0xf bank_mask:0xf bound_ctrl:1
	v_add_f32_dpp v136, v136, v136 row_ror:8 row_mask:0xf bank_mask:0xf bound_ctrl:1
	s_nop 0
	v_add_f32_dpp v48, v48, v48 row_ror:4 row_mask:0xf bank_mask:0xf bound_ctrl:1
	v_add_f32_dpp v136, v136, v136 row_ror:4 row_mask:0xf bank_mask:0xf bound_ctrl:1
	s_nop 0
	v_add_f32_dpp v48, v48, v48 row_ror:2 row_mask:0xf bank_mask:0xf bound_ctrl:1
	v_add_f32_dpp v136, v136, v136 row_ror:2 row_mask:0xf bank_mask:0xf bound_ctrl:1
	s_nop 0
	v_add_f32_dpp v48, v48, v48 row_ror:1 row_mask:0xf bank_mask:0xf bound_ctrl:1
	v_add_f32_dpp v136, v136, v136 row_ror:1 row_mask:0xf bank_mask:0xf bound_ctrl:1
	v_mul_f32_e32 v48, 0x3c800000, v48
	v_mul_f32_e32 v136, 0x3c800000, v136
	v_pk_add_f32 v[52:53], v[194:195], v[48:49] op_sel_hi:[1,0] neg_lo:[0,1] neg_hi:[0,1]
	v_pk_add_f32 v[142:143], v[142:143], v[136:137] op_sel_hi:[1,0] neg_lo:[0,1] neg_hi:[0,1]
	v_pk_mul_f32 v[56:57], v[52:53], v[52:53]
	v_pk_add_f32 v[48:49], v[144:145], v[48:49] op_sel_hi:[1,0] neg_lo:[0,1] neg_hi:[0,1]
	v_pk_mul_f32 v[144:145], v[142:143], v[142:143]
	v_pk_add_f32 v[136:137], v[140:141], v[136:137] op_sel_hi:[1,0] neg_lo:[0,1] neg_hi:[0,1]
	v_pk_mul_f32 v[60:61], v[48:49], v[48:49]
	v_pk_mul_f32 v[140:141], v[136:137], v[136:137]
	v_mov_b32_e32 v146, v144
	v_mov_b32_e32 v147, v56
	v_mov_b32_e32 v56, v145
	v_pk_add_f32 v[56:57], v[146:147], v[56:57]
	v_mov_b32_e32 v144, v141
	v_mov_b32_e32 v145, v61
	v_pk_add_f32 v[56:57], v[144:145], v[56:57]
	v_mov_b32_e32 v141, v60
	v_pk_add_f32 v[56:57], v[140:141], v[56:57]
	s_nop 1
	v_mov_b32_dpp v61, v57 row_ror:8 row_mask:0xf bank_mask:0xf bound_ctrl:1
	v_mov_b32_dpp v60, v56 row_ror:8 row_mask:0xf bank_mask:0xf bound_ctrl:1
	v_pk_add_f32 v[56:57], v[56:57], v[60:61]
	s_nop 1
	v_mov_b32_dpp v61, v57 row_ror:4 row_mask:0xf bank_mask:0xf bound_ctrl:1
	v_mov_b32_dpp v60, v56 row_ror:4 row_mask:0xf bank_mask:0xf bound_ctrl:1
	v_pk_add_f32 v[56:57], v[56:57], v[60:61]
	s_nop 1
	v_mov_b32_dpp v61, v57 row_ror:2 row_mask:0xf bank_mask:0xf bound_ctrl:1
	v_mov_b32_dpp v60, v56 row_ror:2 row_mask:0xf bank_mask:0xf bound_ctrl:1
	v_pk_add_f32 v[56:57], v[56:57], v[60:61]
	s_nop 1
	v_mov_b32_dpp v61, v57 row_ror:1 row_mask:0xf bank_mask:0xf bound_ctrl:1
	v_mov_b32_dpp v60, v56 row_ror:1 row_mask:0xf bank_mask:0xf bound_ctrl:1
	v_pk_add_f32 v[56:57], v[56:57], v[60:61]
	s_nop 0
	v_pk_fma_f32 v[56:57], v[56:57], s[22:23], v[150:151] op_sel_hi:[1,0,0]
	s_nop 0
	v_mul_f32_e32 v60, 0x4b800000, v57
	v_cmp_gt_f32_e32 vcc, s39, v57
	s_nop 1
	v_cndmask_b32_e32 v57, v57, v60, vcc
	v_rsq_f32_e32 v57, v57
	v_lshl_add_u64 v[60:61], s[86:87], 0, v[134:135]
	v_lshl_add_u64 v[134:135], v[60:61], 0, v[130:131]
	v_lshl_add_u64 v[60:61], v[60:61], 0, v[132:133]
	v_mul_f32_e32 v140, 0x45800000, v57
	v_cndmask_b32_e32 v57, v57, v140, vcc
	v_mul_f32_e32 v49, v49, v57
	v_mul_f32_e32 v52, v52, v57
	v_fma_f32 v49, v101, v49, v87
	v_fma_f32 v52, v97, v52, v75
	v_fmac_f32_e32 v49, v185, v228
	v_fmac_f32_e32 v52, v185, v197
	v_mul_f32_e32 v49, v58, v49
	v_mul_f32_e32 v50, v50, v52
	v_cvt_pk_bf16_f32 v49, v49, s0
	v_cvt_pk_bf16_f32 v50, v50, s0
	flat_store_short v[134:135], v49 offset:64
	v_mul_f32_e32 v49, 0x4b800000, v56
; __device__ __forceinline__ u16 f2bf(float f) { return (u16)(pack2(f, 0.f) & 0xffffu); }
; __device__ __forceinline__ float bf2f(u16 h) { return __uint_as_float(((unsigned)h) << 16); }
; __device__ __forceinline__ void even_post_phase(const Params& p, int ei, char* smem) {
;     ...
;       for (int q8 = 0; q8 < 4; ++q8) {
;         const int m = mh, j = q8;
;         const int tk = m * 16 + fq * 4 + j;
;         const size_t row = (size_t)row0 + tk;
;         const int l = l0 + tk;
;         const bool hp = l > seg_lo, hn = (l + 1) < seg_hi;
;         bon[q8] = 0.5f * (bonf[row * 8 + wid] + bonb[row * 8 + wid]);
; #pragma unroll
;         for (int n = 0; n < 4; ++n) {
;           const int col = wid * 64 + n * 16 + fr;
;           ov[q8][n] = bf2f(of[row * 512 + col]) + bf2f(ob[row * 512 + col]);
;           const u16* pv = big + row * PSTR + 1024 + col;
;           const float c = bf2f(*pv);
;           const float pr = hp ? bf2f(*(pv - PSTR)) : 0.f;
;           const float nx = hn ? bf2f(*(pv + PSTR)) : 0.f;
;           vs[q8][n] = c + muv[n] * (0.5f * (pr + nx) - c);
;         }
;       }
;     ...
;       for (int q8 = 0; q8 < 4; ++q8) {
;         const int m = mh, j = q8;
;         const size_t row = (size_t)row0 + m * 16 + fq * 4 + j;
;         float sm = ov[q8][0] + ov[q8][1] + ov[q8][2] + ov[q8][3];
;         sm = row_sum16(sm);
;         const float mean = sm * (1.f / 64.f);
;         float vsum = 0.f;
; #pragma unroll
;         for (int n = 0; n < 4; ++n) { float dlt = ov[q8][n] - mean; vsum += dlt * dlt; }
;         vsum = row_sum16(vsum);
;         const float rstd = rsqrtf(vsum * (1.f / 64.f) + 64e-5f);
; #pragma unroll
;         for (int n = 0; n < 4; ++n) {
;           const int col = wid * 64 + n * 16 + fr;
;           const float on = (ov[q8][n] - mean) * rstd * lnw[n] + lnb[n];
;           act[row * D + col] = f2bf((on + bon[q8] * vs[q8][n]) * acc[m][n][j]);
;         }
;       }
	v_cmp_gt_f32_e32 vcc, s39, v56
	flat_store_short v[134:135], v50
	v_mul_f32_e32 v50, v53, v57
	v_mul_f32_e32 v48, v48, v57
	v_cndmask_b32_e32 v49, v56, v49, vcc
	v_fma_f32 v50, v99, v50, v85
	v_fma_f32 v48, v103, v48, v89
	v_rsq_f32_e32 v49, v49
	v_fmac_f32_e32 v50, v185, v200
	v_fmac_f32_e32 v48, v185, v233
	v_mul_f32_e32 v50, v62, v50
	v_mul_f32_e32 v48, v54, v48
	v_cvt_pk_bf16_f32 v50, v50, s0
	v_cvt_pk_bf16_f32 v48, v48, s0
	flat_store_short v[134:135], v50 offset:32
	flat_store_short v[60:61], v48
	v_mul_f32_e32 v48, 0x45800000, v49
	v_cndmask_b32_e32 v52, v49, v48, vcc
	v_mul_f32_e32 v50, v142, v52
	v_fma_f32 v50, v97, v50, v75
	v_lshlrev_b64 v[48:49], 11, v[138:139]
	v_fmac_f32_e32 v50, v230, v240
	v_lshl_add_u64 v[48:49], s[86:87], 0, v[48:49]
	v_mul_f32_e32 v50, v51, v50
	v_cvt_pk_bf16_f32 v53, v50, s0
	v_lshl_add_u64 v[50:51], v[48:49], 0, v[130:131]
	flat_store_short v[50:51], v53
	v_mul_f32_e32 v53, v143, v52
	v_fma_f32 v53, v99, v53, v85
	v_fmac_f32_e32 v53, v230, v246
	v_mul_f32_e32 v53, v63, v53
	v_cvt_pk_bf16_f32 v53, v53, s0
	flat_store_short v[50:51], v53 offset:32
	v_mul_f32_e32 v53, v137, v52
	v_fma_f32 v53, v101, v53, v87
	v_fmac_f32_e32 v53, v230, v252
	v_mul_f32_e32 v53, v59, v53
	v_cvt_pk_bf16_f32 v53, v53, s0
	flat_store_short v[50:51], v53 offset:64
	v_mul_f32_e32 v50, v136, v52
	v_fma_f32 v50, v103, v50, v89
	v_fmac_f32_e32 v50, v230, v248
	v_mul_f32_e32 v50, v55, v50
	v_cvt_pk_bf16_f32 v50, v50, s0
	v_lshl_add_u64 v[48:49], v[48:49], 0, v[132:133]
	flat_store_short v[48:49], v50
	v_mov_b32_e32 v49, s51
	v_or_b32_e32 v48, s50, v90
	v_lshl_add_u64 v[50:51], v[48:49], 3, v[72:73]
	v_lshlrev_b64 v[50:51], 2, v[50:51]
	v_lshlrev_b64 v[52:53], 9, v[48:49]
	v_lshl_add_u64 v[56:57], s[42:43], 0, v[50:51]
	v_lshl_add_u64 v[58:59], s[14:15], 0, v[50:51]
	v_mov_b64_e32 v[50:51], s[8:9]
	v_lshl_add_u64 v[54:55], v[52:53], 0, v[64:65]
	v_mad_i64_i32 v[50:51], s[0:1], v48, s19, v[50:51]
	v_lshlrev_b64 v[54:55], 1, v[54:55]
	v_lshl_add_u64 v[60:61], s[16:17], 0, v[54:55]
	v_lshl_add_u64 v[62:63], s[10:11], 0, v[54:55]
	v_lshl_add_u64 v[54:55], v[50:51], 0, v[130:131]
	flat_load_dword v134, v[56:57]
	flat_load_dword v137, v[58:59]
	flat_load_ushort v135, v[60:61]
	flat_load_ushort v136, v[62:63]
	flat_load_ushort v138, v[54:55] offset:2048
	v_or_b32_e32 v58, s46, v90
	v_cmp_lt_i32_e64 s[0:1], s47, v58
	v_lshl_add_u64 v[56:57], v[54:55], 0, s[54:55]
	s_and_saveexec_b64 s[4:5], s[0:1]
	s_cbranch_execz .LBB0_582
	v_add_co_u32_e32 v60, vcc, 0xffffe900, v56
	s_nop 1
	v_addc_co_u32_e32 v61, vcc, -1, v57, vcc
	flat_load_ushort v108, v[60:61]
.LBB0_582:
	s_or_b64 exec, exec, s[4:5]
	v_cmp_gt_i32_e64 s[4:5], s80, v58
	v_mov_b32_e32 v140, 0
	v_mov_b32_e32 v139, 0
	s_and_saveexec_b64 s[44:45], s[4:5]
	s_cbranch_execz .LBB0_584
	v_add_co_u32_e32 v56, vcc, 0x1000, v56
	s_nop 1
	v_addc_co_u32_e32 v57, vcc, 0, v57, vcc
	flat_load_ushort v139, v[56:57] offset:1792
.LBB0_584:
	s_or_b64 exec, exec, s[44:45]
	v_lshl_add_u64 v[56:57], v[52:53], 0, v[68:69]
	v_lshlrev_b64 v[56:57], 1, v[56:57]
	v_lshl_add_u64 v[58:59], s[16:17], 0, v[56:57]
	v_lshl_add_u64 v[56:57], s[10:11], 0, v[56:57]
	flat_load_ushort v141, v[58:59]
	flat_load_ushort v142, v[56:57]
	flat_load_ushort v143, v[54:55] offset:2080
	v_lshl_add_u64 v[56:57], v[54:55], 0, s[56:57]
	s_and_saveexec_b64 s[44:45], s[0:1]
	s_cbranch_execz .LBB0_586
	v_add_co_u32_e32 v58, vcc, 0xffffe900, v56
	s_nop 1
	v_addc_co_u32_e32 v59, vcc, -1, v57, vcc
	flat_load_ushort v140, v[58:59]
.LBB0_586:
	s_or_b64 exec, exec, s[44:45]
	v_mov_b32_e32 v145, 0
	v_mov_b32_e32 v144, 0
	s_and_saveexec_b64 s[44:45], s[4:5]
	s_cbranch_execz .LBB0_588
	v_add_co_u32_e32 v56, vcc, 0x1000, v56
	s_nop 1
	v_addc_co_u32_e32 v57, vcc, 0, v57, vcc
	flat_load_ushort v144, v[56:57] offset:1792
.LBB0_588:
	s_or_b64 exec, exec, s[44:45]
	v_lshl_add_u64 v[56:57], v[52:53], 0, v[70:71]
	v_lshlrev_b64 v[56:57], 1, v[56:57]
	v_lshl_add_u64 v[58:59], s[16:17], 0, v[56:57]
	v_lshl_add_u64 v[56:57], s[10:11], 0, v[56:57]
	flat_load_ushort v146, v[58:59]
	flat_load_ushort v147, v[56:57]
	flat_load_ushort v148, v[54:55] offset:2112
	v_lshl_add_u64 v[56:57], v[54:55], 0, s[58:59]
	s_and_saveexec_b64 s[44:45], s[0:1]
	s_cbranch_execz .LBB0_590
	v_add_co_u32_e32 v54, vcc, 0xffffe900, v56
	s_nop 1
	v_addc_co_u32_e32 v55, vcc, -1, v57, vcc
	flat_load_ushort v145, v[54:55]
.LBB0_590:
	s_or_b64 exec, exec, s[44:45]
	v_mov_b32_e32 v150, 0
	v_mov_b32_e32 v149, 0
	s_and_saveexec_b64 s[44:45], s[4:5]
	s_cbranch_execz .LBB0_592
	v_add_co_u32_e32 v54, vcc, 0x1000, v56
	s_nop 1
	v_addc_co_u32_e32 v55, vcc, 0, v57, vcc
	flat_load_ushort v149, v[54:55] offset:1792
.LBB0_592:
	s_or_b64 exec, exec, s[44:45]
	v_lshl_add_u64 v[52:53], v[52:53], 0, v[66:67]
	v_lshlrev_b64 v[52:53], 1, v[52:53]
	v_lshl_add_u64 v[54:55], s[16:17], 0, v[52:53]
	v_lshl_add_u64 v[52:53], s[10:11], 0, v[52:53]
	flat_load_ushort v151, v[54:55]
	flat_load_ushort v152, v[52:53]
	v_lshl_add_u64 v[52:53], v[66:67], 1, v[50:51]
	flat_load_ushort v153, v[52:53] offset:2048
	v_lshl_add_u64 v[50:51], v[52:53], 0, s[54:55]
	s_and_saveexec_b64 s[44:45], s[0:1]
	s_cbranch_execz .LBB0_594
	v_add_co_u32_e32 v52, vcc, 0xffffe900, v50
	s_nop 1
	v_addc_co_u32_e32 v53, vcc, -1, v51, vcc
	flat_load_ushort v150, v[52:53]
.LBB0_594:
	s_or_b64 exec, exec, s[44:45]
	v_mov_b32_e32 v155, 0
	v_mov_b32_e32 v154, 0
	s_and_saveexec_b64 s[0:1], s[4:5]
	s_cbranch_execz .LBB0_596
	v_add_co_u32_e32 v50, vcc, 0x1000, v50
	s_nop 1
	v_addc_co_u32_e32 v51, vcc, 0, v51, vcc
	flat_load_ushort v154, v[50:51] offset:1792
; __device__ __forceinline__ float bf2f(u16 h) { return __uint_as_float(((unsigned)h) << 16); }
; __device__ __forceinline__ void even_post_phase(const Params& p, int ei, char* smem) {
;     ...
;       for (int q8 = 0; q8 < 4; ++q8) {
;         const int m = mh, j = q8;
;         const int tk = m * 16 + fq * 4 + j;
;         const size_t row = (size_t)row0 + tk;
;         const int l = l0 + tk;
;         const bool hp = l > seg_lo, hn = (l + 1) < seg_hi;
;         bon[q8] = 0.5f * (bonf[row * 8 + wid] + bonb[row * 8 + wid]);
; #pragma unroll
;         for (int n = 0; n < 4; ++n) {
;           const int col = wid * 64 + n * 16 + fr;
;           ov[q8][n] = bf2f(of[row * 512 + col]) + bf2f(ob[row * 512 + col]);
;           const u16* pv = big + row * PSTR + 1024 + col;
;           const float c = bf2f(*pv);
;           const float pr = hp ? bf2f(*(pv - PSTR)) : 0.f;
;           const float nx = hn ? bf2f(*(pv + PSTR)) : 0.f;
;           vs[q8][n] = c + muv[n] * (0.5f * (pr + nx) - c);
;         }
;       }
.LBB0_596:
	s_or_b64 exec, exec, s[0:1]
	v_mov_b32_e32 v51, s51
	v_or_b32_e32 v50, s50, v92
	v_lshl_add_u64 v[52:53], v[50:51], 3, v[72:73]
	v_lshlrev_b64 v[54:55], 9, v[50:51]
	v_lshlrev_b64 v[52:53], 2, v[52:53]
	v_lshl_add_u64 v[56:57], v[54:55], 0, v[64:65]
	v_lshl_add_u64 v[58:59], s[42:43], 0, v[52:53]
	v_lshl_add_u64 v[60:61], s[14:15], 0, v[52:53]
	v_mov_b64_e32 v[52:53], s[8:9]
	v_lshlrev_b64 v[56:57], 1, v[56:57]
	v_mad_i64_i32 v[52:53], s[0:1], v50, s19, v[52:53]
	v_lshl_add_u64 v[160:161], s[10:11], 0, v[56:57]
	v_lshl_add_u64 v[62:63], s[16:17], 0, v[56:57]
	v_lshl_add_u64 v[56:57], v[64:65], 1, v[52:53]
	flat_load_dword v156, v[58:59]
	flat_load_dword v159, v[60:61]
	flat_load_ushort v157, v[62:63]
	flat_load_ushort v158, v[160:161]
	s_nop 0
	flat_load_ushort v160, v[56:57] offset:2048
	v_or_b32_e32 v60, s46, v92
	v_cmp_lt_i32_e64 s[0:1], s47, v60
	v_lshl_add_u64 v[58:59], v[56:57], 0, s[54:55]
	s_and_saveexec_b64 s[4:5], s[0:1]
	s_cbranch_execz .LBB0_598
	v_add_co_u32_e32 v62, vcc, 0xffffe900, v58
	s_nop 1
	v_addc_co_u32_e32 v63, vcc, -1, v59, vcc
	flat_load_ushort v155, v[62:63]
.LBB0_598:
	s_or_b64 exec, exec, s[4:5]
	v_cmp_gt_i32_e64 s[4:5], s80, v60
	v_mov_b32_e32 v162, 0
	v_mov_b32_e32 v161, 0
	s_and_saveexec_b64 s[44:45], s[4:5]
	s_cbranch_execz .LBB0_600
	v_add_co_u32_e32 v58, vcc, 0x1000, v58
	s_nop 1
	v_addc_co_u32_e32 v59, vcc, 0, v59, vcc
	flat_load_ushort v161, v[58:59] offset:1792
.LBB0_600:
	s_or_b64 exec, exec, s[44:45]
	v_lshl_add_u64 v[58:59], v[54:55], 0, v[68:69]
	v_lshlrev_b64 v[58:59], 1, v[58:59]
	v_lshl_add_u64 v[60:61], s[16:17], 0, v[58:59]
	v_lshl_add_u64 v[58:59], s[10:11], 0, v[58:59]
	flat_load_ushort v163, v[60:61]
	flat_load_ushort v164, v[58:59]
	flat_load_ushort v165, v[56:57] offset:2080
	v_lshl_add_u64 v[58:59], v[56:57], 0, s[56:57]
	s_and_saveexec_b64 s[44:45], s[0:1]
	s_cbranch_execz .LBB0_602
	v_add_co_u32_e32 v60, vcc, 0xffffe900, v58
	s_nop 1
	v_addc_co_u32_e32 v61, vcc, -1, v59, vcc
	flat_load_ushort v162, v[60:61]
.LBB0_602:
	s_or_b64 exec, exec, s[44:45]
	v_mov_b32_e32 v167, 0
	v_mov_b32_e32 v166, 0
	s_and_saveexec_b64 s[44:45], s[4:5]
	s_cbranch_execz .LBB0_604
	v_add_co_u32_e32 v58, vcc, 0x1000, v58
	s_nop 1
	v_addc_co_u32_e32 v59, vcc, 0, v59, vcc
	flat_load_ushort v166, v[58:59] offset:1792
.LBB0_604:
	s_or_b64 exec, exec, s[44:45]
	v_lshl_add_u64 v[58:59], v[54:55], 0, v[70:71]
	v_lshlrev_b64 v[58:59], 1, v[58:59]
	v_lshl_add_u64 v[60:61], s[16:17], 0, v[58:59]
	v_lshl_add_u64 v[58:59], s[10:11], 0, v[58:59]
	flat_load_ushort v168, v[60:61]
	flat_load_ushort v169, v[58:59]
	flat_load_ushort v170, v[56:57] offset:2112
	v_lshl_add_u64 v[58:59], v[56:57], 0, s[58:59]
	s_and_saveexec_b64 s[44:45], s[0:1]
	s_cbranch_execz .LBB0_606
	v_add_co_u32_e32 v56, vcc, 0xffffe900, v58
	s_nop 1
	v_addc_co_u32_e32 v57, vcc, -1, v59, vcc
	flat_load_ushort v167, v[56:57]
.LBB0_606:
	s_or_b64 exec, exec, s[44:45]
	v_mov_b32_e32 v172, 0
	v_mov_b32_e32 v171, 0
	s_and_saveexec_b64 s[44:45], s[4:5]
	s_cbranch_execz .LBB0_608
	v_add_co_u32_e32 v56, vcc, 0x1000, v58
	s_nop 1
	v_addc_co_u32_e32 v57, vcc, 0, v59, vcc
	flat_load_ushort v171, v[56:57] offset:1792
.LBB0_608:
	s_or_b64 exec, exec, s[44:45]
	v_lshl_add_u64 v[54:55], v[54:55], 0, v[66:67]
	v_lshlrev_b64 v[54:55], 1, v[54:55]
	v_lshl_add_u64 v[56:57], s[16:17], 0, v[54:55]
	v_lshl_add_u64 v[54:55], s[10:11], 0, v[54:55]
	flat_load_ushort v173, v[56:57]
	flat_load_ushort v174, v[54:55]
	v_lshl_add_u64 v[54:55], v[66:67], 1, v[52:53]
	flat_load_ushort v175, v[54:55] offset:2048
	v_lshl_add_u64 v[52:53], v[54:55], 0, s[54:55]
	s_and_saveexec_b64 s[44:45], s[0:1]
	s_cbranch_execz .LBB0_610
	v_add_co_u32_e32 v54, vcc, 0xffffe900, v52
	s_nop 1
	v_addc_co_u32_e32 v55, vcc, -1, v53, vcc
	flat_load_ushort v172, v[54:55]
.LBB0_610:
	s_or_b64 exec, exec, s[44:45]
	v_mov_b32_e32 v177, 0
	v_mov_b32_e32 v176, 0
	s_and_saveexec_b64 s[0:1], s[4:5]
	s_cbranch_execz .LBB0_612
	v_add_co_u32_e32 v52, vcc, 0x1000, v52
	s_nop 1
	v_addc_co_u32_e32 v53, vcc, 0, v53, vcc
	flat_load_ushort v176, v[52:53] offset:1792
; __device__ __forceinline__ float bf2f(u16 h) { return __uint_as_float(((unsigned)h) << 16); }
; __device__ __forceinline__ void even_post_phase(const Params& p, int ei, char* smem) {
;     ...
;       for (int q8 = 0; q8 < 4; ++q8) {
;         const int m = mh, j = q8;
;         const int tk = m * 16 + fq * 4 + j;
;         const size_t row = (size_t)row0 + tk;
;         const int l = l0 + tk;
;         const bool hp = l > seg_lo, hn = (l + 1) < seg_hi;
;         bon[q8] = 0.5f * (bonf[row * 8 + wid] + bonb[row * 8 + wid]);
; #pragma unroll
;         for (int n = 0; n < 4; ++n) {
;           const int col = wid * 64 + n * 16 + fr;
;           ov[q8][n] = bf2f(of[row * 512 + col]) + bf2f(ob[row * 512 + col]);
;           const u16* pv = big + row * PSTR + 1024 + col;
;           const float c = bf2f(*pv);
;           const float pr = hp ? bf2f(*(pv - PSTR)) : 0.f;
;           const float nx = hn ? bf2f(*(pv + PSTR)) : 0.f;
;           vs[q8][n] = c + muv[n] * (0.5f * (pr + nx) - c);
;         }
;       }
.LBB0_612:
	s_or_b64 exec, exec, s[0:1]
	v_mov_b32_e32 v53, s51
	v_or_b32_e32 v52, s50, v94
	v_lshl_add_u64 v[54:55], v[52:53], 3, v[72:73]
	v_lshlrev_b64 v[56:57], 9, v[52:53]
	v_lshlrev_b64 v[54:55], 2, v[54:55]
	v_lshl_add_u64 v[58:59], v[56:57], 0, v[64:65]
	v_lshl_add_u64 v[60:61], s[42:43], 0, v[54:55]
	v_lshl_add_u64 v[62:63], s[14:15], 0, v[54:55]
	v_mov_b64_e32 v[54:55], s[8:9]
	v_lshlrev_b64 v[58:59], 1, v[58:59]
	v_mad_i64_i32 v[54:55], s[0:1], v52, s19, v[54:55]
	v_lshl_add_u64 v[182:183], s[16:17], 0, v[58:59]
	v_lshl_add_u64 v[184:185], s[10:11], 0, v[58:59]
	v_lshl_add_u64 v[58:59], v[64:65], 1, v[54:55]
	flat_load_dword v178, v[60:61]
	flat_load_dword v181, v[62:63]
	flat_load_ushort v179, v[182:183]
	flat_load_ushort v180, v[184:185]
	s_nop 0
	flat_load_ushort v182, v[58:59] offset:2048
	v_or_b32_e32 v62, s46, v94
	v_cmp_lt_i32_e64 s[0:1], s47, v62
	v_lshl_add_u64 v[60:61], v[58:59], 0, s[54:55]
	s_and_saveexec_b64 s[4:5], s[0:1]
	s_cbranch_execz .LBB0_614
	v_add_co_u32_e32 v184, vcc, 0xffffe900, v60
	s_nop 1
	v_addc_co_u32_e32 v185, vcc, -1, v61, vcc
	flat_load_ushort v177, v[184:185]
.LBB0_614:
	s_or_b64 exec, exec, s[4:5]
	v_cmp_gt_i32_e64 s[4:5], s80, v62
	v_mov_b32_e32 v184, 0
	v_mov_b32_e32 v183, 0
	s_and_saveexec_b64 s[44:45], s[4:5]
	s_cbranch_execz .LBB0_616
	v_add_co_u32_e32 v60, vcc, 0x1000, v60
	s_nop 1
	v_addc_co_u32_e32 v61, vcc, 0, v61, vcc
	flat_load_ushort v183, v[60:61] offset:1792
.LBB0_616:
	s_or_b64 exec, exec, s[44:45]
	v_lshl_add_u64 v[60:61], v[56:57], 0, v[68:69]
	v_lshlrev_b64 v[60:61], 1, v[60:61]
	v_lshl_add_u64 v[62:63], s[16:17], 0, v[60:61]
	v_lshl_add_u64 v[60:61], s[10:11], 0, v[60:61]
	flat_load_ushort v185, v[62:63]
	flat_load_ushort v186, v[60:61]
	flat_load_ushort v187, v[58:59] offset:2080
	v_lshl_add_u64 v[60:61], v[58:59], 0, s[56:57]
	s_and_saveexec_b64 s[44:45], s[0:1]
	s_cbranch_execz .LBB0_618
	v_add_co_u32_e32 v62, vcc, 0xffffe900, v60
	s_nop 1
	v_addc_co_u32_e32 v63, vcc, -1, v61, vcc
	flat_load_ushort v184, v[62:63]
.LBB0_618:
	s_or_b64 exec, exec, s[44:45]
	v_mov_b32_e32 v189, 0
	v_mov_b32_e32 v188, 0
	s_and_saveexec_b64 s[44:45], s[4:5]
	s_cbranch_execz .LBB0_620
	v_add_co_u32_e32 v60, vcc, 0x1000, v60
	s_nop 1
	v_addc_co_u32_e32 v61, vcc, 0, v61, vcc
	flat_load_ushort v188, v[60:61] offset:1792
.LBB0_620:
	s_or_b64 exec, exec, s[44:45]
	v_lshl_add_u64 v[60:61], v[56:57], 0, v[70:71]
	v_lshlrev_b64 v[60:61], 1, v[60:61]
	v_lshl_add_u64 v[62:63], s[16:17], 0, v[60:61]
	v_lshl_add_u64 v[60:61], s[10:11], 0, v[60:61]
	flat_load_ushort v190, v[62:63]
	flat_load_ushort v191, v[60:61]
	flat_load_ushort v192, v[58:59] offset:2112
	v_lshl_add_u64 v[60:61], v[58:59], 0, s[58:59]
	s_and_saveexec_b64 s[44:45], s[0:1]
	s_cbranch_execz .LBB0_622
	v_add_co_u32_e32 v58, vcc, 0xffffe900, v60
	s_nop 1
	v_addc_co_u32_e32 v59, vcc, -1, v61, vcc
	flat_load_ushort v189, v[58:59]
.LBB0_622:
	s_or_b64 exec, exec, s[44:45]
	v_mov_b32_e32 v194, 0
	v_mov_b32_e32 v193, 0
	s_and_saveexec_b64 s[44:45], s[4:5]
	s_cbranch_execz .LBB0_624
	v_add_co_u32_e32 v58, vcc, 0x1000, v60
	s_nop 1
	v_addc_co_u32_e32 v59, vcc, 0, v61, vcc
	flat_load_ushort v193, v[58:59] offset:1792
.LBB0_624:
	s_or_b64 exec, exec, s[44:45]
	v_lshl_add_u64 v[56:57], v[56:57], 0, v[66:67]
	v_lshlrev_b64 v[56:57], 1, v[56:57]
	v_lshl_add_u64 v[58:59], s[16:17], 0, v[56:57]
	v_lshl_add_u64 v[56:57], s[10:11], 0, v[56:57]
	flat_load_ushort v195, v[58:59]
	flat_load_ushort v196, v[56:57]
	v_lshl_add_u64 v[56:57], v[66:67], 1, v[54:55]
	flat_load_ushort v197, v[56:57] offset:2048
	v_lshl_add_u64 v[54:55], v[56:57], 0, s[54:55]
	s_and_saveexec_b64 s[44:45], s[0:1]
	s_cbranch_execz .LBB0_626
	v_add_co_u32_e32 v56, vcc, 0xffffe900, v54
	s_nop 1
	v_addc_co_u32_e32 v57, vcc, -1, v55, vcc
	flat_load_ushort v194, v[56:57]
.LBB0_626:
	s_or_b64 exec, exec, s[44:45]
	v_mov_b32_e32 v199, 0
	v_mov_b32_e32 v198, 0
	s_and_saveexec_b64 s[0:1], s[4:5]
	s_cbranch_execz .LBB0_628
	v_add_co_u32_e32 v54, vcc, 0x1000, v54
	s_nop 1
	v_addc_co_u32_e32 v55, vcc, 0, v55, vcc
	flat_load_ushort v198, v[54:55] offset:1792

; __device__ __forceinline__ float bf2f(u16 h) { return __uint_as_float(((unsigned)h) << 16); }
; __device__ __forceinline__ void even_post_phase(const Params& p, int ei, char* smem) {
;     ...
;       for (int q8 = 0; q8 < 4; ++q8) {
;         const int m = mh, j = q8;
;         const int tk = m * 16 + fq * 4 + j;
;         const size_t row = (size_t)row0 + tk;
;         const int l = l0 + tk;
;         const bool hp = l > seg_lo, hn = (l + 1) < seg_hi;
;         bon[q8] = 0.5f * (bonf[row * 8 + wid] + bonb[row * 8 + wid]);
; #pragma unroll
;         for (int n = 0; n < 4; ++n) {
;           const int col = wid * 64 + n * 16 + fr;
;           ov[q8][n] = bf2f(of[row * 512 + col]) + bf2f(ob[row * 512 + col]);
;           const u16* pv = big + row * PSTR + 1024 + col;
;           const float c = bf2f(*pv);
;           const float pr = hp ? bf2f(*(pv - PSTR)) : 0.f;
;           const float nx = hn ? bf2f(*(pv + PSTR)) : 0.f;
;           vs[q8][n] = c + muv[n] * (0.5f * (pr + nx) - c);
;         }
;       }
.LBB0_630:
	s_or_b64 exec, exec, s[4:5]
	v_cmp_gt_i32_e64 s[4:5], s80, v228
	v_mov_b32_e32 v229, 0
	v_mov_b32_e32 v228, 0
	s_and_saveexec_b64 s[44:45], s[4:5]
	s_cbranch_execz .LBB0_632
	v_add_co_u32_e32 v62, vcc, 0x1000, v62
	s_nop 1
	v_addc_co_u32_e32 v63, vcc, 0, v63, vcc
	flat_load_ushort v228, v[62:63] offset:1792

; __device__ __forceinline__ float bf2f(u16 h) { return __uint_as_float(((unsigned)h) << 16); }
; __device__ __forceinline__ void even_post_phase(const Params& p, int ei, char* smem) {
;     ...
;       for (int q8 = 0; q8 < 4; ++q8) {
;         const int m = mh, j = q8;
;         const int tk = m * 16 + fq * 4 + j;
;         const size_t row = (size_t)row0 + tk;
;         const int l = l0 + tk;
;         const bool hp = l > seg_lo, hn = (l + 1) < seg_hi;
;         bon[q8] = 0.5f * (bonf[row * 8 + wid] + bonb[row * 8 + wid]);
; #pragma unroll
;         for (int n = 0; n < 4; ++n) {
;           const int col = wid * 64 + n * 16 + fr;
;           ov[q8][n] = bf2f(of[row * 512 + col]) + bf2f(ob[row * 512 + col]);
;           const u16* pv = big + row * PSTR + 1024 + col;
;           const float c = bf2f(*pv);
;           const float pr = hp ? bf2f(*(pv - PSTR)) : 0.f;
;           const float nx = hn ? bf2f(*(pv + PSTR)) : 0.f;
;           vs[q8][n] = c + muv[n] * (0.5f * (pr + nx) - c);
;         }
;       }
.LBB0_634:
	s_or_b64 exec, exec, s[44:45]
	v_mov_b32_e32 v235, 0
	v_mov_b32_e32 v234, 0
	s_and_saveexec_b64 s[44:45], s[4:5]
	s_cbranch_execz .LBB0_636
	v_add_co_u32_e32 v62, vcc, 0x1000, v62
	s_nop 1
	v_addc_co_u32_e32 v63, vcc, 0, v63, vcc
	flat_load_ushort v234, v[62:63] offset:1792
.LBB0_636:
	s_or_b64 exec, exec, s[44:45]
	v_lshl_add_u64 v[62:63], v[58:59], 0, v[70:71]
	v_lshlrev_b64 v[62:63], 1, v[62:63]
	v_lshl_add_u64 v[236:237], s[16:17], 0, v[62:63]
	v_lshl_add_u64 v[62:63], s[10:11], 0, v[62:63]
	flat_load_ushort v236, v[236:237]
	s_nop 0
	flat_load_ushort v237, v[62:63]
	v_lshl_add_u64 v[62:63], v[60:61], 0, s[58:59]
	flat_load_ushort v60, v[60:61] offset:2112
	s_and_saveexec_b64 s[44:45], s[0:1]
	s_cbranch_execz .LBB0_638
	v_add_co_u32_e32 v238, vcc, 0xffffe900, v62
	s_nop 1
	v_addc_co_u32_e32 v239, vcc, -1, v63, vcc
	flat_load_ushort v235, v[238:239]

; __device__ __forceinline__ float bf2f(u16 h) { return __uint_as_float(((unsigned)h) << 16); }
; __device__ __forceinline__ void even_post_phase(const Params& p, int ei, char* smem) {
;     ...
;       for (int q8 = 0; q8 < 4; ++q8) {
;         const int m = mh, j = q8;
;         const int tk = m * 16 + fq * 4 + j;
;         const size_t row = (size_t)row0 + tk;
;         const int l = l0 + tk;
;         const bool hp = l > seg_lo, hn = (l + 1) < seg_hi;
;         bon[q8] = 0.5f * (bonf[row * 8 + wid] + bonb[row * 8 + wid]);
; #pragma unroll
;         for (int n = 0; n < 4; ++n) {
;           const int col = wid * 64 + n * 16 + fr;
;           ov[q8][n] = bf2f(of[row * 512 + col]) + bf2f(ob[row * 512 + col]);
;           const u16* pv = big + row * PSTR + 1024 + col;
;           const float c = bf2f(*pv);
;           const float pr = hp ? bf2f(*(pv - PSTR)) : 0.f;
;           const float nx = hn ? bf2f(*(pv + PSTR)) : 0.f;
;           vs[q8][n] = c + muv[n] * (0.5f * (pr + nx) - c);
;         }
;       }
;       __builtin_amdgcn_sched_barrier(0);
; #pragma unroll
;       for (int q8 = 0; q8 < 4; ++q8) {
;         const int m = mh, j = q8;
;         const size_t row = (size_t)row0 + m * 16 + fq * 4 + j;
;         float sm = ov[q8][0] + ov[q8][1] + ov[q8][2] + ov[q8][3];
;         sm = row_sum16(sm);
;         const float mean = sm * (1.f / 64.f);
;         float vsum = 0.f;
; #pragma unroll
;         for (int n = 0; n < 4; ++n) { float dlt = ov[q8][n] - mean; vsum += dlt * dlt; }
;         vsum = row_sum16(vsum);
;         const float rstd = rsqrtf(vsum * (1.f / 64.f) + 64e-5f);
.LBB0_640:
	s_or_b64 exec, exec, s[44:45]
	v_lshl_add_u64 v[58:59], v[58:59], 0, v[66:67]
	v_lshlrev_b64 v[62:63], 1, v[58:59]
	v_lshl_add_u64 v[58:59], s[16:17], 0, v[62:63]
	v_lshl_add_u64 v[62:63], s[10:11], 0, v[62:63]
	flat_load_ushort v58, v[58:59]
	s_nop 0
	flat_load_ushort v59, v[62:63]
	v_lshl_add_u64 v[62:63], v[66:67], 1, v[56:57]
	flat_load_ushort v238, v[62:63] offset:2048
	v_lshl_add_u64 v[56:57], v[62:63], 0, s[54:55]
	s_and_saveexec_b64 s[44:45], s[0:1]
	s_cbranch_execz .LBB0_642
	v_add_co_u32_e32 v62, vcc, 0xffffe900, v56
	s_nop 1
	v_addc_co_u32_e32 v63, vcc, -1, v57, vcc
	flat_load_ushort v232, v[62:63]
.LBB0_642:
	s_or_b64 exec, exec, s[44:45]
	v_mov_b32_e32 v62, 0
	v_mov_b32_e32 v63, 0
	s_and_saveexec_b64 s[0:1], s[4:5]
	s_cbranch_execz .LBB0_644
	v_add_co_u32_e32 v56, vcc, 0x1000, v56
	s_nop 1
	v_addc_co_u32_e32 v57, vcc, 0, v57, vcc
	flat_load_ushort v63, v[56:57] offset:1792
.LBB0_644:
	s_or_b64 exec, exec, s[0:1]
	s_waitcnt vmcnt(0) lgkmcnt(0)
	v_lshlrev_b32_e32 v108, 16, v108
	v_lshlrev_b32_e32 v139, 16, v139
	v_lshlrev_b32_e32 v140, 16, v140
	v_lshlrev_b32_e32 v144, 16, v144
	v_lshlrev_b32_e32 v145, 16, v145
	v_lshlrev_b32_e32 v149, 16, v149
	v_lshlrev_b32_e32 v150, 16, v150
	v_lshlrev_b32_e32 v154, 16, v154
	v_lshlrev_b32_e32 v155, 16, v155
	v_lshlrev_b32_e32 v161, 16, v161
	v_lshlrev_b32_e32 v162, 16, v162
	v_lshlrev_b32_e32 v166, 16, v166
	v_lshlrev_b32_e32 v167, 16, v167
	v_lshlrev_b32_e32 v171, 16, v171
	v_lshlrev_b32_e32 v172, 16, v172
	v_lshlrev_b32_e32 v176, 16, v176
	v_lshlrev_b32_e32 v177, 16, v177
	v_lshlrev_b32_e32 v183, 16, v183
	v_lshlrev_b32_e32 v184, 16, v184
	v_lshlrev_b32_e32 v188, 16, v188
	v_lshlrev_b32_e32 v189, 16, v189
	v_lshlrev_b32_e32 v193, 16, v193
	v_lshlrev_b32_e32 v194, 16, v194
	v_lshlrev_b32_e32 v198, 16, v198
	v_lshlrev_b32_e32 v199, 16, v199
	v_lshlrev_b32_e32 v228, 16, v228
	v_lshlrev_b32_e32 v229, 16, v229
	v_lshlrev_b32_e32 v234, 16, v234
	v_lshlrev_b32_e32 v235, 16, v235
	v_lshlrev_b32_e32 v61, 16, v61
	v_lshlrev_b32_e32 v232, 16, v232
	v_lshlrev_b32_e32 v63, 16, v63
	v_lshlrev_b32_e32 v239, 16, v60
	v_add_f32_e32 v56, v235, v61
	v_fma_f32 v56, v56, 0.5, -v239
	v_fmac_f32_e32 v239, v95, v56
	v_lshlrev_b32_e32 v56, 16, v58
	v_lshlrev_b32_e32 v57, 16, v59
	v_add_f32_e32 v56, v56, v57
	v_lshlrev_b32_e32 v233, 16, v233
	v_add_f32_e32 v57, v229, v234
	v_fma_f32 v57, v57, 0.5, -v233
	v_fmac_f32_e32 v233, v93, v57
	v_lshlrev_b32_e32 v57, 16, v236
	v_lshlrev_b32_e32 v58, 16, v237
	v_add_f32_e32 v57, v57, v58
	v_lshlrev_b32_e32 v227, 16, v227
	v_add_f32_e32 v58, v199, v228
	v_fma_f32 v58, v58, 0.5, -v227
	v_fmac_f32_e32 v227, v91, v58
	v_lshlrev_b32_e32 v58, 16, v230
	v_lshlrev_b32_e32 v59, 16, v231
	v_add_f32_e32 v59, v58, v59
	v_lshlrev_b32_e32 v197, 16, v197
	v_add_f32_e32 v58, v194, v198
	v_fma_f32 v58, v58, 0.5, -v197
	v_fmac_f32_e32 v197, v121, v58
	v_add_f32_e32 v58, v200, v201
	v_mul_f32_e32 v194, 0.5, v58
	v_lshlrev_b32_e32 v58, 16, v225
	v_lshlrev_b32_e32 v60, 16, v226
	v_add_f32_e32 v58, v58, v60
	v_lshlrev_b32_e32 v192, 16, v192
	v_add_f32_e32 v60, v189, v193
	v_lshlrev_b32_e32 v175, 16, v175
	v_add_f32_e32 v172, v172, v176
	v_lshlrev_b32_e32 v153, 16, v153
	v_add_f32_e32 v150, v150, v154
	v_fma_f32 v60, v60, 0.5, -v192
	v_fma_f32 v172, v172, 0.5, -v175
	v_fma_f32 v150, v150, 0.5, -v153
	v_lshlrev_b32_e32 v154, 16, v158
	v_lshlrev_b32_e32 v158, 16, v138
	v_add_f32_e32 v108, v108, v139
	v_fmac_f32_e32 v192, v95, v60
	v_lshlrev_b32_e32 v60, 16, v195
	v_lshlrev_b32_e32 v61, 16, v196
	v_fmac_f32_e32 v175, v121, v172
	v_add_f32_e32 v172, v178, v181
	v_lshlrev_b32_e32 v176, 16, v179
	v_lshlrev_b32_e32 v178, 16, v180
	v_fmac_f32_e32 v153, v121, v150
	v_add_f32_e32 v150, v156, v159
	v_fma_f32 v108, v108, 0.5, -v158
	v_add_f32_e32 v60, v60, v61
	v_lshlrev_b32_e32 v187, 16, v187
	v_add_f32_e32 v61, v184, v188
	v_lshlrev_b32_e32 v182, 16, v182
	v_add_f32_e32 v177, v177, v183
	v_add_f32_e32 v176, v176, v178
	v_lshlrev_b32_e32 v178, 16, v170
	v_add_f32_e32 v167, v167, v171
	v_lshlrev_b32_e32 v165, 16, v165
	v_add_f32_e32 v162, v162, v166
	v_lshlrev_b32_e32 v160, 16, v160
	v_add_f32_e32 v155, v155, v161
	v_mul_f32_e32 v156, 0.5, v150
	v_lshlrev_b32_e32 v150, 16, v157
	v_lshlrev_b32_e32 v157, 16, v148
	v_add_f32_e32 v145, v145, v149
	v_lshlrev_b32_e32 v148, 16, v152
	v_lshlrev_b32_e32 v152, 16, v143
	v_add_f32_e32 v140, v140, v144
	v_fmac_f32_e32 v158, v91, v108
	v_lshlrev_b32_e32 v108, 16, v141
	v_lshlrev_b32_e32 v138, 16, v142
	v_lshlrev_b32_e32 v235, 16, v238
	v_fma_f32 v61, v61, 0.5, -v187
	v_fma_f32 v177, v177, 0.5, -v182
	v_fma_f32 v167, v167, 0.5, -v178
	v_fma_f32 v162, v162, 0.5, -v165
	v_fma_f32 v155, v155, 0.5, -v160
	v_fma_f32 v145, v145, 0.5, -v157
	v_fma_f32 v140, v140, 0.5, -v152
	v_add_f32_e32 v139, v108, v138
	v_add_f32_e32 v108, v134, v137
	v_add_f32_e32 v63, v232, v63
	v_fmac_f32_e32 v187, v93, v61
	v_lshlrev_b32_e32 v61, 16, v190
	v_lshlrev_b32_e32 v184, 16, v191
	v_fmac_f32_e32 v182, v91, v177
	v_lshlrev_b32_e32 v177, 16, v185
	v_lshlrev_b32_e32 v183, 16, v186
	v_fmac_f32_e32 v178, v95, v167
	v_lshlrev_b32_e32 v167, 16, v173
	v_lshlrev_b32_e32 v170, 16, v174
	v_fmac_f32_e32 v165, v93, v162
	v_lshlrev_b32_e32 v162, 16, v168
	v_lshlrev_b32_e32 v166, 16, v169
	v_fmac_f32_e32 v160, v91, v155
	v_lshlrev_b32_e32 v155, 16, v163
	v_lshlrev_b32_e32 v161, 16, v164
	v_fmac_f32_e32 v157, v95, v145
	v_lshlrev_b32_e32 v145, 16, v151
	v_fmac_f32_e32 v152, v93, v140
	v_lshlrev_b32_e32 v140, 16, v146
	v_lshlrev_b32_e32 v143, 16, v147
	v_mul_f32_e32 v159, 0.5, v108
	v_lshlrev_b32_e32 v108, 16, v135
	v_lshlrev_b32_e32 v134, 16, v136
	v_fma_f32 v63, v63, 0.5, -v235
	v_add_f32_e32 v61, v61, v184
; __device__ __forceinline__ u16 f2bf(float f) { return (u16)(pack2(f, 0.f) & 0xffffu); }
; __device__ __forceinline__ void even_post_phase(const Params& p, int ei, char* smem) {
;     ...
;       for (int q8 = 0; q8 < 4; ++q8) {
;         const int m = mh, j = q8;
;         const size_t row = (size_t)row0 + m * 16 + fq * 4 + j;
;         float sm = ov[q8][0] + ov[q8][1] + ov[q8][2] + ov[q8][3];
;         sm = row_sum16(sm);
;         const float mean = sm * (1.f / 64.f);
;         float vsum = 0.f;
; #pragma unroll
;         for (int n = 0; n < 4; ++n) { float dlt = ov[q8][n] - mean; vsum += dlt * dlt; }
;         vsum = row_sum16(vsum);
;         const float rstd = rsqrtf(vsum * (1.f / 64.f) + 64e-5f);
; #pragma unroll
;         for (int n = 0; n < 4; ++n) {
;           const int col = wid * 64 + n * 16 + fr;
;           const float on = (ov[q8][n] - mean) * rstd * lnw[n] + lnb[n];
;           act[row * D + col] = f2bf((on + bon[q8] * vs[q8][n]) * acc[m][n][j]);
;         }
;       }
	v_add_f32_e32 v177, v177, v183
	v_mul_f32_e32 v172, 0.5, v172
	v_add_f32_e32 v170, v167, v170
	v_add_f32_e32 v171, v162, v166
	v_add_f32_e32 v155, v155, v161
	v_add_f32_e32 v154, v150, v154
	v_add_f32_e32 v148, v145, v148
	v_add_f32_e32 v149, v140, v143
	v_add_f32_e32 v138, v108, v134
	v_fmac_f32_e32 v235, v121, v63
	v_add_f32_e32 v63, v138, v139
	v_add_f32_e32 v63, v63, v149
	v_add_f32_e32 v63, v63, v148
	s_mov_b32 s0, 0x3a27c5ac
	v_lshlrev_b64 v[48:49], 11, v[48:49]
	v_add_f32_dpp v63, v63, v63 row_ror:8 row_mask:0xf bank_mask:0xf bound_ctrl:1
	v_lshl_add_u64 v[48:49], s[86:87], 0, v[48:49]
	s_nop 0
	v_add_f32_dpp v63, v63, v63 row_ror:4 row_mask:0xf bank_mask:0xf bound_ctrl:1
	s_nop 1
	v_add_f32_dpp v63, v63, v63 row_ror:2 row_mask:0xf bank_mask:0xf bound_ctrl:1
	s_nop 1
	v_add_f32_dpp v63, v63, v63 row_ror:1 row_mask:0xf bank_mask:0xf bound_ctrl:1
	v_mul_f32_e32 v108, 0x3c800000, v63
	v_add_f32_e32 v63, v154, v155
	v_add_f32_e32 v63, v63, v171
	v_add_f32_e32 v63, v63, v170
	v_pk_add_f32 v[134:135], v[138:139], v[108:109] op_sel_hi:[1,0] neg_lo:[0,1] neg_hi:[0,1]
	v_pk_add_f32 v[138:139], v[148:149], v[108:109] op_sel_hi:[1,0] neg_lo:[0,1] neg_hi:[0,1]
	v_add_f32_dpp v63, v63, v63 row_ror:8 row_mask:0xf bank_mask:0xf bound_ctrl:1
	v_pk_mul_f32 v[136:137], v[134:135], v[134:135]
	v_pk_mul_f32 v[140:141], v[138:139], v[138:139]
	v_add_f32_dpp v63, v63, v63 row_ror:4 row_mask:0xf bank_mask:0xf bound_ctrl:1
	v_mov_b32_e32 v151, v136
	s_nop 0
	v_add_f32_dpp v63, v63, v63 row_ror:2 row_mask:0xf bank_mask:0xf bound_ctrl:1
	s_nop 1
	v_add_f32_dpp v63, v63, v63 row_ror:1 row_mask:0xf bank_mask:0xf bound_ctrl:1
	v_mul_f32_e32 v108, 0x3c800000, v63
	v_pk_add_f32 v[142:143], v[154:155], v[108:109] op_sel_hi:[1,0] neg_lo:[0,1] neg_hi:[0,1]
	v_pk_add_f32 v[146:147], v[170:171], v[108:109] op_sel_hi:[1,0] neg_lo:[0,1] neg_hi:[0,1]
	v_pk_mul_f32 v[144:145], v[142:143], v[142:143]
	v_pk_mul_f32 v[148:149], v[146:147], v[146:147]
	v_mov_b32_e32 v150, v144
	v_mov_b32_e32 v136, v145
	v_pk_add_f32 v[136:137], v[150:151], v[136:137]
	v_mov_b32_e32 v144, v149
	v_mov_b32_e32 v145, v141
	v_pk_add_f32 v[136:137], v[144:145], v[136:137]
	v_mov_b32_e32 v149, v140
	v_pk_add_f32 v[136:137], v[148:149], v[136:137]
	v_lshl_add_u64 v[144:145], v[48:49], 0, v[130:131]
	v_lshl_add_u64 v[48:49], v[48:49], 0, v[132:133]
	v_mov_b32_dpp v141, v137 row_ror:8 row_mask:0xf bank_mask:0xf bound_ctrl:1
	v_mov_b32_dpp v140, v136 row_ror:8 row_mask:0xf bank_mask:0xf bound_ctrl:1
	v_pk_add_f32 v[136:137], v[136:137], v[140:141]
	s_nop 1
	v_mov_b32_dpp v141, v137 row_ror:4 row_mask:0xf bank_mask:0xf bound_ctrl:1
	v_mov_b32_dpp v140, v136 row_ror:4 row_mask:0xf bank_mask:0xf bound_ctrl:1
	v_pk_add_f32 v[136:137], v[136:137], v[140:141]
	s_nop 1
	v_mov_b32_dpp v141, v137 row_ror:2 row_mask:0xf bank_mask:0xf bound_ctrl:1
	v_mov_b32_dpp v140, v136 row_ror:2 row_mask:0xf bank_mask:0xf bound_ctrl:1
	v_pk_add_f32 v[136:137], v[136:137], v[140:141]
	s_nop 1
	v_mov_b32_dpp v141, v137 row_ror:1 row_mask:0xf bank_mask:0xf bound_ctrl:1
	v_mov_b32_dpp v140, v136 row_ror:1 row_mask:0xf bank_mask:0xf bound_ctrl:1
	v_pk_add_f32 v[136:137], v[136:137], v[140:141]
	v_mov_b64_e32 v[140:141], s[0:1]
	v_pk_fma_f32 v[136:137], v[136:137], s[22:23], v[140:141] op_sel_hi:[1,0,0]
	s_nop 0
	v_mul_f32_e32 v63, 0x4b800000, v137
	v_cmp_gt_f32_e32 vcc, s39, v137
	s_nop 1
	v_cndmask_b32_e32 v63, v137, v63, vcc
	v_rsq_f32_e32 v63, v63
	s_nop 0
	v_mul_f32_e32 v108, 0x45800000, v63
	v_cndmask_b32_e32 v63, v63, v108, vcc
	v_mul_f32_e32 v108, v134, v63
	v_fma_f32 v108, v97, v108, v75
	v_fmac_f32_e32 v108, v159, v158
	v_mul_f32_e32 v44, v44, v108
	v_cvt_pk_bf16_f32 v44, v44, s0
	flat_store_short v[144:145], v44
	v_mul_f32_e32 v44, v135, v63
	v_fma_f32 v44, v99, v44, v85
	v_fmac_f32_e32 v44, v159, v152
	v_mul_f32_e32 v40, v40, v44
	v_cvt_pk_bf16_f32 v40, v40, s0
	flat_store_short v[144:145], v40 offset:32
	v_mul_f32_e32 v40, v139, v63
	v_fma_f32 v40, v101, v40, v87
	v_fmac_f32_e32 v40, v159, v157
	v_mul_f32_e32 v36, v36, v40
	v_cvt_pk_bf16_f32 v36, v36, s0
	v_mul_f32_e32 v40, 0x4b800000, v136
	v_cmp_gt_f32_e32 vcc, s39, v136
	flat_store_short v[144:145], v36 offset:64
	v_mul_f32_e32 v36, v138, v63
	v_cndmask_b32_e32 v40, v136, v40, vcc
	v_fma_f32 v36, v103, v36, v89
	v_rsq_f32_e32 v40, v40
	v_fmac_f32_e32 v36, v159, v153
	v_mul_f32_e32 v32, v32, v36
	v_cvt_pk_bf16_f32 v32, v32, s0
	flat_store_short v[48:49], v32
	v_mul_f32_e32 v32, 0x45800000, v40
	v_cndmask_b32_e32 v32, v40, v32, vcc
	v_mul_f32_e32 v36, v142, v32
	v_fma_f32 v36, v97, v36, v75
	v_lshlrev_b64 v[48:49], 11, v[50:51]
	v_fmac_f32_e32 v36, v156, v160
	v_lshl_add_u64 v[48:49], s[86:87], 0, v[48:49]
	v_mul_f32_e32 v36, v45, v36
	v_cvt_pk_bf16_f32 v36, v36, s0
	v_lshl_add_u64 v[44:45], v[48:49], 0, v[130:131]
	flat_store_short v[44:45], v36
	v_mul_f32_e32 v36, v143, v32
	v_fma_f32 v36, v99, v36, v85
	v_fmac_f32_e32 v36, v156, v165
	v_mul_f32_e32 v36, v41, v36
	v_cvt_pk_bf16_f32 v36, v36, s0
	flat_store_short v[44:45], v36 offset:32
	v_mul_f32_e32 v36, v147, v32
	v_fma_f32 v36, v101, v36, v87
	v_mul_f32_e32 v32, v146, v32
	v_fmac_f32_e32 v36, v156, v178
	v_fma_f32 v32, v103, v32, v89
	v_mul_f32_e32 v36, v37, v36
	v_fmac_f32_e32 v32, v156, v175
	v_cvt_pk_bf16_f32 v36, v36, s0
	v_mul_f32_e32 v32, v33, v32
	flat_store_short v[44:45], v36 offset:64
	v_cvt_pk_bf16_f32 v36, v32, s0
	v_lshl_add_u64 v[32:33], v[48:49], 0, v[132:133]
	flat_store_short v[32:33], v36
	v_add_f32_e32 v32, v176, v177
	v_add_f32_e32 v50, v58, v59
	v_add_f32_e32 v32, v32, v61
	v_add_f32_e32 v50, v50, v57
	v_add_f32_e32 v32, v32, v60
	v_add_f32_e32 v50, v50, v56
	v_lshlrev_b64 v[48:49], 11, v[52:53]
; __device__ __forceinline__ u16 f2bf(float f) { return (u16)(pack2(f, 0.f) & 0xffffu); }
; __device__ __forceinline__ float bf2f(u16 h) { return __uint_as_float(((unsigned)h) << 16); }
; __device__ __forceinline__ void even_post_phase(const Params& p, int ei, char* smem) {
;     ...
;       for (int q8 = 0; q8 < 4; ++q8) {
;         const int m = mh, j = q8;
;         const int tk = m * 16 + fq * 4 + j;
;         const size_t row = (size_t)row0 + tk;
;         const int l = l0 + tk;
;         const bool hp = l > seg_lo, hn = (l + 1) < seg_hi;
;         bon[q8] = 0.5f * (bonf[row * 8 + wid] + bonb[row * 8 + wid]);
; #pragma unroll
;         for (int n = 0; n < 4; ++n) {
;           const int col = wid * 64 + n * 16 + fr;
;           ov[q8][n] = bf2f(of[row * 512 + col]) + bf2f(ob[row * 512 + col]);
;           const u16* pv = big + row * PSTR + 1024 + col;
;           const float c = bf2f(*pv);
;           const float pr = hp ? bf2f(*(pv - PSTR)) : 0.f;
;           const float nx = hn ? bf2f(*(pv + PSTR)) : 0.f;
;           vs[q8][n] = c + muv[n] * (0.5f * (pr + nx) - c);
;         }
;       }
;     ...
;       for (int q8 = 0; q8 < 4; ++q8) {
;         const int m = mh, j = q8;
;         const size_t row = (size_t)row0 + m * 16 + fq * 4 + j;
;         float sm = ov[q8][0] + ov[q8][1] + ov[q8][2] + ov[q8][3];
;         sm = row_sum16(sm);
;         const float mean = sm * (1.f / 64.f);
;         float vsum = 0.f;
; #pragma unroll
;         for (int n = 0; n < 4; ++n) { float dlt = ov[q8][n] - mean; vsum += dlt * dlt; }
;         vsum = row_sum16(vsum);
;         const float rstd = rsqrtf(vsum * (1.f / 64.f) + 64e-5f);
; #pragma unroll
;         for (int n = 0; n < 4; ++n) {
;           const int col = wid * 64 + n * 16 + fr;
;           const float on = (ov[q8][n] - mean) * rstd * lnw[n] + lnb[n];
;           act[row * D + col] = f2bf((on + bon[q8] * vs[q8][n]) * acc[m][n][j]);
;         }
;       }
	v_add_f32_dpp v32, v32, v32 row_ror:8 row_mask:0xf bank_mask:0xf bound_ctrl:1
	v_add_f32_dpp v50, v50, v50 row_ror:8 row_mask:0xf bank_mask:0xf bound_ctrl:1
	s_nop 0
	v_add_f32_dpp v32, v32, v32 row_ror:4 row_mask:0xf bank_mask:0xf bound_ctrl:1
	v_add_f32_dpp v50, v50, v50 row_ror:4 row_mask:0xf bank_mask:0xf bound_ctrl:1
	s_nop 0
	v_add_f32_dpp v32, v32, v32 row_ror:2 row_mask:0xf bank_mask:0xf bound_ctrl:1
	v_add_f32_dpp v50, v50, v50 row_ror:2 row_mask:0xf bank_mask:0xf bound_ctrl:1
	s_nop 0
	v_add_f32_dpp v32, v32, v32 row_ror:1 row_mask:0xf bank_mask:0xf bound_ctrl:1
	v_add_f32_dpp v50, v50, v50 row_ror:1 row_mask:0xf bank_mask:0xf bound_ctrl:1
	v_mul_f32_e32 v32, 0x3c800000, v32
	v_mul_f32_e32 v50, 0x3c800000, v50
	v_pk_add_f32 v[36:37], v[176:177], v[32:33] op_sel_hi:[1,0] neg_lo:[0,1] neg_hi:[0,1]
	v_pk_add_f32 v[52:53], v[58:59], v[50:51] op_sel_hi:[1,0] neg_lo:[0,1] neg_hi:[0,1]
	v_pk_mul_f32 v[40:41], v[36:37], v[36:37]
	v_pk_add_f32 v[32:33], v[60:61], v[32:33] op_sel_hi:[1,0] neg_lo:[0,1] neg_hi:[0,1]
	v_pk_mul_f32 v[58:59], v[52:53], v[52:53]
	v_pk_add_f32 v[50:51], v[56:57], v[50:51] op_sel_hi:[1,0] neg_lo:[0,1] neg_hi:[0,1]
	v_pk_mul_f32 v[44:45], v[32:33], v[32:33]
	v_pk_mul_f32 v[56:57], v[50:51], v[50:51]
	v_mov_b32_e32 v60, v58
	v_mov_b32_e32 v61, v40
	v_mov_b32_e32 v40, v59
	v_pk_add_f32 v[40:41], v[60:61], v[40:41]
	v_mov_b32_e32 v58, v57
	v_mov_b32_e32 v59, v45
	v_pk_add_f32 v[40:41], v[58:59], v[40:41]
	v_mov_b32_e32 v57, v44
	v_pk_add_f32 v[40:41], v[56:57], v[40:41]
	s_nop 1
	v_mov_b32_dpp v45, v41 row_ror:8 row_mask:0xf bank_mask:0xf bound_ctrl:1
	v_mov_b32_dpp v44, v40 row_ror:8 row_mask:0xf bank_mask:0xf bound_ctrl:1
	v_pk_add_f32 v[40:41], v[40:41], v[44:45]
	s_nop 1
	v_mov_b32_dpp v45, v41 row_ror:4 row_mask:0xf bank_mask:0xf bound_ctrl:1
	v_mov_b32_dpp v44, v40 row_ror:4 row_mask:0xf bank_mask:0xf bound_ctrl:1
	v_pk_add_f32 v[40:41], v[40:41], v[44:45]
	s_nop 1
	v_mov_b32_dpp v45, v41 row_ror:2 row_mask:0xf bank_mask:0xf bound_ctrl:1
	v_mov_b32_dpp v44, v40 row_ror:2 row_mask:0xf bank_mask:0xf bound_ctrl:1
	v_pk_add_f32 v[40:41], v[40:41], v[44:45]
	s_nop 1
	v_mov_b32_dpp v45, v41 row_ror:1 row_mask:0xf bank_mask:0xf bound_ctrl:1
	v_mov_b32_dpp v44, v40 row_ror:1 row_mask:0xf bank_mask:0xf bound_ctrl:1
	v_pk_add_f32 v[40:41], v[40:41], v[44:45]
	s_nop 0
	v_pk_fma_f32 v[40:41], v[40:41], s[22:23], v[140:141] op_sel_hi:[1,0,0]
	s_nop 0
	v_mul_f32_e32 v44, 0x4b800000, v41
	v_cmp_gt_f32_e32 vcc, s39, v41
	s_nop 1
	v_cndmask_b32_e32 v41, v41, v44, vcc
	v_rsq_f32_e32 v41, v41
	v_lshl_add_u64 v[44:45], s[86:87], 0, v[48:49]
	v_lshl_add_u64 v[48:49], v[44:45], 0, v[130:131]
	v_lshl_add_u64 v[44:45], v[44:45], 0, v[132:133]
	v_mul_f32_e32 v56, 0x45800000, v41
	v_cndmask_b32_e32 v41, v41, v56, vcc
	v_mul_f32_e32 v33, v33, v41
	v_mul_f32_e32 v36, v36, v41
	v_fma_f32 v33, v101, v33, v87
	v_fma_f32 v36, v97, v36, v75
	v_fmac_f32_e32 v33, v172, v192
	v_fmac_f32_e32 v36, v172, v182
	v_mul_f32_e32 v33, v38, v33
	v_mul_f32_e32 v36, v46, v36
	v_cvt_pk_bf16_f32 v33, v33, s0
	v_cvt_pk_bf16_f32 v36, v36, s0
	flat_store_short v[48:49], v33 offset:64
	v_mul_f32_e32 v33, 0x4b800000, v40
	v_cmp_gt_f32_e32 vcc, s39, v40
	flat_store_short v[48:49], v36
	v_mul_f32_e32 v36, v37, v41
	v_mul_f32_e32 v32, v32, v41
	v_cndmask_b32_e32 v33, v40, v33, vcc
	v_fma_f32 v36, v99, v36, v85
	v_fma_f32 v32, v103, v32, v89
	v_rsq_f32_e32 v33, v33
	v_fmac_f32_e32 v36, v172, v187
	v_fmac_f32_e32 v32, v172, v197
	v_mul_f32_e32 v36, v42, v36
	v_mul_f32_e32 v32, v34, v32
	v_cvt_pk_bf16_f32 v36, v36, s0
	v_cvt_pk_bf16_f32 v32, v32, s0
	flat_store_short v[48:49], v36 offset:32
	flat_store_short v[44:45], v32
	v_mul_f32_e32 v32, 0x45800000, v33
	v_cndmask_b32_e32 v34, v33, v32, vcc
	v_mul_f32_e32 v36, v52, v34
	v_fma_f32 v36, v97, v36, v75
	v_lshlrev_b64 v[32:33], 11, v[54:55]
	v_fmac_f32_e32 v36, v194, v227
	v_lshl_add_u64 v[32:33], s[86:87], 0, v[32:33]
	v_mul_f32_e32 v36, v47, v36
	v_cvt_pk_bf16_f32 v38, v36, s0
	v_lshl_add_u64 v[36:37], v[32:33], 0, v[130:131]
	flat_store_short v[36:37], v38
	v_mul_f32_e32 v38, v53, v34
	v_fma_f32 v38, v99, v38, v85
	v_fmac_f32_e32 v38, v194, v233
	v_mul_f32_e32 v38, v43, v38
	v_cvt_pk_bf16_f32 v38, v38, s0
	flat_store_short v[36:37], v38 offset:32
	v_mul_f32_e32 v38, v51, v34
	v_mul_f32_e32 v34, v50, v34
	v_fma_f32 v38, v101, v38, v87
	v_fma_f32 v34, v103, v34, v89
	v_fmac_f32_e32 v38, v194, v239
	v_fmac_f32_e32 v34, v194, v235
	v_mul_f32_e32 v38, v39, v38
	v_mul_f32_e32 v34, v35, v34
	v_cvt_pk_bf16_f32 v38, v38, s0
	v_cvt_pk_bf16_f32 v34, v34, s0
	v_lshl_add_u64 v[32:33], v[32:33], 0, v[132:133]
	flat_store_short v[36:37], v38 offset:64
	flat_store_short v[32:33], v34
	v_mov_b32_e32 v33, s51
	v_or_b32_e32 v32, s50, v98
	v_lshl_add_u64 v[34:35], v[32:33], 3, v[72:73]
	v_lshlrev_b64 v[34:35], 2, v[34:35]
	v_lshlrev_b64 v[36:37], 9, v[32:33]
	v_lshl_add_u64 v[40:41], s[42:43], 0, v[34:35]
	v_lshl_add_u64 v[42:43], s[14:15], 0, v[34:35]
	v_mov_b64_e32 v[34:35], s[8:9]
	v_lshl_add_u64 v[38:39], v[36:37], 0, v[64:65]
	v_mad_i64_i32 v[34:35], s[0:1], v32, s19, v[34:35]
	v_lshlrev_b64 v[38:39], 1, v[38:39]
	v_lshl_add_u64 v[44:45], s[16:17], 0, v[38:39]
	v_lshl_add_u64 v[46:47], s[10:11], 0, v[38:39]
	v_lshl_add_u64 v[38:39], v[34:35], 0, v[130:131]
	flat_load_dword v48, v[40:41]
	flat_load_dword v51, v[42:43]
	flat_load_ushort v49, v[44:45]
	flat_load_ushort v50, v[46:47]
	flat_load_ushort v52, v[38:39] offset:2048
	v_or_b32_e32 v42, s46, v98
	v_cmp_lt_i32_e64 s[0:1], s47, v42
	v_lshl_add_u64 v[40:41], v[38:39], 0, s[54:55]
	s_and_saveexec_b64 s[4:5], s[0:1]
	s_cbranch_execz .LBB0_646
	v_add_co_u32_e32 v44, vcc, 0xffffe900, v40
	s_nop 1
	v_addc_co_u32_e32 v45, vcc, -1, v41, vcc
	flat_load_ushort v62, v[44:45]
; __device__ __forceinline__ float bf2f(u16 h) { return __uint_as_float(((unsigned)h) << 16); }
; __device__ __forceinline__ void even_post_phase(const Params& p, int ei, char* smem) {
;     ...
;       for (int q8 = 0; q8 < 4; ++q8) {
;         const int m = mh, j = q8;
;         const int tk = m * 16 + fq * 4 + j;
;         const size_t row = (size_t)row0 + tk;
;         const int l = l0 + tk;
;         const bool hp = l > seg_lo, hn = (l + 1) < seg_hi;
;         bon[q8] = 0.5f * (bonf[row * 8 + wid] + bonb[row * 8 + wid]);
; #pragma unroll
;         for (int n = 0; n < 4; ++n) {
;           const int col = wid * 64 + n * 16 + fr;
;           ov[q8][n] = bf2f(of[row * 512 + col]) + bf2f(ob[row * 512 + col]);
;           const u16* pv = big + row * PSTR + 1024 + col;
;           const float c = bf2f(*pv);
;           const float pr = hp ? bf2f(*(pv - PSTR)) : 0.f;
;           const float nx = hn ? bf2f(*(pv + PSTR)) : 0.f;
;           vs[q8][n] = c + muv[n] * (0.5f * (pr + nx) - c);
;         }
;       }
.LBB0_646:
	s_or_b64 exec, exec, s[4:5]
	v_cmp_gt_i32_e64 s[4:5], s80, v42
	v_mov_b32_e32 v54, 0
	v_mov_b32_e32 v53, 0
	s_and_saveexec_b64 s[44:45], s[4:5]
	s_cbranch_execz .LBB0_648
	v_add_co_u32_e32 v40, vcc, 0x1000, v40
	s_nop 1
	v_addc_co_u32_e32 v41, vcc, 0, v41, vcc
	flat_load_ushort v53, v[40:41] offset:1792
.LBB0_648:
	s_or_b64 exec, exec, s[44:45]
	v_lshl_add_u64 v[40:41], v[36:37], 0, v[68:69]
	v_lshlrev_b64 v[40:41], 1, v[40:41]
	v_lshl_add_u64 v[42:43], s[16:17], 0, v[40:41]
	v_lshl_add_u64 v[40:41], s[10:11], 0, v[40:41]
	flat_load_ushort v55, v[42:43]
	flat_load_ushort v56, v[40:41]
	flat_load_ushort v57, v[38:39] offset:2080
	v_lshl_add_u64 v[40:41], v[38:39], 0, s[56:57]
	s_and_saveexec_b64 s[44:45], s[0:1]
	s_cbranch_execz .LBB0_650
	v_add_co_u32_e32 v42, vcc, 0xffffe900, v40
	s_nop 1
	v_addc_co_u32_e32 v43, vcc, -1, v41, vcc
	flat_load_ushort v54, v[42:43]
.LBB0_650:
	s_or_b64 exec, exec, s[44:45]
	v_mov_b32_e32 v59, 0
	v_mov_b32_e32 v58, 0
	s_and_saveexec_b64 s[44:45], s[4:5]
	s_cbranch_execz .LBB0_652
	v_add_co_u32_e32 v40, vcc, 0x1000, v40
	s_nop 1
	v_addc_co_u32_e32 v41, vcc, 0, v41, vcc
	flat_load_ushort v58, v[40:41] offset:1792
.LBB0_652:
	s_or_b64 exec, exec, s[44:45]
	v_lshl_add_u64 v[40:41], v[36:37], 0, v[70:71]
	v_lshlrev_b64 v[40:41], 1, v[40:41]
	v_lshl_add_u64 v[42:43], s[16:17], 0, v[40:41]
	v_lshl_add_u64 v[40:41], s[10:11], 0, v[40:41]
	flat_load_ushort v60, v[42:43]
	flat_load_ushort v61, v[40:41]
	flat_load_ushort v63, v[38:39] offset:2112
	v_lshl_add_u64 v[40:41], v[38:39], 0, s[58:59]
	s_and_saveexec_b64 s[44:45], s[0:1]
	s_cbranch_execz .LBB0_654
	v_add_co_u32_e32 v38, vcc, 0xffffe900, v40
	s_nop 1
	v_addc_co_u32_e32 v39, vcc, -1, v41, vcc
	flat_load_ushort v59, v[38:39]
.LBB0_654:
	s_or_b64 exec, exec, s[44:45]
	v_mov_b32_e32 v134, 0
	v_mov_b32_e32 v108, 0
	s_and_saveexec_b64 s[44:45], s[4:5]
	s_cbranch_execz .LBB0_656
	v_add_co_u32_e32 v38, vcc, 0x1000, v40
	s_nop 1
	v_addc_co_u32_e32 v39, vcc, 0, v41, vcc
	flat_load_ushort v108, v[38:39] offset:1792
.LBB0_656:
	s_or_b64 exec, exec, s[44:45]
	v_lshl_add_u64 v[36:37], v[36:37], 0, v[66:67]
	v_lshlrev_b64 v[36:37], 1, v[36:37]
	v_lshl_add_u64 v[38:39], s[16:17], 0, v[36:37]
	v_lshl_add_u64 v[36:37], s[10:11], 0, v[36:37]
	flat_load_ushort v135, v[38:39]
	flat_load_ushort v136, v[36:37]
	v_lshl_add_u64 v[36:37], v[66:67], 1, v[34:35]
	flat_load_ushort v137, v[36:37] offset:2048
	v_lshl_add_u64 v[34:35], v[36:37], 0, s[54:55]
	s_and_saveexec_b64 s[44:45], s[0:1]
	s_cbranch_execz .LBB0_658
	v_add_co_u32_e32 v36, vcc, 0xffffe900, v34
	s_nop 1
	v_addc_co_u32_e32 v37, vcc, -1, v35, vcc
	flat_load_ushort v134, v[36:37]
.LBB0_658:
	s_or_b64 exec, exec, s[44:45]
	v_mov_b32_e32 v139, 0
	v_mov_b32_e32 v138, 0
	s_and_saveexec_b64 s[0:1], s[4:5]
	s_cbranch_execz .LBB0_660
	v_add_co_u32_e32 v34, vcc, 0x1000, v34
	s_nop 1
	v_addc_co_u32_e32 v35, vcc, 0, v35, vcc
	flat_load_ushort v138, v[34:35] offset:1792
.LBB0_660:
	s_or_b64 exec, exec, s[0:1]
	v_mov_b32_e32 v35, s51
	v_or_b32_e32 v34, s50, v100
	v_lshl_add_u64 v[36:37], v[34:35], 3, v[72:73]
	v_lshlrev_b64 v[38:39], 9, v[34:35]
	v_lshlrev_b64 v[36:37], 2, v[36:37]
	v_lshl_add_u64 v[40:41], v[38:39], 0, v[64:65]
	v_lshl_add_u64 v[42:43], s[42:43], 0, v[36:37]
	v_lshl_add_u64 v[44:45], s[14:15], 0, v[36:37]
	v_mov_b64_e32 v[36:37], s[8:9]
	v_lshlrev_b64 v[40:41], 1, v[40:41]
	v_mad_i64_i32 v[36:37], s[0:1], v34, s19, v[36:37]
	v_lshl_add_u64 v[144:145], s[10:11], 0, v[40:41]
	v_lshl_add_u64 v[46:47], s[16:17], 0, v[40:41]
	v_lshl_add_u64 v[40:41], v[64:65], 1, v[36:37]
	flat_load_dword v140, v[42:43]
	flat_load_dword v143, v[44:45]
	flat_load_ushort v141, v[46:47]
	flat_load_ushort v142, v[144:145]
	s_nop 0
	flat_load_ushort v144, v[40:41] offset:2048
	v_or_b32_e32 v44, s46, v100
	v_cmp_lt_i32_e64 s[0:1], s47, v44
	v_lshl_add_u64 v[42:43], v[40:41], 0, s[54:55]
	s_and_saveexec_b64 s[4:5], s[0:1]
	s_cbranch_execz .LBB0_662
	v_add_co_u32_e32 v46, vcc, 0xffffe900, v42
	s_nop 1
	v_addc_co_u32_e32 v47, vcc, -1, v43, vcc
	flat_load_ushort v139, v[46:47]
.LBB0_662:
	s_or_b64 exec, exec, s[4:5]
	v_cmp_gt_i32_e64 s[4:5], s80, v44
	v_mov_b32_e32 v146, 0
	v_mov_b32_e32 v145, 0
	s_and_saveexec_b64 s[44:45], s[4:5]
	s_cbranch_execz .LBB0_664
	v_add_co_u32_e32 v42, vcc, 0x1000, v42
	s_nop 1
	v_addc_co_u32_e32 v43, vcc, 0, v43, vcc
	flat_load_ushort v145, v[42:43] offset:1792
.LBB0_664:
	s_or_b64 exec, exec, s[44:45]
	v_lshl_add_u64 v[42:43], v[38:39], 0, v[68:69]
	v_lshlrev_b64 v[42:43], 1, v[42:43]
	v_lshl_add_u64 v[44:45], s[16:17], 0, v[42:43]
	v_lshl_add_u64 v[42:43], s[10:11], 0, v[42:43]
	flat_load_ushort v147, v[44:45]
	flat_load_ushort v148, v[42:43]
	flat_load_ushort v149, v[40:41] offset:2080
	v_lshl_add_u64 v[42:43], v[40:41], 0, s[56:57]
	s_and_saveexec_b64 s[44:45], s[0:1]
	s_cbranch_execz .LBB0_666
	v_add_co_u32_e32 v44, vcc, 0xffffe900, v42
	s_nop 1
	v_addc_co_u32_e32 v45, vcc, -1, v43, vcc
	flat_load_ushort v146, v[44:45]
.LBB0_666:
	s_or_b64 exec, exec, s[44:45]
	v_mov_b32_e32 v151, 0
	v_mov_b32_e32 v150, 0
	s_and_saveexec_b64 s[44:45], s[4:5]
	s_cbranch_execz .LBB0_668
	v_add_co_u32_e32 v42, vcc, 0x1000, v42
	s_nop 1
	v_addc_co_u32_e32 v43, vcc, 0, v43, vcc
	flat_load_ushort v150, v[42:43] offset:1792
.LBB0_668:
	s_or_b64 exec, exec, s[44:45]
	v_lshl_add_u64 v[42:43], v[38:39], 0, v[70:71]
	v_lshlrev_b64 v[42:43], 1, v[42:43]
	v_lshl_add_u64 v[44:45], s[16:17], 0, v[42:43]
	v_lshl_add_u64 v[42:43], s[10:11], 0, v[42:43]
	flat_load_ushort v152, v[44:45]
	flat_load_ushort v153, v[42:43]
	flat_load_ushort v154, v[40:41] offset:2112
	v_lshl_add_u64 v[42:43], v[40:41], 0, s[58:59]
	s_and_saveexec_b64 s[44:45], s[0:1]
	s_cbranch_execz .LBB0_670
	v_add_co_u32_e32 v40, vcc, 0xffffe900, v42
	s_nop 1
	v_addc_co_u32_e32 v41, vcc, -1, v43, vcc
	flat_load_ushort v151, v[40:41]
; __device__ __forceinline__ float bf2f(u16 h) { return __uint_as_float(((unsigned)h) << 16); }
; __device__ __forceinline__ void even_post_phase(const Params& p, int ei, char* smem) {
;     ...
;       for (int q8 = 0; q8 < 4; ++q8) {
;         const int m = mh, j = q8;
;         const int tk = m * 16 + fq * 4 + j;
;         const size_t row = (size_t)row0 + tk;
;         const int l = l0 + tk;
;         const bool hp = l > seg_lo, hn = (l + 1) < seg_hi;
;         bon[q8] = 0.5f * (bonf[row * 8 + wid] + bonb[row * 8 + wid]);
; #pragma unroll
;         for (int n = 0; n < 4; ++n) {
;           const int col = wid * 64 + n * 16 + fr;
;           ov[q8][n] = bf2f(of[row * 512 + col]) + bf2f(ob[row * 512 + col]);
;           const u16* pv = big + row * PSTR + 1024 + col;
;           const float c = bf2f(*pv);
;           const float pr = hp ? bf2f(*(pv - PSTR)) : 0.f;
;           const float nx = hn ? bf2f(*(pv + PSTR)) : 0.f;
;           vs[q8][n] = c + muv[n] * (0.5f * (pr + nx) - c);
;         }
;       }
.LBB0_670:
	s_or_b64 exec, exec, s[44:45]
	v_mov_b32_e32 v156, 0
	v_mov_b32_e32 v155, 0
	s_and_saveexec_b64 s[44:45], s[4:5]
	s_cbranch_execz .LBB0_672
	v_add_co_u32_e32 v40, vcc, 0x1000, v42
	s_nop 1
	v_addc_co_u32_e32 v41, vcc, 0, v43, vcc
	flat_load_ushort v155, v[40:41] offset:1792
.LBB0_672:
	s_or_b64 exec, exec, s[44:45]
	v_lshl_add_u64 v[38:39], v[38:39], 0, v[66:67]
	v_lshlrev_b64 v[38:39], 1, v[38:39]
	v_lshl_add_u64 v[40:41], s[16:17], 0, v[38:39]
	v_lshl_add_u64 v[38:39], s[10:11], 0, v[38:39]
	flat_load_ushort v157, v[40:41]
	flat_load_ushort v158, v[38:39]
	v_lshl_add_u64 v[38:39], v[66:67], 1, v[36:37]
	flat_load_ushort v159, v[38:39] offset:2048
	v_lshl_add_u64 v[36:37], v[38:39], 0, s[54:55]
	s_and_saveexec_b64 s[44:45], s[0:1]
	s_cbranch_execz .LBB0_674
	v_add_co_u32_e32 v38, vcc, 0xffffe900, v36
	s_nop 1
	v_addc_co_u32_e32 v39, vcc, -1, v37, vcc
	flat_load_ushort v156, v[38:39]
.LBB0_674:
	s_or_b64 exec, exec, s[44:45]
	v_mov_b32_e32 v161, 0
	v_mov_b32_e32 v160, 0
	s_and_saveexec_b64 s[0:1], s[4:5]
	s_cbranch_execz .LBB0_676
	v_add_co_u32_e32 v36, vcc, 0x1000, v36
	s_nop 1
	v_addc_co_u32_e32 v37, vcc, 0, v37, vcc
	flat_load_ushort v160, v[36:37] offset:1792
.LBB0_676:
	s_or_b64 exec, exec, s[0:1]
	v_mov_b32_e32 v37, s51
	v_or_b32_e32 v36, s50, v102
	v_lshl_add_u64 v[38:39], v[36:37], 3, v[72:73]
	v_lshlrev_b64 v[40:41], 9, v[36:37]
	v_lshlrev_b64 v[38:39], 2, v[38:39]
	v_lshl_add_u64 v[42:43], v[40:41], 0, v[64:65]
	v_lshl_add_u64 v[44:45], s[42:43], 0, v[38:39]
	v_lshl_add_u64 v[46:47], s[14:15], 0, v[38:39]
	v_mov_b64_e32 v[38:39], s[8:9]
	v_lshlrev_b64 v[42:43], 1, v[42:43]
	v_mad_i64_i32 v[38:39], s[0:1], v36, s19, v[38:39]
	v_lshl_add_u64 v[166:167], s[16:17], 0, v[42:43]
	v_lshl_add_u64 v[168:169], s[10:11], 0, v[42:43]
	v_lshl_add_u64 v[42:43], v[64:65], 1, v[38:39]
	flat_load_dword v162, v[44:45]
	flat_load_dword v165, v[46:47]
	flat_load_ushort v163, v[166:167]
	flat_load_ushort v164, v[168:169]
	s_nop 0
	flat_load_ushort v166, v[42:43] offset:2048
	v_or_b32_e32 v46, s46, v102
	v_cmp_lt_i32_e64 s[0:1], s47, v46
	v_lshl_add_u64 v[44:45], v[42:43], 0, s[54:55]
	s_and_saveexec_b64 s[4:5], s[0:1]
	s_cbranch_execz .LBB0_678
	v_add_co_u32_e32 v168, vcc, 0xffffe900, v44
	s_nop 1
	v_addc_co_u32_e32 v169, vcc, -1, v45, vcc
	flat_load_ushort v161, v[168:169]
.LBB0_678:
	s_or_b64 exec, exec, s[4:5]
	v_cmp_gt_i32_e64 s[4:5], s80, v46
	v_mov_b32_e32 v168, 0
	v_mov_b32_e32 v167, 0
	s_and_saveexec_b64 s[44:45], s[4:5]
	s_cbranch_execz .LBB0_680
	v_add_co_u32_e32 v44, vcc, 0x1000, v44
	s_nop 1
	v_addc_co_u32_e32 v45, vcc, 0, v45, vcc
	flat_load_ushort v167, v[44:45] offset:1792
.LBB0_680:
	s_or_b64 exec, exec, s[44:45]
	v_lshl_add_u64 v[44:45], v[40:41], 0, v[68:69]
	v_lshlrev_b64 v[44:45], 1, v[44:45]
	v_lshl_add_u64 v[46:47], s[16:17], 0, v[44:45]
	v_lshl_add_u64 v[44:45], s[10:11], 0, v[44:45]
	flat_load_ushort v169, v[46:47]
	flat_load_ushort v170, v[44:45]
	flat_load_ushort v171, v[42:43] offset:2080
	v_lshl_add_u64 v[44:45], v[42:43], 0, s[56:57]
	s_and_saveexec_b64 s[44:45], s[0:1]
	s_cbranch_execz .LBB0_682
	v_add_co_u32_e32 v46, vcc, 0xffffe900, v44
	s_nop 1
	v_addc_co_u32_e32 v47, vcc, -1, v45, vcc
	flat_load_ushort v168, v[46:47]
.LBB0_682:
	s_or_b64 exec, exec, s[44:45]
	v_mov_b32_e32 v173, 0
	v_mov_b32_e32 v172, 0
	s_and_saveexec_b64 s[44:45], s[4:5]
	s_cbranch_execz .LBB0_684
	v_add_co_u32_e32 v44, vcc, 0x1000, v44
	s_nop 1
	v_addc_co_u32_e32 v45, vcc, 0, v45, vcc
	flat_load_ushort v172, v[44:45] offset:1792
.LBB0_684:
	s_or_b64 exec, exec, s[44:45]
	v_lshl_add_u64 v[44:45], v[40:41], 0, v[70:71]
	v_lshlrev_b64 v[44:45], 1, v[44:45]
	v_lshl_add_u64 v[46:47], s[16:17], 0, v[44:45]
	v_lshl_add_u64 v[44:45], s[10:11], 0, v[44:45]
	flat_load_ushort v174, v[46:47]
	flat_load_ushort v175, v[44:45]
	flat_load_ushort v176, v[42:43] offset:2112
	v_lshl_add_u64 v[44:45], v[42:43], 0, s[58:59]
	s_and_saveexec_b64 s[44:45], s[0:1]
	s_cbranch_execz .LBB0_686
	v_add_co_u32_e32 v42, vcc, 0xffffe900, v44
	s_nop 1
	v_addc_co_u32_e32 v43, vcc, -1, v45, vcc
	flat_load_ushort v173, v[42:43]
.LBB0_686:
	s_or_b64 exec, exec, s[44:45]
	v_mov_b32_e32 v178, 0
	v_mov_b32_e32 v177, 0
	s_and_saveexec_b64 s[44:45], s[4:5]
	s_cbranch_execz .LBB0_688
	v_add_co_u32_e32 v42, vcc, 0x1000, v44
	s_nop 1
	v_addc_co_u32_e32 v43, vcc, 0, v45, vcc
	flat_load_ushort v177, v[42:43] offset:1792
.LBB0_688:
	s_or_b64 exec, exec, s[44:45]
	v_lshl_add_u64 v[40:41], v[40:41], 0, v[66:67]
	v_lshlrev_b64 v[40:41], 1, v[40:41]
	v_lshl_add_u64 v[42:43], s[16:17], 0, v[40:41]
	v_lshl_add_u64 v[40:41], s[10:11], 0, v[40:41]
	flat_load_ushort v179, v[42:43]
	flat_load_ushort v180, v[40:41]
	v_lshl_add_u64 v[40:41], v[66:67], 1, v[38:39]
	flat_load_ushort v181, v[40:41] offset:2048
	v_lshl_add_u64 v[38:39], v[40:41], 0, s[54:55]
	s_and_saveexec_b64 s[44:45], s[0:1]
	s_cbranch_execz .LBB0_690
	v_add_co_u32_e32 v40, vcc, 0xffffe900, v38
	s_nop 1
	v_addc_co_u32_e32 v41, vcc, -1, v39, vcc
	flat_load_ushort v178, v[40:41]
.LBB0_690:
	s_or_b64 exec, exec, s[44:45]
	v_mov_b32_e32 v183, 0
	v_mov_b32_e32 v182, 0
	s_and_saveexec_b64 s[0:1], s[4:5]
	s_cbranch_execz .LBB0_692
	v_add_co_u32_e32 v38, vcc, 0x1000, v38
	s_nop 1
	v_addc_co_u32_e32 v39, vcc, 0, v39, vcc
	flat_load_ushort v182, v[38:39] offset:1792

; __device__ __forceinline__ float bf2f(u16 h) { return __uint_as_float(((unsigned)h) << 16); }
; __device__ __forceinline__ void even_post_phase(const Params& p, int ei, char* smem) {
;     ...
;       for (int q8 = 0; q8 < 4; ++q8) {
;         const int m = mh, j = q8;
;         const int tk = m * 16 + fq * 4 + j;
;         const size_t row = (size_t)row0 + tk;
;         const int l = l0 + tk;
;         const bool hp = l > seg_lo, hn = (l + 1) < seg_hi;
;         bon[q8] = 0.5f * (bonf[row * 8 + wid] + bonb[row * 8 + wid]);
; #pragma unroll
;         for (int n = 0; n < 4; ++n) {
;           const int col = wid * 64 + n * 16 + fr;
;           ov[q8][n] = bf2f(of[row * 512 + col]) + bf2f(ob[row * 512 + col]);
;           const u16* pv = big + row * PSTR + 1024 + col;
;           const float c = bf2f(*pv);
;           const float pr = hp ? bf2f(*(pv - PSTR)) : 0.f;
;           const float nx = hn ? bf2f(*(pv + PSTR)) : 0.f;
;           vs[q8][n] = c + muv[n] * (0.5f * (pr + nx) - c);
;         }
;       }
.LBB0_694:
	s_or_b64 exec, exec, s[4:5]
	v_cmp_gt_i32_e64 s[4:5], s80, v189
	v_mov_b32_e32 v190, 0
	v_mov_b32_e32 v189, 0
	s_and_saveexec_b64 s[44:45], s[4:5]
	s_cbranch_execz .LBB0_696
	v_add_co_u32_e32 v46, vcc, 0x1000, v46
	s_nop 1
	v_addc_co_u32_e32 v47, vcc, 0, v47, vcc
	flat_load_ushort v189, v[46:47] offset:1792

; __device__ __forceinline__ float bf2f(u16 h) { return __uint_as_float(((unsigned)h) << 16); }
; __device__ __forceinline__ void even_post_phase(const Params& p, int ei, char* smem) {
;     ...
;       for (int q8 = 0; q8 < 4; ++q8) {
;         const int m = mh, j = q8;
;         const int tk = m * 16 + fq * 4 + j;
;         const size_t row = (size_t)row0 + tk;
;         const int l = l0 + tk;
;         const bool hp = l > seg_lo, hn = (l + 1) < seg_hi;
;         bon[q8] = 0.5f * (bonf[row * 8 + wid] + bonb[row * 8 + wid]);
; #pragma unroll
;         for (int n = 0; n < 4; ++n) {
;           const int col = wid * 64 + n * 16 + fr;
;           ov[q8][n] = bf2f(of[row * 512 + col]) + bf2f(ob[row * 512 + col]);
;           const u16* pv = big + row * PSTR + 1024 + col;
;           const float c = bf2f(*pv);
;           const float pr = hp ? bf2f(*(pv - PSTR)) : 0.f;
;           const float nx = hn ? bf2f(*(pv + PSTR)) : 0.f;
;           vs[q8][n] = c + muv[n] * (0.5f * (pr + nx) - c);
;         }
;       }
.LBB0_698:
	s_or_b64 exec, exec, s[44:45]
	v_mov_b32_e32 v196, 0
	v_mov_b32_e32 v195, 0
	s_and_saveexec_b64 s[44:45], s[4:5]
	s_cbranch_execz .LBB0_700
	v_add_co_u32_e32 v46, vcc, 0x1000, v46
	s_nop 1
	v_addc_co_u32_e32 v47, vcc, 0, v47, vcc
	flat_load_ushort v195, v[46:47] offset:1792
.LBB0_700:
	s_or_b64 exec, exec, s[44:45]
	v_lshl_add_u64 v[46:47], v[42:43], 0, v[70:71]
	v_lshlrev_b64 v[46:47], 1, v[46:47]
	v_lshl_add_u64 v[198:199], s[16:17], 0, v[46:47]
	v_lshl_add_u64 v[46:47], s[10:11], 0, v[46:47]
	flat_load_ushort v197, v[198:199]
	s_nop 0
	flat_load_ushort v198, v[46:47]
	v_lshl_add_u64 v[46:47], v[44:45], 0, s[58:59]
	flat_load_ushort v44, v[44:45] offset:2112
	s_and_saveexec_b64 s[44:45], s[0:1]
	s_cbranch_execz .LBB0_702
	v_add_co_u32_e32 v200, vcc, 0xffffe900, v46
	s_nop 1
	v_addc_co_u32_e32 v201, vcc, -1, v47, vcc
	flat_load_ushort v196, v[200:201]

; __device__ __forceinline__ float bf2f(u16 h) { return __uint_as_float(((unsigned)h) << 16); }
; __device__ __forceinline__ void even_post_phase(const Params& p, int ei, char* smem) {
;     ...
;       for (int q8 = 0; q8 < 4; ++q8) {
;         const int m = mh, j = q8;
;         const int tk = m * 16 + fq * 4 + j;
;         const size_t row = (size_t)row0 + tk;
;         const int l = l0 + tk;
;         const bool hp = l > seg_lo, hn = (l + 1) < seg_hi;
;         bon[q8] = 0.5f * (bonf[row * 8 + wid] + bonb[row * 8 + wid]);
; #pragma unroll
;         for (int n = 0; n < 4; ++n) {
;           const int col = wid * 64 + n * 16 + fr;
;           ov[q8][n] = bf2f(of[row * 512 + col]) + bf2f(ob[row * 512 + col]);
;           const u16* pv = big + row * PSTR + 1024 + col;
;           const float c = bf2f(*pv);
;           const float pr = hp ? bf2f(*(pv - PSTR)) : 0.f;
;           const float nx = hn ? bf2f(*(pv + PSTR)) : 0.f;
;           vs[q8][n] = c + muv[n] * (0.5f * (pr + nx) - c);
;         }
;       }
;       __builtin_amdgcn_sched_barrier(0);
; #pragma unroll
;       for (int q8 = 0; q8 < 4; ++q8) {
;         const int m = mh, j = q8;
;         const size_t row = (size_t)row0 + m * 16 + fq * 4 + j;
;         float sm = ov[q8][0] + ov[q8][1] + ov[q8][2] + ov[q8][3];
;         sm = row_sum16(sm);
;         const float mean = sm * (1.f / 64.f);
;         float vsum = 0.f;
; #pragma unroll
;         for (int n = 0; n < 4; ++n) { float dlt = ov[q8][n] - mean; vsum += dlt * dlt; }
;         vsum = row_sum16(vsum);
;         const float rstd = rsqrtf(vsum * (1.f / 64.f) + 64e-5f);
.LBB0_704:
	s_or_b64 exec, exec, s[44:45]
	v_lshl_add_u64 v[42:43], v[42:43], 0, v[66:67]
	v_lshlrev_b64 v[46:47], 1, v[42:43]
	v_lshl_add_u64 v[42:43], s[16:17], 0, v[46:47]
	v_lshl_add_u64 v[46:47], s[10:11], 0, v[46:47]
	flat_load_ushort v42, v[42:43]
	s_nop 0
	flat_load_ushort v43, v[46:47]
	v_lshl_add_u64 v[46:47], v[66:67], 1, v[40:41]
	flat_load_ushort v199, v[46:47] offset:2048
	v_lshl_add_u64 v[40:41], v[46:47], 0, s[54:55]
	s_and_saveexec_b64 s[44:45], s[0:1]
	s_cbranch_execz .LBB0_706
	v_add_co_u32_e32 v46, vcc, 0xffffe900, v40
	s_nop 1
	v_addc_co_u32_e32 v47, vcc, -1, v41, vcc
	flat_load_ushort v193, v[46:47]
.LBB0_706:
	s_or_b64 exec, exec, s[44:45]
	v_mov_b32_e32 v46, 0
	v_mov_b32_e32 v47, 0
	s_and_saveexec_b64 s[0:1], s[4:5]
	s_cbranch_execz .LBB0_708
	v_add_co_u32_e32 v40, vcc, 0x1000, v40
	s_nop 1
	v_addc_co_u32_e32 v41, vcc, 0, v41, vcc
	flat_load_ushort v47, v[40:41] offset:1792
.LBB0_708:
	s_or_b64 exec, exec, s[0:1]
	s_waitcnt vmcnt(0) lgkmcnt(0)
	v_lshlrev_b32_e32 v62, 16, v62
	v_lshlrev_b32_e32 v53, 16, v53
	v_lshlrev_b32_e32 v54, 16, v54
	v_lshlrev_b32_e32 v58, 16, v58
	v_lshlrev_b32_e32 v59, 16, v59
	v_lshlrev_b32_e32 v108, 16, v108
	v_lshlrev_b32_e32 v134, 16, v134
	v_lshlrev_b32_e32 v138, 16, v138
	v_lshlrev_b32_e32 v139, 16, v139
	v_lshlrev_b32_e32 v145, 16, v145
	v_lshlrev_b32_e32 v146, 16, v146
	v_lshlrev_b32_e32 v150, 16, v150
	v_lshlrev_b32_e32 v151, 16, v151
	v_lshlrev_b32_e32 v155, 16, v155
	v_lshlrev_b32_e32 v156, 16, v156
	v_lshlrev_b32_e32 v160, 16, v160
	v_lshlrev_b32_e32 v161, 16, v161
	v_lshlrev_b32_e32 v167, 16, v167
	v_lshlrev_b32_e32 v168, 16, v168
	v_lshlrev_b32_e32 v172, 16, v172
	v_lshlrev_b32_e32 v173, 16, v173
	v_lshlrev_b32_e32 v177, 16, v177
	v_lshlrev_b32_e32 v178, 16, v178
	v_lshlrev_b32_e32 v182, 16, v182
	v_lshlrev_b32_e32 v183, 16, v183
	v_lshlrev_b32_e32 v189, 16, v189
	v_lshlrev_b32_e32 v190, 16, v190
	v_lshlrev_b32_e32 v195, 16, v195
	v_lshlrev_b32_e32 v196, 16, v196
	v_lshlrev_b32_e32 v45, 16, v45
	v_lshlrev_b32_e32 v193, 16, v193
	v_lshlrev_b32_e32 v47, 16, v47
	v_lshlrev_b32_e32 v200, 16, v44
	v_add_f32_e32 v40, v196, v45
	v_fma_f32 v40, v40, 0.5, -v200
	v_fmac_f32_e32 v200, v95, v40
	v_lshlrev_b32_e32 v40, 16, v42
	v_lshlrev_b32_e32 v41, 16, v43
	v_add_f32_e32 v40, v40, v41
	v_lshlrev_b32_e32 v194, 16, v194
	v_add_f32_e32 v41, v190, v195
	v_fma_f32 v41, v41, 0.5, -v194
	v_fmac_f32_e32 v194, v93, v41
	v_lshlrev_b32_e32 v41, 16, v197
	v_lshlrev_b32_e32 v42, 16, v198
	v_add_f32_e32 v41, v41, v42
	v_lshlrev_b32_e32 v188, 16, v188
	v_add_f32_e32 v42, v183, v189
	v_fma_f32 v42, v42, 0.5, -v188
	v_fmac_f32_e32 v188, v91, v42
	v_lshlrev_b32_e32 v42, 16, v191
	v_lshlrev_b32_e32 v43, 16, v192
	v_add_f32_e32 v43, v42, v43
	v_lshlrev_b32_e32 v181, 16, v181
	v_add_f32_e32 v42, v178, v182
	v_fma_f32 v42, v42, 0.5, -v181
	v_fmac_f32_e32 v181, v121, v42
	v_add_f32_e32 v42, v184, v187
	v_mul_f32_e32 v178, 0.5, v42
	v_lshlrev_b32_e32 v42, 16, v185
	v_lshlrev_b32_e32 v44, 16, v186
	v_add_f32_e32 v42, v42, v44
	v_lshlrev_b32_e32 v176, 16, v176
	v_add_f32_e32 v44, v173, v177
	v_lshlrev_b32_e32 v159, 16, v159
	v_add_f32_e32 v156, v156, v160
	v_lshlrev_b32_e32 v137, 16, v137
	v_add_f32_e32 v134, v134, v138
	v_fma_f32 v44, v44, 0.5, -v176
	v_fma_f32 v156, v156, 0.5, -v159
	v_fma_f32 v134, v134, 0.5, -v137
	v_fmac_f32_e32 v176, v95, v44
	v_lshlrev_b32_e32 v44, 16, v179
	v_lshlrev_b32_e32 v45, 16, v180
	v_fmac_f32_e32 v159, v121, v156
	v_add_f32_e32 v156, v162, v165
	v_lshlrev_b32_e32 v160, 16, v163
	v_lshlrev_b32_e32 v162, 16, v164
	v_fmac_f32_e32 v137, v121, v134
	v_add_f32_e32 v134, v140, v143
	v_add_f32_e32 v44, v44, v45
	v_lshlrev_b32_e32 v171, 16, v171
	v_add_f32_e32 v45, v168, v172
	v_lshlrev_b32_e32 v166, 16, v166
	v_add_f32_e32 v161, v161, v167
	v_add_f32_e32 v160, v160, v162
	v_lshlrev_b32_e32 v162, 16, v154
	v_add_f32_e32 v151, v151, v155
	v_lshlrev_b32_e32 v149, 16, v149
	v_add_f32_e32 v146, v146, v150
	v_lshlrev_b32_e32 v144, 16, v144
	v_add_f32_e32 v139, v139, v145
	v_mul_f32_e32 v140, 0.5, v134
	v_lshlrev_b32_e32 v134, 16, v141
	v_lshlrev_b32_e32 v141, 16, v63
	v_add_f32_e32 v59, v59, v108
	v_lshlrev_b32_e32 v63, 16, v136
	v_lshlrev_b32_e32 v108, 16, v57
	v_add_f32_e32 v54, v54, v58
	v_lshlrev_b32_e32 v136, 16, v52
	v_add_f32_e32 v52, v62, v53
	v_lshlrev_b32_e32 v196, 16, v199
	v_fma_f32 v45, v45, 0.5, -v171
	v_fma_f32 v161, v161, 0.5, -v166
	v_fma_f32 v151, v151, 0.5, -v162
	v_fma_f32 v146, v146, 0.5, -v149
	v_fma_f32 v139, v139, 0.5, -v144
	v_fma_f32 v59, v59, 0.5, -v141
	v_fma_f32 v54, v54, 0.5, -v108
	v_fma_f32 v52, v52, 0.5, -v136
	v_add_f32_e32 v48, v48, v51
	v_add_f32_e32 v47, v193, v47
	v_fmac_f32_e32 v171, v93, v45
	v_lshlrev_b32_e32 v45, 16, v174
	v_lshlrev_b32_e32 v168, 16, v175
	v_fmac_f32_e32 v166, v91, v161
	v_lshlrev_b32_e32 v161, 16, v169
	v_lshlrev_b32_e32 v167, 16, v170
	v_fmac_f32_e32 v162, v95, v151
	v_lshlrev_b32_e32 v151, 16, v157
	v_lshlrev_b32_e32 v154, 16, v158
	v_fmac_f32_e32 v149, v93, v146
	v_lshlrev_b32_e32 v146, 16, v152
	v_lshlrev_b32_e32 v150, 16, v153
	v_fmac_f32_e32 v144, v91, v139
	v_lshlrev_b32_e32 v139, 16, v147
	v_lshlrev_b32_e32 v145, 16, v148
	v_lshlrev_b32_e32 v138, 16, v142
	v_fmac_f32_e32 v141, v95, v59
	v_lshlrev_b32_e32 v59, 16, v135
	v_fmac_f32_e32 v108, v93, v54
	v_lshlrev_b32_e32 v54, 16, v60
	v_lshlrev_b32_e32 v57, 16, v61
	v_fmac_f32_e32 v136, v91, v52
	v_lshlrev_b32_e32 v52, 16, v55
	v_lshlrev_b32_e32 v53, 16, v56
	v_mul_f32_e32 v142, 0.5, v48
	v_lshlrev_b32_e32 v48, 16, v49
	v_lshlrev_b32_e32 v49, 16, v50
	v_fma_f32 v47, v47, 0.5, -v196
	v_add_f32_e32 v45, v45, v168
	v_add_f32_e32 v161, v161, v167
	v_mul_f32_e32 v156, 0.5, v156
; __device__ __forceinline__ u16 f2bf(float f) { return (u16)(pack2(f, 0.f) & 0xffffu); }
; __device__ __forceinline__ void even_post_phase(const Params& p, int ei, char* smem) {
;     ...
;       for (int q8 = 0; q8 < 4; ++q8) {
;         const int m = mh, j = q8;
;         const size_t row = (size_t)row0 + m * 16 + fq * 4 + j;
;         float sm = ov[q8][0] + ov[q8][1] + ov[q8][2] + ov[q8][3];
;         sm = row_sum16(sm);
;         const float mean = sm * (1.f / 64.f);
;         float vsum = 0.f;
; #pragma unroll
;         for (int n = 0; n < 4; ++n) { float dlt = ov[q8][n] - mean; vsum += dlt * dlt; }
;         vsum = row_sum16(vsum);
;         const float rstd = rsqrtf(vsum * (1.f / 64.f) + 64e-5f);
; #pragma unroll
;         for (int n = 0; n < 4; ++n) {
;           const int col = wid * 64 + n * 16 + fr;
;           const float on = (ov[q8][n] - mean) * rstd * lnw[n] + lnb[n];
;           act[row * D + col] = f2bf((on + bon[q8] * vs[q8][n]) * acc[m][n][j]);
;         }
;       }
	v_add_f32_e32 v154, v151, v154
	v_add_f32_e32 v155, v146, v150
	v_add_f32_e32 v139, v139, v145
	v_add_f32_e32 v138, v134, v138
	v_add_f32_e32 v134, v59, v63
	v_add_f32_e32 v135, v54, v57
	v_add_f32_e32 v53, v52, v53
	v_add_f32_e32 v52, v48, v49
	v_fmac_f32_e32 v196, v121, v47
	v_add_f32_e32 v47, v52, v53
	v_add_f32_e32 v47, v47, v135
	v_add_f32_e32 v47, v47, v134
	s_mov_b32 s0, 0x3a27c5ac
	v_lshlrev_b64 v[32:33], 11, v[32:33]
	v_add_f32_dpp v47, v47, v47 row_ror:8 row_mask:0xf bank_mask:0xf bound_ctrl:1
	v_lshl_add_u64 v[32:33], s[86:87], 0, v[32:33]
	s_nop 0
	v_add_f32_dpp v47, v47, v47 row_ror:4 row_mask:0xf bank_mask:0xf bound_ctrl:1
	s_nop 1
	v_add_f32_dpp v47, v47, v47 row_ror:2 row_mask:0xf bank_mask:0xf bound_ctrl:1
	s_nop 1
	v_add_f32_dpp v47, v47, v47 row_ror:1 row_mask:0xf bank_mask:0xf bound_ctrl:1
	v_mul_f32_e32 v48, 0x3c800000, v47
	v_add_f32_e32 v47, v138, v139
	v_add_f32_e32 v47, v47, v155
	v_add_f32_e32 v47, v47, v154
	v_pk_add_f32 v[50:51], v[52:53], v[48:49] op_sel_hi:[1,0] neg_lo:[0,1] neg_hi:[0,1]
	v_pk_add_f32 v[48:49], v[134:135], v[48:49] op_sel_hi:[1,0] neg_lo:[0,1] neg_hi:[0,1]
	v_add_f32_dpp v47, v47, v47 row_ror:8 row_mask:0xf bank_mask:0xf bound_ctrl:1
	v_pk_mul_f32 v[52:53], v[50:51], v[50:51]
	v_pk_mul_f32 v[54:55], v[48:49], v[48:49]
	v_add_f32_dpp v47, v47, v47 row_ror:4 row_mask:0xf bank_mask:0xf bound_ctrl:1
	v_mov_b32_e32 v135, v52
	s_nop 0
	v_add_f32_dpp v47, v47, v47 row_ror:2 row_mask:0xf bank_mask:0xf bound_ctrl:1
	s_nop 1
	v_add_f32_dpp v47, v47, v47 row_ror:1 row_mask:0xf bank_mask:0xf bound_ctrl:1
	v_mul_f32_e32 v56, 0x3c800000, v47
	v_pk_add_f32 v[58:59], v[138:139], v[56:57] op_sel_hi:[1,0] neg_lo:[0,1] neg_hi:[0,1]
	v_pk_add_f32 v[56:57], v[154:155], v[56:57] op_sel_hi:[1,0] neg_lo:[0,1] neg_hi:[0,1]
	v_pk_mul_f32 v[60:61], v[58:59], v[58:59]
	v_pk_mul_f32 v[62:63], v[56:57], v[56:57]
	v_mov_b32_e32 v134, v60
	v_mov_b32_e32 v52, v61
	v_pk_add_f32 v[52:53], v[134:135], v[52:53]
	v_mov_b32_e32 v60, v63
	v_mov_b32_e32 v61, v55
	v_pk_add_f32 v[52:53], v[60:61], v[52:53]
	v_mov_b32_e32 v63, v54
	v_pk_add_f32 v[52:53], v[62:63], v[52:53]
	v_lshl_add_u64 v[60:61], v[32:33], 0, v[130:131]
	v_lshl_add_u64 v[32:33], v[32:33], 0, v[132:133]
	v_mov_b32_dpp v55, v53 row_ror:8 row_mask:0xf bank_mask:0xf bound_ctrl:1
	v_mov_b32_dpp v54, v52 row_ror:8 row_mask:0xf bank_mask:0xf bound_ctrl:1
	v_pk_add_f32 v[52:53], v[52:53], v[54:55]
	s_nop 1
	v_mov_b32_dpp v55, v53 row_ror:4 row_mask:0xf bank_mask:0xf bound_ctrl:1
	v_mov_b32_dpp v54, v52 row_ror:4 row_mask:0xf bank_mask:0xf bound_ctrl:1
	v_pk_add_f32 v[52:53], v[52:53], v[54:55]
	s_nop 1
	v_mov_b32_dpp v55, v53 row_ror:2 row_mask:0xf bank_mask:0xf bound_ctrl:1
	v_mov_b32_dpp v54, v52 row_ror:2 row_mask:0xf bank_mask:0xf bound_ctrl:1
	v_pk_add_f32 v[52:53], v[52:53], v[54:55]
	s_nop 1
	v_mov_b32_dpp v55, v53 row_ror:1 row_mask:0xf bank_mask:0xf bound_ctrl:1
	v_mov_b32_dpp v54, v52 row_ror:1 row_mask:0xf bank_mask:0xf bound_ctrl:1
	v_pk_add_f32 v[52:53], v[52:53], v[54:55]
	v_mov_b64_e32 v[54:55], s[0:1]
	v_pk_fma_f32 v[52:53], v[52:53], s[22:23], v[54:55] op_sel_hi:[1,0,0]
	s_nop 0
	v_mul_f32_e32 v47, 0x4b800000, v53
	v_cmp_gt_f32_e32 vcc, s39, v53
	s_nop 1
	v_cndmask_b32_e32 v47, v53, v47, vcc
	v_rsq_f32_e32 v47, v47
	s_nop 0
	v_mul_f32_e32 v53, 0x45800000, v47
	v_cndmask_b32_e32 v47, v47, v53, vcc
	v_mul_f32_e32 v50, v50, v47
	v_fma_f32 v50, v97, v50, v75
	v_fmac_f32_e32 v50, v142, v136
	v_mul_f32_e32 v24, v24, v50
	v_cvt_pk_bf16_f32 v24, v24, s0
	flat_store_short v[60:61], v24
	v_mul_f32_e32 v24, v51, v47
	v_fma_f32 v24, v99, v24, v85
	v_fmac_f32_e32 v24, v142, v108
	v_mul_f32_e32 v24, v28, v24
	v_cvt_pk_bf16_f32 v24, v24, s0
	flat_store_short v[60:61], v24 offset:32
	v_mul_f32_e32 v24, v49, v47
	v_fma_f32 v24, v101, v24, v87
	v_fmac_f32_e32 v24, v142, v141
	v_mul_f32_e32 v16, v16, v24
	v_cvt_pk_bf16_f32 v16, v16, s0
	v_mul_f32_e32 v24, 0x4b800000, v52
	v_cmp_gt_f32_e32 vcc, s39, v52
	flat_store_short v[60:61], v16 offset:64
	v_mul_f32_e32 v16, v48, v47
	v_cndmask_b32_e32 v24, v52, v24, vcc
	v_fma_f32 v16, v103, v16, v89
	v_rsq_f32_e32 v24, v24
	v_fmac_f32_e32 v16, v142, v137
	v_mul_f32_e32 v16, v20, v16
	v_cvt_pk_bf16_f32 v16, v16, s0
	flat_store_short v[32:33], v16
	v_mul_f32_e32 v16, 0x45800000, v24
	v_cndmask_b32_e32 v16, v24, v16, vcc
	v_mul_f32_e32 v20, v58, v16
	v_fma_f32 v20, v97, v20, v75
	v_lshlrev_b64 v[32:33], 11, v[34:35]
	v_fmac_f32_e32 v20, v140, v144
	v_lshl_add_u64 v[32:33], s[86:87], 0, v[32:33]
	v_mul_f32_e32 v20, v25, v20
	v_cvt_pk_bf16_f32 v20, v20, s0
	v_lshl_add_u64 v[24:25], v[32:33], 0, v[130:131]
	flat_store_short v[24:25], v20
	v_mul_f32_e32 v20, v59, v16
	v_fma_f32 v20, v99, v20, v85
	v_fmac_f32_e32 v20, v140, v149
	v_mul_f32_e32 v20, v29, v20
	v_cvt_pk_bf16_f32 v20, v20, s0
	flat_store_short v[24:25], v20 offset:32
	v_mul_f32_e32 v20, v57, v16
	v_fma_f32 v20, v101, v20, v87
	v_mul_f32_e32 v16, v56, v16
	v_fmac_f32_e32 v20, v140, v162
	v_fma_f32 v16, v103, v16, v89
	v_mul_f32_e32 v17, v17, v20
	v_fmac_f32_e32 v16, v140, v159
	v_cvt_pk_bf16_f32 v17, v17, s0
	v_mul_f32_e32 v16, v21, v16
	flat_store_short v[24:25], v17 offset:64
	v_cvt_pk_bf16_f32 v20, v16, s0
	v_lshl_add_u64 v[16:17], v[32:33], 0, v[132:133]
	flat_store_short v[16:17], v20
	v_add_f32_e32 v16, v160, v161
	v_add_f32_e32 v34, v42, v43
	v_add_f32_e32 v16, v16, v45
	v_add_f32_e32 v34, v34, v41
	v_add_f32_e32 v16, v16, v44
	v_add_f32_e32 v34, v34, v40
	v_lshlrev_b64 v[32:33], 11, v[36:37]
	v_add_f32_dpp v16, v16, v16 row_ror:8 row_mask:0xf bank_mask:0xf bound_ctrl:1
	v_add_f32_dpp v34, v34, v34 row_ror:8 row_mask:0xf bank_mask:0xf bound_ctrl:1
	s_nop 0
; __device__ __forceinline__ u16 f2bf(float f) { return (u16)(pack2(f, 0.f) & 0xffffu); }
; __device__ __forceinline__ float bf2f(u16 h) { return __uint_as_float(((unsigned)h) << 16); }
; __device__ __forceinline__ void even_post_phase(const Params& p, int ei, char* smem) {
;     ...
;       for (int q8 = 0; q8 < 4; ++q8) {
;         const int m = mh, j = q8;
;         const int tk = m * 16 + fq * 4 + j;
;         const size_t row = (size_t)row0 + tk;
;         const int l = l0 + tk;
;         const bool hp = l > seg_lo, hn = (l + 1) < seg_hi;
;         bon[q8] = 0.5f * (bonf[row * 8 + wid] + bonb[row * 8 + wid]);
; #pragma unroll
;         for (int n = 0; n < 4; ++n) {
;           const int col = wid * 64 + n * 16 + fr;
;           ov[q8][n] = bf2f(of[row * 512 + col]) + bf2f(ob[row * 512 + col]);
;           const u16* pv = big + row * PSTR + 1024 + col;
;           const float c = bf2f(*pv);
;           const float pr = hp ? bf2f(*(pv - PSTR)) : 0.f;
;           const float nx = hn ? bf2f(*(pv + PSTR)) : 0.f;
;           vs[q8][n] = c + muv[n] * (0.5f * (pr + nx) - c);
;         }
;       }
;     ...
;       for (int q8 = 0; q8 < 4; ++q8) {
;         const int m = mh, j = q8;
;         const size_t row = (size_t)row0 + m * 16 + fq * 4 + j;
;         float sm = ov[q8][0] + ov[q8][1] + ov[q8][2] + ov[q8][3];
;         sm = row_sum16(sm);
;         const float mean = sm * (1.f / 64.f);
;         float vsum = 0.f;
; #pragma unroll
;         for (int n = 0; n < 4; ++n) { float dlt = ov[q8][n] - mean; vsum += dlt * dlt; }
;         vsum = row_sum16(vsum);
;         const float rstd = rsqrtf(vsum * (1.f / 64.f) + 64e-5f);
; #pragma unroll
;         for (int n = 0; n < 4; ++n) {
;           const int col = wid * 64 + n * 16 + fr;
;           const float on = (ov[q8][n] - mean) * rstd * lnw[n] + lnb[n];
;           act[row * D + col] = f2bf((on + bon[q8] * vs[q8][n]) * acc[m][n][j]);
;         }
;       }
	v_add_f32_dpp v16, v16, v16 row_ror:4 row_mask:0xf bank_mask:0xf bound_ctrl:1
	v_add_f32_dpp v34, v34, v34 row_ror:4 row_mask:0xf bank_mask:0xf bound_ctrl:1
	s_nop 0
	v_add_f32_dpp v16, v16, v16 row_ror:2 row_mask:0xf bank_mask:0xf bound_ctrl:1
	v_add_f32_dpp v34, v34, v34 row_ror:2 row_mask:0xf bank_mask:0xf bound_ctrl:1
	s_nop 0
	v_add_f32_dpp v16, v16, v16 row_ror:1 row_mask:0xf bank_mask:0xf bound_ctrl:1
	v_add_f32_dpp v34, v34, v34 row_ror:1 row_mask:0xf bank_mask:0xf bound_ctrl:1
	v_mul_f32_e32 v16, 0x3c800000, v16
	v_mul_f32_e32 v34, 0x3c800000, v34
	v_pk_add_f32 v[20:21], v[160:161], v[16:17] op_sel_hi:[1,0] neg_lo:[0,1] neg_hi:[0,1]
	v_pk_add_f32 v[36:37], v[42:43], v[34:35] op_sel_hi:[1,0] neg_lo:[0,1] neg_hi:[0,1]
	v_pk_mul_f32 v[24:25], v[20:21], v[20:21]
	v_pk_add_f32 v[16:17], v[44:45], v[16:17] op_sel_hi:[1,0] neg_lo:[0,1] neg_hi:[0,1]
	v_pk_mul_f32 v[42:43], v[36:37], v[36:37]
	v_pk_add_f32 v[34:35], v[40:41], v[34:35] op_sel_hi:[1,0] neg_lo:[0,1] neg_hi:[0,1]
	v_pk_mul_f32 v[28:29], v[16:17], v[16:17]
	v_pk_mul_f32 v[40:41], v[34:35], v[34:35]
	v_mov_b32_e32 v44, v42
	v_mov_b32_e32 v45, v24
	v_mov_b32_e32 v24, v43
	v_pk_add_f32 v[24:25], v[44:45], v[24:25]
	v_mov_b32_e32 v42, v41
	v_mov_b32_e32 v43, v29
	v_pk_add_f32 v[24:25], v[42:43], v[24:25]
	v_mov_b32_e32 v41, v28
	v_pk_add_f32 v[24:25], v[40:41], v[24:25]
	s_nop 1
	v_mov_b32_dpp v29, v25 row_ror:8 row_mask:0xf bank_mask:0xf bound_ctrl:1
	v_mov_b32_dpp v28, v24 row_ror:8 row_mask:0xf bank_mask:0xf bound_ctrl:1
	v_pk_add_f32 v[24:25], v[24:25], v[28:29]
	s_nop 1
	v_mov_b32_dpp v29, v25 row_ror:4 row_mask:0xf bank_mask:0xf bound_ctrl:1
	v_mov_b32_dpp v28, v24 row_ror:4 row_mask:0xf bank_mask:0xf bound_ctrl:1
	v_pk_add_f32 v[24:25], v[24:25], v[28:29]
	s_nop 1
	v_mov_b32_dpp v29, v25 row_ror:2 row_mask:0xf bank_mask:0xf bound_ctrl:1
	v_mov_b32_dpp v28, v24 row_ror:2 row_mask:0xf bank_mask:0xf bound_ctrl:1
	v_pk_add_f32 v[24:25], v[24:25], v[28:29]
	s_nop 1
	v_mov_b32_dpp v29, v25 row_ror:1 row_mask:0xf bank_mask:0xf bound_ctrl:1
	v_mov_b32_dpp v28, v24 row_ror:1 row_mask:0xf bank_mask:0xf bound_ctrl:1
	v_pk_add_f32 v[24:25], v[24:25], v[28:29]
	s_nop 0
	v_pk_fma_f32 v[24:25], v[24:25], s[22:23], v[54:55] op_sel_hi:[1,0,0]
	s_nop 0
	v_mul_f32_e32 v28, 0x4b800000, v25
	v_cmp_gt_f32_e32 vcc, s39, v25
	s_nop 1
	v_cndmask_b32_e32 v25, v25, v28, vcc
	v_rsq_f32_e32 v25, v25
	v_lshl_add_u64 v[28:29], s[86:87], 0, v[32:33]
	v_lshl_add_u64 v[32:33], v[28:29], 0, v[130:131]
	v_lshl_add_u64 v[28:29], v[28:29], 0, v[132:133]
	v_mul_f32_e32 v40, 0x45800000, v25
	v_cndmask_b32_e32 v25, v25, v40, vcc
	v_mul_f32_e32 v17, v17, v25
	v_mul_f32_e32 v20, v20, v25
	v_fma_f32 v17, v101, v17, v87
	v_fma_f32 v20, v97, v20, v75
	v_fmac_f32_e32 v17, v156, v176
	v_fmac_f32_e32 v20, v156, v166
	v_mul_f32_e32 v17, v18, v17
	v_mul_f32_e32 v20, v26, v20
	v_cvt_pk_bf16_f32 v17, v17, s0
	v_cvt_pk_bf16_f32 v20, v20, s0
	flat_store_short v[32:33], v17 offset:64
	v_mul_f32_e32 v17, 0x4b800000, v24
	v_cmp_gt_f32_e32 vcc, s39, v24
	flat_store_short v[32:33], v20
	v_mul_f32_e32 v20, v21, v25
	v_mul_f32_e32 v16, v16, v25
	v_cndmask_b32_e32 v17, v24, v17, vcc
	v_fma_f32 v20, v99, v20, v85
	v_fma_f32 v16, v103, v16, v89
	v_rsq_f32_e32 v17, v17
	v_fmac_f32_e32 v20, v156, v171
	v_fmac_f32_e32 v16, v156, v181
	v_mul_f32_e32 v20, v30, v20
	v_mul_f32_e32 v16, v22, v16
	v_cvt_pk_bf16_f32 v20, v20, s0
	v_cvt_pk_bf16_f32 v16, v16, s0
	flat_store_short v[32:33], v20 offset:32
	flat_store_short v[28:29], v16
	v_mul_f32_e32 v16, 0x45800000, v17
	v_cndmask_b32_e32 v18, v17, v16, vcc
	v_mul_f32_e32 v20, v36, v18
	v_fma_f32 v20, v97, v20, v75
	v_lshlrev_b64 v[16:17], 11, v[38:39]
	v_fmac_f32_e32 v20, v178, v188
	v_lshl_add_u64 v[16:17], s[86:87], 0, v[16:17]
	v_mul_f32_e32 v20, v27, v20
	v_cvt_pk_bf16_f32 v22, v20, s0
	v_lshl_add_u64 v[20:21], v[16:17], 0, v[130:131]
	flat_store_short v[20:21], v22
	v_mul_f32_e32 v22, v37, v18
	v_fma_f32 v22, v99, v22, v85
	v_fmac_f32_e32 v22, v178, v194
	v_mul_f32_e32 v22, v31, v22
	v_cvt_pk_bf16_f32 v22, v22, s0
	flat_store_short v[20:21], v22 offset:32
	v_mul_f32_e32 v22, v35, v18
	v_mul_f32_e32 v18, v34, v18
	v_fma_f32 v22, v101, v22, v87
	v_fma_f32 v18, v103, v18, v89
	v_fmac_f32_e32 v22, v178, v200
	v_fmac_f32_e32 v18, v178, v196
	v_mul_f32_e32 v19, v19, v22
	v_mul_f32_e32 v18, v23, v18
	v_cvt_pk_bf16_f32 v19, v19, s0
	v_cvt_pk_bf16_f32 v18, v18, s0
	v_lshl_add_u64 v[16:17], v[16:17], 0, v[132:133]
	flat_store_short v[20:21], v19 offset:64
	flat_store_short v[16:17], v18
	v_mov_b32_e32 v17, s51
	v_or_b32_e32 v16, s50, v122
	v_lshl_add_u64 v[18:19], v[16:17], 3, v[72:73]
	v_lshlrev_b64 v[18:19], 2, v[18:19]
	v_lshlrev_b64 v[20:21], 9, v[16:17]
	v_lshl_add_u64 v[24:25], s[42:43], 0, v[18:19]
	v_lshl_add_u64 v[26:27], s[14:15], 0, v[18:19]
	v_mov_b64_e32 v[18:19], s[8:9]
	v_lshl_add_u64 v[22:23], v[20:21], 0, v[64:65]
	v_mad_i64_i32 v[18:19], s[0:1], v16, s19, v[18:19]
	v_lshlrev_b64 v[22:23], 1, v[22:23]
	v_lshl_add_u64 v[28:29], s[16:17], 0, v[22:23]
	v_lshl_add_u64 v[30:31], s[10:11], 0, v[22:23]
	v_lshl_add_u64 v[22:23], v[18:19], 0, v[130:131]
	flat_load_dword v32, v[24:25]
	flat_load_dword v35, v[26:27]
	flat_load_ushort v33, v[28:29]
	flat_load_ushort v34, v[30:31]
	flat_load_ushort v36, v[22:23] offset:2048
	v_or_b32_e32 v26, s46, v122
	v_cmp_lt_i32_e64 s[0:1], s47, v26
	v_lshl_add_u64 v[24:25], v[22:23], 0, s[54:55]
	s_and_saveexec_b64 s[4:5], s[0:1]
	s_cbranch_execz .LBB0_710
	v_add_co_u32_e32 v28, vcc, 0xffffe900, v24
	s_nop 1
	v_addc_co_u32_e32 v29, vcc, -1, v25, vcc
	flat_load_ushort v46, v[28:29]
; __device__ __forceinline__ float bf2f(u16 h) { return __uint_as_float(((unsigned)h) << 16); }
; __device__ __forceinline__ void even_post_phase(const Params& p, int ei, char* smem) {
;     ...
;       for (int q8 = 0; q8 < 4; ++q8) {
;         const int m = mh, j = q8;
;         const int tk = m * 16 + fq * 4 + j;
;         const size_t row = (size_t)row0 + tk;
;         const int l = l0 + tk;
;         const bool hp = l > seg_lo, hn = (l + 1) < seg_hi;
;         bon[q8] = 0.5f * (bonf[row * 8 + wid] + bonb[row * 8 + wid]);
; #pragma unroll
;         for (int n = 0; n < 4; ++n) {
;           const int col = wid * 64 + n * 16 + fr;
;           ov[q8][n] = bf2f(of[row * 512 + col]) + bf2f(ob[row * 512 + col]);
;           const u16* pv = big + row * PSTR + 1024 + col;
;           const float c = bf2f(*pv);
;           const float pr = hp ? bf2f(*(pv - PSTR)) : 0.f;
;           const float nx = hn ? bf2f(*(pv + PSTR)) : 0.f;
;           vs[q8][n] = c + muv[n] * (0.5f * (pr + nx) - c);
;         }
;       }
.LBB0_710:
	s_or_b64 exec, exec, s[4:5]
	v_cmp_gt_i32_e64 s[4:5], s80, v26
	v_mov_b32_e32 v38, 0
	v_mov_b32_e32 v37, 0
	s_and_saveexec_b64 s[44:45], s[4:5]
	s_cbranch_execz .LBB0_712
	v_add_co_u32_e32 v24, vcc, 0x1000, v24
	s_nop 1
	v_addc_co_u32_e32 v25, vcc, 0, v25, vcc
	flat_load_ushort v37, v[24:25] offset:1792
.LBB0_712:
	s_or_b64 exec, exec, s[44:45]
	v_lshl_add_u64 v[24:25], v[20:21], 0, v[68:69]
	v_lshlrev_b64 v[24:25], 1, v[24:25]
	v_lshl_add_u64 v[26:27], s[16:17], 0, v[24:25]
	v_lshl_add_u64 v[24:25], s[10:11], 0, v[24:25]
	flat_load_ushort v39, v[26:27]
	flat_load_ushort v40, v[24:25]
	flat_load_ushort v41, v[22:23] offset:2080
	v_lshl_add_u64 v[24:25], v[22:23], 0, s[56:57]
	s_and_saveexec_b64 s[44:45], s[0:1]
	s_cbranch_execz .LBB0_714
	v_add_co_u32_e32 v26, vcc, 0xffffe900, v24
	s_nop 1
	v_addc_co_u32_e32 v27, vcc, -1, v25, vcc
	flat_load_ushort v38, v[26:27]
.LBB0_714:
	s_or_b64 exec, exec, s[44:45]
	v_mov_b32_e32 v43, 0
	v_mov_b32_e32 v42, 0
	s_and_saveexec_b64 s[44:45], s[4:5]
	s_cbranch_execz .LBB0_716
	v_add_co_u32_e32 v24, vcc, 0x1000, v24
	s_nop 1
	v_addc_co_u32_e32 v25, vcc, 0, v25, vcc
	flat_load_ushort v42, v[24:25] offset:1792
.LBB0_716:
	s_or_b64 exec, exec, s[44:45]
	v_lshl_add_u64 v[24:25], v[20:21], 0, v[70:71]
	v_lshlrev_b64 v[24:25], 1, v[24:25]
	v_lshl_add_u64 v[26:27], s[16:17], 0, v[24:25]
	v_lshl_add_u64 v[24:25], s[10:11], 0, v[24:25]
	flat_load_ushort v44, v[26:27]
	flat_load_ushort v45, v[24:25]
	flat_load_ushort v47, v[22:23] offset:2112
	v_lshl_add_u64 v[24:25], v[22:23], 0, s[58:59]
	s_and_saveexec_b64 s[44:45], s[0:1]
	s_cbranch_execz .LBB0_718
	v_add_co_u32_e32 v22, vcc, 0xffffe900, v24
	s_nop 1
	v_addc_co_u32_e32 v23, vcc, -1, v25, vcc
	flat_load_ushort v43, v[22:23]
.LBB0_718:
	s_or_b64 exec, exec, s[44:45]
	v_mov_b32_e32 v49, 0
	v_mov_b32_e32 v48, 0
	s_and_saveexec_b64 s[44:45], s[4:5]
	s_cbranch_execz .LBB0_720
	v_add_co_u32_e32 v22, vcc, 0x1000, v24
	s_nop 1
	v_addc_co_u32_e32 v23, vcc, 0, v25, vcc
	flat_load_ushort v48, v[22:23] offset:1792
.LBB0_720:
	s_or_b64 exec, exec, s[44:45]
	v_lshl_add_u64 v[20:21], v[20:21], 0, v[66:67]
	v_lshlrev_b64 v[20:21], 1, v[20:21]
	v_lshl_add_u64 v[22:23], s[16:17], 0, v[20:21]
	v_lshl_add_u64 v[20:21], s[10:11], 0, v[20:21]
	flat_load_ushort v50, v[22:23]
	flat_load_ushort v51, v[20:21]
	v_lshl_add_u64 v[20:21], v[66:67], 1, v[18:19]
	flat_load_ushort v52, v[20:21] offset:2048
	v_lshl_add_u64 v[18:19], v[20:21], 0, s[54:55]
	s_and_saveexec_b64 s[44:45], s[0:1]
	s_cbranch_execz .LBB0_722
	v_add_co_u32_e32 v20, vcc, 0xffffe900, v18
	s_nop 1
	v_addc_co_u32_e32 v21, vcc, -1, v19, vcc
	flat_load_ushort v49, v[20:21]
.LBB0_722:
	s_or_b64 exec, exec, s[44:45]
	v_mov_b32_e32 v54, 0
	v_mov_b32_e32 v53, 0
	s_and_saveexec_b64 s[0:1], s[4:5]
	s_cbranch_execz .LBB0_724
	v_add_co_u32_e32 v18, vcc, 0x1000, v18
	s_nop 1
	v_addc_co_u32_e32 v19, vcc, 0, v19, vcc
	flat_load_ushort v53, v[18:19] offset:1792
.LBB0_724:
	s_or_b64 exec, exec, s[0:1]
	v_mov_b32_e32 v19, s51
	v_or_b32_e32 v18, s50, v124
	v_lshl_add_u64 v[20:21], v[18:19], 3, v[72:73]
	v_lshlrev_b64 v[20:21], 2, v[20:21]
	v_lshlrev_b64 v[22:23], 9, v[18:19]
	v_lshl_add_u64 v[26:27], s[42:43], 0, v[20:21]
	v_lshl_add_u64 v[28:29], s[14:15], 0, v[20:21]
	v_mov_b64_e32 v[20:21], s[8:9]
	v_lshl_add_u64 v[24:25], v[22:23], 0, v[64:65]
	v_mad_i64_i32 v[20:21], s[0:1], v18, s19, v[20:21]
	v_lshlrev_b64 v[24:25], 1, v[24:25]
	v_lshl_add_u64 v[30:31], s[16:17], 0, v[24:25]
	v_lshl_add_u64 v[60:61], s[10:11], 0, v[24:25]
	v_lshl_add_u64 v[24:25], v[64:65], 1, v[20:21]
	flat_load_dword v55, v[26:27]
	flat_load_dword v58, v[28:29]
	flat_load_ushort v56, v[30:31]
	flat_load_ushort v57, v[60:61]
	flat_load_ushort v59, v[24:25] offset:2048
	v_or_b32_e32 v28, s46, v124
	v_cmp_lt_i32_e64 s[0:1], s47, v28
	v_lshl_add_u64 v[26:27], v[24:25], 0, s[54:55]
	s_and_saveexec_b64 s[4:5], s[0:1]
	s_cbranch_execz .LBB0_726
	v_add_co_u32_e32 v30, vcc, 0xffffe900, v26
	s_nop 1
	v_addc_co_u32_e32 v31, vcc, -1, v27, vcc
	flat_load_ushort v54, v[30:31]
.LBB0_726:
	s_or_b64 exec, exec, s[4:5]
	v_cmp_gt_i32_e64 s[4:5], s80, v28
	v_mov_b32_e32 v61, 0
	v_mov_b32_e32 v60, 0
	s_and_saveexec_b64 s[44:45], s[4:5]
	s_cbranch_execz .LBB0_728
	v_add_co_u32_e32 v26, vcc, 0x1000, v26
	s_nop 1
	v_addc_co_u32_e32 v27, vcc, 0, v27, vcc
	flat_load_ushort v60, v[26:27] offset:1792
.LBB0_728:
	s_or_b64 exec, exec, s[44:45]
	v_lshl_add_u64 v[26:27], v[22:23], 0, v[68:69]
	v_lshlrev_b64 v[26:27], 1, v[26:27]
	v_lshl_add_u64 v[28:29], s[16:17], 0, v[26:27]
	v_lshl_add_u64 v[26:27], s[10:11], 0, v[26:27]
	flat_load_ushort v62, v[28:29]
	flat_load_ushort v63, v[26:27]
	flat_load_ushort v108, v[24:25] offset:2080
	v_lshl_add_u64 v[26:27], v[24:25], 0, s[56:57]
	s_and_saveexec_b64 s[44:45], s[0:1]
	s_cbranch_execz .LBB0_730
	v_add_co_u32_e32 v28, vcc, 0xffffe900, v26
	s_nop 1
	v_addc_co_u32_e32 v29, vcc, -1, v27, vcc
	flat_load_ushort v61, v[28:29]
.LBB0_730:
	s_or_b64 exec, exec, s[44:45]
	v_mov_b32_e32 v135, 0
	v_mov_b32_e32 v134, 0
	s_and_saveexec_b64 s[44:45], s[4:5]
	s_cbranch_execz .LBB0_732
	v_add_co_u32_e32 v26, vcc, 0x1000, v26
	s_nop 1
	v_addc_co_u32_e32 v27, vcc, 0, v27, vcc
	flat_load_ushort v134, v[26:27] offset:1792
.LBB0_732:
	s_or_b64 exec, exec, s[44:45]
	v_lshl_add_u64 v[26:27], v[22:23], 0, v[70:71]
	v_lshlrev_b64 v[26:27], 1, v[26:27]
	v_lshl_add_u64 v[28:29], s[16:17], 0, v[26:27]
	v_lshl_add_u64 v[26:27], s[10:11], 0, v[26:27]
	flat_load_ushort v136, v[28:29]
	flat_load_ushort v137, v[26:27]
	flat_load_ushort v138, v[24:25] offset:2112
	v_lshl_add_u64 v[26:27], v[24:25], 0, s[58:59]
	s_and_saveexec_b64 s[44:45], s[0:1]
	s_cbranch_execz .LBB0_734
	v_add_co_u32_e32 v24, vcc, 0xffffe900, v26
	s_nop 1
	v_addc_co_u32_e32 v25, vcc, -1, v27, vcc
	flat_load_ushort v135, v[24:25]
; __device__ __forceinline__ float bf2f(u16 h) { return __uint_as_float(((unsigned)h) << 16); }
; __device__ __forceinline__ void even_post_phase(const Params& p, int ei, char* smem) {
;     ...
;       for (int q8 = 0; q8 < 4; ++q8) {
;         const int m = mh, j = q8;
;         const int tk = m * 16 + fq * 4 + j;
;         const size_t row = (size_t)row0 + tk;
;         const int l = l0 + tk;
;         const bool hp = l > seg_lo, hn = (l + 1) < seg_hi;
;         bon[q8] = 0.5f * (bonf[row * 8 + wid] + bonb[row * 8 + wid]);
; #pragma unroll
;         for (int n = 0; n < 4; ++n) {
;           const int col = wid * 64 + n * 16 + fr;
;           ov[q8][n] = bf2f(of[row * 512 + col]) + bf2f(ob[row * 512 + col]);
;           const u16* pv = big + row * PSTR + 1024 + col;
;           const float c = bf2f(*pv);
;           const float pr = hp ? bf2f(*(pv - PSTR)) : 0.f;
;           const float nx = hn ? bf2f(*(pv + PSTR)) : 0.f;
;           vs[q8][n] = c + muv[n] * (0.5f * (pr + nx) - c);
;         }
;       }
.LBB0_734:
	s_or_b64 exec, exec, s[44:45]
	v_mov_b32_e32 v140, 0
	v_mov_b32_e32 v139, 0
	s_and_saveexec_b64 s[44:45], s[4:5]
	s_cbranch_execz .LBB0_736
	v_add_co_u32_e32 v24, vcc, 0x1000, v26
	s_nop 1
	v_addc_co_u32_e32 v25, vcc, 0, v27, vcc
	flat_load_ushort v139, v[24:25] offset:1792
.LBB0_736:
	s_or_b64 exec, exec, s[44:45]
	v_lshl_add_u64 v[22:23], v[22:23], 0, v[66:67]
	v_lshlrev_b64 v[22:23], 1, v[22:23]
	v_lshl_add_u64 v[24:25], s[16:17], 0, v[22:23]
	v_lshl_add_u64 v[22:23], s[10:11], 0, v[22:23]
	flat_load_ushort v141, v[24:25]
	flat_load_ushort v142, v[22:23]
	v_lshl_add_u64 v[22:23], v[66:67], 1, v[20:21]
	flat_load_ushort v143, v[22:23] offset:2048
	v_lshl_add_u64 v[20:21], v[22:23], 0, s[54:55]
	s_and_saveexec_b64 s[44:45], s[0:1]
	s_cbranch_execz .LBB0_738
	v_add_co_u32_e32 v22, vcc, 0xffffe900, v20
	s_nop 1
	v_addc_co_u32_e32 v23, vcc, -1, v21, vcc
	flat_load_ushort v140, v[22:23]
.LBB0_738:
	s_or_b64 exec, exec, s[44:45]
	v_mov_b32_e32 v145, 0
	v_mov_b32_e32 v144, 0
	s_and_saveexec_b64 s[0:1], s[4:5]
	s_cbranch_execz .LBB0_740
	v_add_co_u32_e32 v20, vcc, 0x1000, v20
	s_nop 1
	v_addc_co_u32_e32 v21, vcc, 0, v21, vcc
	flat_load_ushort v144, v[20:21] offset:1792
.LBB0_740:
	s_or_b64 exec, exec, s[0:1]
	v_mov_b32_e32 v21, s51
	v_or_b32_e32 v20, s50, v126
	v_lshl_add_u64 v[22:23], v[20:21], 3, v[72:73]
	v_lshlrev_b64 v[24:25], 9, v[20:21]
	v_lshlrev_b64 v[22:23], 2, v[22:23]
	v_lshl_add_u64 v[26:27], v[24:25], 0, v[64:65]
	v_lshl_add_u64 v[28:29], s[42:43], 0, v[22:23]
	v_lshl_add_u64 v[30:31], s[14:15], 0, v[22:23]
	v_mov_b64_e32 v[22:23], s[8:9]
	v_lshlrev_b64 v[26:27], 1, v[26:27]
	v_mad_i64_i32 v[22:23], s[0:1], v20, s19, v[22:23]
	v_lshl_add_u64 v[150:151], s[16:17], 0, v[26:27]
	v_lshl_add_u64 v[152:153], s[10:11], 0, v[26:27]
	v_lshl_add_u64 v[26:27], v[64:65], 1, v[22:23]
	flat_load_dword v146, v[28:29]
	flat_load_dword v149, v[30:31]
	flat_load_ushort v147, v[150:151]
	flat_load_ushort v148, v[152:153]
	s_nop 0
	flat_load_ushort v150, v[26:27] offset:2048
	v_or_b32_e32 v30, s46, v126
	v_cmp_lt_i32_e64 s[0:1], s47, v30
	v_lshl_add_u64 v[28:29], v[26:27], 0, s[54:55]
	s_and_saveexec_b64 s[4:5], s[0:1]
	s_cbranch_execz .LBB0_742
	v_add_co_u32_e32 v152, vcc, 0xffffe900, v28
	s_nop 1
	v_addc_co_u32_e32 v153, vcc, -1, v29, vcc
	flat_load_ushort v145, v[152:153]
.LBB0_742:
	s_or_b64 exec, exec, s[4:5]
	v_cmp_gt_i32_e64 s[4:5], s80, v30
	v_mov_b32_e32 v152, 0
	v_mov_b32_e32 v151, 0
	s_and_saveexec_b64 s[44:45], s[4:5]
	s_cbranch_execz .LBB0_744
	v_add_co_u32_e32 v28, vcc, 0x1000, v28
	s_nop 1
	v_addc_co_u32_e32 v29, vcc, 0, v29, vcc
	flat_load_ushort v151, v[28:29] offset:1792
.LBB0_744:
	s_or_b64 exec, exec, s[44:45]
	v_lshl_add_u64 v[28:29], v[24:25], 0, v[68:69]
	v_lshlrev_b64 v[28:29], 1, v[28:29]
	v_lshl_add_u64 v[30:31], s[16:17], 0, v[28:29]
	v_lshl_add_u64 v[28:29], s[10:11], 0, v[28:29]
	flat_load_ushort v153, v[30:31]
	flat_load_ushort v154, v[28:29]
	flat_load_ushort v155, v[26:27] offset:2080
	v_lshl_add_u64 v[28:29], v[26:27], 0, s[56:57]
	s_and_saveexec_b64 s[44:45], s[0:1]
	s_cbranch_execz .LBB0_746
	v_add_co_u32_e32 v30, vcc, 0xffffe900, v28
	s_nop 1
	v_addc_co_u32_e32 v31, vcc, -1, v29, vcc
	flat_load_ushort v152, v[30:31]
.LBB0_746:
	s_or_b64 exec, exec, s[44:45]
	v_mov_b32_e32 v157, 0
	v_mov_b32_e32 v156, 0
	s_and_saveexec_b64 s[44:45], s[4:5]
	s_cbranch_execz .LBB0_748
	v_add_co_u32_e32 v28, vcc, 0x1000, v28
	s_nop 1
	v_addc_co_u32_e32 v29, vcc, 0, v29, vcc
	flat_load_ushort v156, v[28:29] offset:1792
.LBB0_748:
	s_or_b64 exec, exec, s[44:45]
	v_lshl_add_u64 v[28:29], v[24:25], 0, v[70:71]
	v_lshlrev_b64 v[28:29], 1, v[28:29]
	v_lshl_add_u64 v[30:31], s[16:17], 0, v[28:29]
	v_lshl_add_u64 v[28:29], s[10:11], 0, v[28:29]
	flat_load_ushort v158, v[30:31]
	flat_load_ushort v159, v[28:29]
	flat_load_ushort v160, v[26:27] offset:2112
	v_lshl_add_u64 v[28:29], v[26:27], 0, s[58:59]
	s_and_saveexec_b64 s[44:45], s[0:1]
	s_cbranch_execz .LBB0_750
	v_add_co_u32_e32 v26, vcc, 0xffffe900, v28
	s_nop 1
	v_addc_co_u32_e32 v27, vcc, -1, v29, vcc
	flat_load_ushort v157, v[26:27]
.LBB0_750:
	s_or_b64 exec, exec, s[44:45]
	v_mov_b32_e32 v162, 0
	v_mov_b32_e32 v161, 0
	s_and_saveexec_b64 s[44:45], s[4:5]
	s_cbranch_execz .LBB0_752
	v_add_co_u32_e32 v26, vcc, 0x1000, v28
	s_nop 1
	v_addc_co_u32_e32 v27, vcc, 0, v29, vcc
	flat_load_ushort v161, v[26:27] offset:1792
.LBB0_752:
	s_or_b64 exec, exec, s[44:45]
	v_lshl_add_u64 v[24:25], v[24:25], 0, v[66:67]
	v_lshlrev_b64 v[24:25], 1, v[24:25]
	v_lshl_add_u64 v[26:27], s[16:17], 0, v[24:25]
	v_lshl_add_u64 v[24:25], s[10:11], 0, v[24:25]
	flat_load_ushort v163, v[26:27]
	flat_load_ushort v164, v[24:25]
	v_lshl_add_u64 v[24:25], v[66:67], 1, v[22:23]
	flat_load_ushort v165, v[24:25] offset:2048
	v_lshl_add_u64 v[22:23], v[24:25], 0, s[54:55]
	s_and_saveexec_b64 s[44:45], s[0:1]
	s_cbranch_execz .LBB0_754
	v_add_co_u32_e32 v24, vcc, 0xffffe900, v22
	s_nop 1
	v_addc_co_u32_e32 v25, vcc, -1, v23, vcc
	flat_load_ushort v162, v[24:25]
.LBB0_754:
	s_or_b64 exec, exec, s[44:45]
	v_mov_b32_e32 v167, 0
	v_mov_b32_e32 v166, 0
	s_and_saveexec_b64 s[0:1], s[4:5]
	s_cbranch_execz .LBB0_756
	v_add_co_u32_e32 v22, vcc, 0x1000, v22
	s_nop 1
	v_addc_co_u32_e32 v23, vcc, 0, v23, vcc
	flat_load_ushort v166, v[22:23] offset:1792

; __device__ __forceinline__ float bf2f(u16 h) { return __uint_as_float(((unsigned)h) << 16); }
; __device__ __forceinline__ void even_post_phase(const Params& p, int ei, char* smem) {
;     ...
;       for (int q8 = 0; q8 < 4; ++q8) {
;         const int m = mh, j = q8;
;         const int tk = m * 16 + fq * 4 + j;
;         const size_t row = (size_t)row0 + tk;
;         const int l = l0 + tk;
;         const bool hp = l > seg_lo, hn = (l + 1) < seg_hi;
;         bon[q8] = 0.5f * (bonf[row * 8 + wid] + bonb[row * 8 + wid]);
; #pragma unroll
;         for (int n = 0; n < 4; ++n) {
;           const int col = wid * 64 + n * 16 + fr;
;           ov[q8][n] = bf2f(of[row * 512 + col]) + bf2f(ob[row * 512 + col]);
;           const u16* pv = big + row * PSTR + 1024 + col;
;           const float c = bf2f(*pv);
;           const float pr = hp ? bf2f(*(pv - PSTR)) : 0.f;
;           const float nx = hn ? bf2f(*(pv + PSTR)) : 0.f;
;           vs[q8][n] = c + muv[n] * (0.5f * (pr + nx) - c);
;         }
;       }
.LBB0_758:
	s_or_b64 exec, exec, s[4:5]
	v_cmp_gt_i32_e64 s[4:5], s80, v173
	v_mov_b32_e32 v174, 0
	v_mov_b32_e32 v173, 0
	s_and_saveexec_b64 s[44:45], s[4:5]
	s_cbranch_execz .LBB0_760
	v_add_co_u32_e32 v30, vcc, 0x1000, v30
	s_nop 1
	v_addc_co_u32_e32 v31, vcc, 0, v31, vcc
	flat_load_ushort v173, v[30:31] offset:1792

; __device__ __forceinline__ float bf2f(u16 h) { return __uint_as_float(((unsigned)h) << 16); }
; __device__ __forceinline__ void even_post_phase(const Params& p, int ei, char* smem) {
;     ...
;       for (int q8 = 0; q8 < 4; ++q8) {
;         const int m = mh, j = q8;
;         const int tk = m * 16 + fq * 4 + j;
;         const size_t row = (size_t)row0 + tk;
;         const int l = l0 + tk;
;         const bool hp = l > seg_lo, hn = (l + 1) < seg_hi;
;         bon[q8] = 0.5f * (bonf[row * 8 + wid] + bonb[row * 8 + wid]);
; #pragma unroll
;         for (int n = 0; n < 4; ++n) {
;           const int col = wid * 64 + n * 16 + fr;
;           ov[q8][n] = bf2f(of[row * 512 + col]) + bf2f(ob[row * 512 + col]);
;           const u16* pv = big + row * PSTR + 1024 + col;
;           const float c = bf2f(*pv);
;           const float pr = hp ? bf2f(*(pv - PSTR)) : 0.f;
;           const float nx = hn ? bf2f(*(pv + PSTR)) : 0.f;
;           vs[q8][n] = c + muv[n] * (0.5f * (pr + nx) - c);
;         }
;       }
.LBB0_762:
	s_or_b64 exec, exec, s[44:45]
	v_mov_b32_e32 v180, 0
	v_mov_b32_e32 v179, 0
	s_and_saveexec_b64 s[44:45], s[4:5]
	s_cbranch_execz .LBB0_764
	v_add_co_u32_e32 v30, vcc, 0x1000, v30
	s_nop 1
	v_addc_co_u32_e32 v31, vcc, 0, v31, vcc
	flat_load_ushort v179, v[30:31] offset:1792
.LBB0_764:
	s_or_b64 exec, exec, s[44:45]
	v_lshl_add_u64 v[30:31], v[26:27], 0, v[70:71]
	v_lshlrev_b64 v[30:31], 1, v[30:31]
	v_lshl_add_u64 v[182:183], s[16:17], 0, v[30:31]
	v_lshl_add_u64 v[30:31], s[10:11], 0, v[30:31]
	flat_load_ushort v181, v[182:183]
	s_nop 0
	flat_load_ushort v182, v[30:31]
	v_lshl_add_u64 v[30:31], v[28:29], 0, s[58:59]
	flat_load_ushort v28, v[28:29] offset:2112
	s_and_saveexec_b64 s[44:45], s[0:1]
	s_cbranch_execz .LBB0_766
	v_add_co_u32_e32 v184, vcc, 0xffffe900, v30
	s_nop 1
	v_addc_co_u32_e32 v185, vcc, -1, v31, vcc
	flat_load_ushort v180, v[184:185]

; __device__ __forceinline__ float bf2f(u16 h) { return __uint_as_float(((unsigned)h) << 16); }
; __device__ __forceinline__ void even_post_phase(const Params& p, int ei, char* smem) {
;     ...
;       for (int q8 = 0; q8 < 4; ++q8) {
;         const int m = mh, j = q8;
;         const int tk = m * 16 + fq * 4 + j;
;         const size_t row = (size_t)row0 + tk;
;         const int l = l0 + tk;
;         const bool hp = l > seg_lo, hn = (l + 1) < seg_hi;
;         bon[q8] = 0.5f * (bonf[row * 8 + wid] + bonb[row * 8 + wid]);
; #pragma unroll
;         for (int n = 0; n < 4; ++n) {
;           const int col = wid * 64 + n * 16 + fr;
;           ov[q8][n] = bf2f(of[row * 512 + col]) + bf2f(ob[row * 512 + col]);
;           const u16* pv = big + row * PSTR + 1024 + col;
;           const float c = bf2f(*pv);
;           const float pr = hp ? bf2f(*(pv - PSTR)) : 0.f;
;           const float nx = hn ? bf2f(*(pv + PSTR)) : 0.f;
;           vs[q8][n] = c + muv[n] * (0.5f * (pr + nx) - c);
;         }
;       }
.LBB0_768:
	s_or_b64 exec, exec, s[44:45]
	v_lshl_add_u64 v[26:27], v[26:27], 0, v[66:67]
	v_lshlrev_b64 v[30:31], 1, v[26:27]
	v_lshl_add_u64 v[26:27], s[16:17], 0, v[30:31]
	v_lshl_add_u64 v[30:31], s[10:11], 0, v[30:31]
	flat_load_ushort v26, v[26:27]
	s_nop 0
	flat_load_ushort v27, v[30:31]
	v_lshl_add_u64 v[30:31], v[66:67], 1, v[24:25]
	v_lshl_add_u64 v[24:25], v[30:31], 0, s[54:55]
	flat_load_ushort v31, v[30:31] offset:2048
	s_and_saveexec_b64 s[44:45], s[0:1]
	s_cbranch_execz .LBB0_770
	v_add_co_u32_e32 v184, vcc, 0xffffe900, v24
	s_nop 1
	v_addc_co_u32_e32 v185, vcc, -1, v25, vcc
	flat_load_ushort v177, v[184:185]
.LBB0_770:
	s_or_b64 exec, exec, s[44:45]
	v_mov_b32_e32 v30, 0
	s_and_saveexec_b64 s[0:1], s[4:5]
	s_cbranch_execz .LBB0_507
	v_add_co_u32_e32 v24, vcc, 0x1000, v24
	s_nop 1
	v_addc_co_u32_e32 v25, vcc, 0, v25, vcc
	flat_load_ushort v30, v[24:25] offset:1792
	s_branch .LBB0_507

; __device__ __forceinline__ void lru_phase(const Params& p, int ei, char* smem) {
;     ...
;       for (int j = 0; j < 4; ++j) {
;         int ll = l + j - 2;
;         if (ll >= seg_lo && ll < seg_hi) {
;           const u16* px = big + ((size_t)b * LT + ll) * PSTR + 1920 + n * 64 + cc;
;           float xv[16];
;           unpack8(*(const uint4*)px, xv);
;           unpack8(*(const uint4*)(px + 8), xv + 8);
; #pragma unroll
;           for (int e4 = 0; e4 < 4; ++e4) {
;             float4 w4 = *(const float4*)(cw + j * 512 + e4 * 4);
;             xb[e4 * 4] += w4.x * xv[e4 * 4]; xb[e4 * 4 + 1] += w4.y * xv[e4 * 4 + 1];
;             xb[e4 * 4 + 2] += w4.z * xv[e4 * 4 + 2]; xb[e4 * 4 + 3] += w4.w * xv[e4 * 4 + 3];
;           }
;         }
.LBB0_881:
	flat_load_dwordx4 v[28:31], v[48:49]
	flat_load_dwordx4 v[24:27], v[48:49] offset:16
	flat_load_dwordx4 v[20:23], v[48:49] offset:32
	flat_load_dwordx4 v[16:19], v[48:49] offset:48
	s_cmp_gt_u32 s17, 3
	v_lshl_or_b32 v70, s17, 6, v45
	s_cselect_b32 s2, s78, 0xff
	v_sub_u32_e32 v72, s2, v70
	v_cndmask_b32_e64 v74, v72, v70, s[0:1]
	v_cmp_gt_i32_e32 vcc, s3, v74
	v_add_u32_e32 v108, -2, v74
	s_nop 0
	v_cndmask_b32_e64 v70, v214, 0, vcc
	v_cndmask_b32_e32 v88, v217, v214, vcc
	v_cmp_ge_i32_e32 vcc, v108, v70
	v_cmp_lt_i32_e64 s[4:5], v108, v88
	s_and_b64 s[42:43], vcc, s[4:5]
	s_and_saveexec_b64 s[4:5], s[42:43]
	s_cbranch_execz .LBB0_883
	v_lshl_add_u64 v[72:73], v[50:51], 0, v[108:109]
	v_mov_b64_e32 v[90:91], s[12:13]
	v_mad_u64_u32 v[90:91], s[42:43], v72, s19, v[90:91]
	v_mov_b32_e32 v72, v91
	v_mad_u64_u32 v[72:73], s[42:43], v73, s19, v[72:73]
	v_mov_b32_e32 v91, v72
	v_lshlrev_b32_e32 v108, 1, v44
	v_lshl_add_u64 v[72:73], v[90:91], 0, v[108:109]
	v_lshlrev_b32_e32 v108, 1, v32
	v_lshl_add_u64 v[72:73], v[72:73], 0, v[108:109]
	v_lshl_add_u64 v[94:95], v[72:73], 0, s[72:73]
	v_add_co_u32_e32 v72, vcc, s79, v72
	s_nop 1
	v_addc_co_u32_e32 v73, vcc, 0, v73, vcc
	flat_load_dwordx4 v[140:143], v[72:73] offset:3840
	flat_load_dwordx4 v[144:147], v[94:95] offset:16
	flat_load_dwordx4 v[90:93], v[46:47]
	flat_load_dwordx4 v[94:97], v[46:47] offset:16
	flat_load_dwordx4 v[98:101], v[46:47] offset:32
	flat_load_dwordx4 v[122:125], v[46:47] offset:48
	s_waitcnt vmcnt(0) lgkmcnt(0)
	v_lshlrev_b32_e32 v72, 16, v140
	v_and_b32_e32 v73, 0xffff0000, v140
	v_lshlrev_b32_e32 v102, 16, v141
	v_and_b32_e32 v103, 0xffff0000, v141
	v_lshlrev_b32_e32 v126, 16, v142
	v_and_b32_e32 v127, 0xffff0000, v142
	v_lshlrev_b32_e32 v128, 16, v143
	v_and_b32_e32 v129, 0xffff0000, v143
	v_lshlrev_b32_e32 v130, 16, v144
	v_and_b32_e32 v131, 0xffff0000, v144
	v_lshlrev_b32_e32 v132, 16, v145
	v_and_b32_e32 v133, 0xffff0000, v145
	v_lshlrev_b32_e32 v134, 16, v146
	v_and_b32_e32 v135, 0xffff0000, v146
	v_lshlrev_b32_e32 v136, 16, v147
	v_and_b32_e32 v137, 0xffff0000, v147
	v_pk_fma_f32 v[30:31], v[92:93], v[102:103], v[30:31]
	v_pk_fma_f32 v[26:27], v[96:97], v[128:129], v[26:27]
	v_pk_fma_f32 v[24:25], v[94:95], v[126:127], v[24:25]
	v_pk_fma_f32 v[28:29], v[90:91], v[72:73], v[28:29]
	v_pk_fma_f32 v[18:19], v[124:125], v[136:137], v[18:19]
	v_pk_fma_f32 v[16:17], v[122:123], v[134:135], v[16:17]
	v_pk_fma_f32 v[22:23], v[100:101], v[132:133], v[22:23]
	v_pk_fma_f32 v[20:21], v[98:99], v[130:131], v[20:21]
.LBB0_883:
	s_or_b64 exec, exec, s[4:5]
	v_add_u32_e32 v108, -1, v74
	v_cmp_ge_i32_e32 vcc, v108, v70
	v_cmp_lt_i32_e64 s[4:5], v108, v88
	s_and_b64 s[42:43], vcc, s[4:5]
	s_and_saveexec_b64 s[4:5], s[42:43]
	s_cbranch_execz .LBB0_885
	v_lshl_add_u64 v[72:73], v[50:51], 0, v[108:109]
	v_mov_b64_e32 v[90:91], s[12:13]
	v_mad_u64_u32 v[90:91], s[42:43], v72, s19, v[90:91]
	v_mov_b32_e32 v72, v91
	v_mad_u64_u32 v[72:73], s[42:43], v73, s19, v[72:73]
	v_mov_b32_e32 v91, v72
	v_lshlrev_b32_e32 v108, 1, v44
	v_lshl_add_u64 v[72:73], v[90:91], 0, v[108:109]
	v_lshlrev_b32_e32 v108, 1, v32
	v_lshl_add_u64 v[72:73], v[72:73], 0, v[108:109]
	v_lshl_add_u64 v[94:95], v[72:73], 0, s[72:73]
	v_add_co_u32_e32 v72, vcc, s79, v72
	s_nop 1
	v_addc_co_u32_e32 v73, vcc, 0, v73, vcc
	flat_load_dwordx4 v[140:143], v[72:73] offset:3840
	flat_load_dwordx4 v[144:147], v[94:95] offset:16
	flat_load_dwordx4 v[90:93], v[46:47] offset:2048
	flat_load_dwordx4 v[94:97], v[46:47] offset:2064
	flat_load_dwordx4 v[98:101], v[46:47] offset:2080
	flat_load_dwordx4 v[122:125], v[46:47] offset:2096
	s_waitcnt vmcnt(0) lgkmcnt(0)
	v_lshlrev_b32_e32 v72, 16, v140
	v_and_b32_e32 v73, 0xffff0000, v140
	v_lshlrev_b32_e32 v102, 16, v141
	v_and_b32_e32 v103, 0xffff0000, v141
	v_lshlrev_b32_e32 v126, 16, v142
	v_and_b32_e32 v127, 0xffff0000, v142
	v_lshlrev_b32_e32 v128, 16, v143
	v_and_b32_e32 v129, 0xffff0000, v143
	v_lshlrev_b32_e32 v130, 16, v144
	v_and_b32_e32 v131, 0xffff0000, v144
	v_lshlrev_b32_e32 v132, 16, v145
	v_and_b32_e32 v133, 0xffff0000, v145
	v_lshlrev_b32_e32 v134, 16, v146
	v_and_b32_e32 v135, 0xffff0000, v146
	v_lshlrev_b32_e32 v136, 16, v147
	v_and_b32_e32 v137, 0xffff0000, v147
	v_pk_fma_f32 v[30:31], v[92:93], v[102:103], v[30:31]
	v_pk_fma_f32 v[26:27], v[96:97], v[128:129], v[26:27]
	v_pk_fma_f32 v[24:25], v[94:95], v[126:127], v[24:25]
	v_pk_fma_f32 v[28:29], v[90:91], v[72:73], v[28:29]
	v_pk_fma_f32 v[18:19], v[124:125], v[136:137], v[18:19]
	v_pk_fma_f32 v[16:17], v[122:123], v[134:135], v[16:17]
	v_pk_fma_f32 v[22:23], v[100:101], v[132:133], v[22:23]
	v_pk_fma_f32 v[20:21], v[98:99], v[130:131], v[20:21]

; __device__ __forceinline__ void lru_phase(const Params& p, int ei, char* smem) {
;     ...
;       for (int j = 0; j < 4; ++j) {
;         int ll = l + j - 2;
;         if (ll >= seg_lo && ll < seg_hi) {
;           const u16* px = big + ((size_t)b * LT + ll) * PSTR + 1920 + n * 64 + cc;
;           float xv[16];
;           unpack8(*(const uint4*)px, xv);
;           unpack8(*(const uint4*)(px + 8), xv + 8);
; #pragma unroll
;           for (int e4 = 0; e4 < 4; ++e4) {
;             float4 w4 = *(const float4*)(cw + j * 512 + e4 * 4);
;             xb[e4 * 4] += w4.x * xv[e4 * 4]; xb[e4 * 4 + 1] += w4.y * xv[e4 * 4 + 1];
;             xb[e4 * 4 + 2] += w4.z * xv[e4 * 4 + 2]; xb[e4 * 4 + 3] += w4.w * xv[e4 * 4 + 3];
;           }
;         }
.LBB0_887:
	s_or_b64 exec, exec, s[4:5]
	v_add_u32_e32 v108, 1, v74
	v_cmp_ge_i32_e32 vcc, v108, v70
	v_cmp_lt_i32_e64 s[4:5], v108, v88
	s_and_b64 s[42:43], vcc, s[4:5]
	s_and_saveexec_b64 s[4:5], s[42:43]
	s_cbranch_execz .LBB0_889
	v_lshl_add_u64 v[74:75], v[50:51], 0, v[108:109]
	v_mov_b64_e32 v[88:89], s[12:13]
	v_mad_u64_u32 v[88:89], s[42:43], v74, s19, v[88:89]
	v_mov_b32_e32 v70, v89
	v_mad_u64_u32 v[74:75], s[42:43], v75, s19, v[70:71]
	v_mov_b32_e32 v89, v74
	v_lshlrev_b32_e32 v108, 1, v44
	v_lshl_add_u64 v[74:75], v[88:89], 0, v[108:109]
	v_lshlrev_b32_e32 v108, 1, v32
	v_lshl_add_u64 v[74:75], v[74:75], 0, v[108:109]
	v_lshl_add_u64 v[92:93], v[74:75], 0, s[72:73]
	v_add_co_u32_e32 v74, vcc, s79, v74
	s_nop 1
	v_addc_co_u32_e32 v75, vcc, 0, v75, vcc
	flat_load_dwordx4 v[140:143], v[74:75] offset:3840
	flat_load_dwordx4 v[144:147], v[92:93] offset:16
	flat_load_dwordx4 v[88:91], v[62:63]
	flat_load_dwordx4 v[92:95], v[64:65]
	flat_load_dwordx4 v[96:99], v[66:67]
	flat_load_dwordx4 v[100:103], v[68:69]
	s_waitcnt vmcnt(0) lgkmcnt(0)
	v_lshlrev_b32_e32 v74, 16, v140
	v_and_b32_e32 v75, 0xffff0000, v140
	v_lshlrev_b32_e32 v122, 16, v141
	v_and_b32_e32 v123, 0xffff0000, v141
	v_lshlrev_b32_e32 v124, 16, v142
	v_and_b32_e32 v125, 0xffff0000, v142
	v_lshlrev_b32_e32 v126, 16, v143
	v_and_b32_e32 v127, 0xffff0000, v143
	v_lshlrev_b32_e32 v128, 16, v144
	v_and_b32_e32 v129, 0xffff0000, v144
	v_lshlrev_b32_e32 v130, 16, v145
	v_and_b32_e32 v131, 0xffff0000, v145
	v_lshlrev_b32_e32 v132, 16, v146
	v_and_b32_e32 v133, 0xffff0000, v146
	v_lshlrev_b32_e32 v134, 16, v147
	v_and_b32_e32 v135, 0xffff0000, v147
	v_pk_fma_f32 v[30:31], v[90:91], v[122:123], v[30:31]
	v_pk_fma_f32 v[26:27], v[94:95], v[126:127], v[26:27]
	v_pk_fma_f32 v[24:25], v[92:93], v[124:125], v[24:25]
	v_pk_fma_f32 v[28:29], v[88:89], v[74:75], v[28:29]
	v_pk_fma_f32 v[18:19], v[102:103], v[134:135], v[18:19]
	v_pk_fma_f32 v[16:17], v[100:101], v[132:133], v[16:17]
	v_pk_fma_f32 v[22:23], v[98:99], v[130:131], v[22:23]
	v_pk_fma_f32 v[20:21], v[96:97], v[128:129], v[20:21]
